# RWKV forward-substitution block rewritten: F rows fetched 16/ds_read_b32 + DPP row_newbcast FMAs, 64 distinct columns per active wave (same f32 sums and order)
# speedup vs baseline: 1.0151x; 1.0151x over previous
.LBB0_2331:
	s_nop 1
	ds_read_b128 v[2:5], v180 offset:36864
	v_add_u32_e32 v90, v112, v111
	ds_read_b128 v[6:9], v90
	ds_read_b128 v[92:95], v180 offset:9216
	ds_read_b128 v[18:21], v90 offset:36864
	ds_read_b128 v[34:37], v180
	ds_read_b128 v[96:99], v90 offset:18432
	ds_read_b128 v[100:103], v180 offset:36896
	ds_read_b128 v[184:187], v90 offset:32
	s_waitcnt lgkmcnt(4)
	v_mfma_f32_32x32x16_bf16 v[18:33], v[92:95], v[18:21], 0
	v_mfma_f32_32x32x16_bf16 v[2:17], v[2:5], v[6:9], 0
	s_waitcnt lgkmcnt(0)
	v_mfma_f32_32x32x16_bf16 v[2:17], v[100:103], v[184:187], v[2:17]
	ds_read_b128 v[100:103], v180 offset:9248
	ds_read_b128 v[184:187], v90 offset:36896
	v_mfma_f32_32x32x16_bf16 v[34:49], v[34:37], v[96:99], 0
	s_waitcnt lgkmcnt(0)
	v_mfma_f32_32x32x16_bf16 v[18:33], v[100:103], v[184:187], v[18:33]
	ds_read_b128 v[184:187], v180 offset:32
	ds_read_b128 v[196:199], v90 offset:18464
	s_waitcnt lgkmcnt(0)
	v_mfma_f32_32x32x16_bf16 v[34:49], v[184:187], v[196:199], v[34:49]
	ds_read_b128 v[184:187], v180 offset:36928
	ds_read_b128 v[200:203], v90 offset:64
	s_waitcnt lgkmcnt(0)
	v_mfma_f32_32x32x16_bf16 v[2:17], v[184:187], v[200:203], v[2:17]
	ds_read_b128 v[186:189], v180 offset:9280
	ds_read_b128 v[200:203], v90 offset:36928
	v_add_u32_e32 v184, 0x6800, v182
	s_waitcnt lgkmcnt(0)
	v_mfma_f32_32x32x16_bf16 v[18:33], v[186:189], v[200:203], v[18:33]
	ds_read_b128 v[200:203], v180 offset:64
	ds_read_b128 v[204:207], v90 offset:18496
	s_waitcnt lgkmcnt(0)
	v_mfma_f32_32x32x16_bf16 v[34:49], v[200:203], v[204:207], v[34:49]
	ds_read_b128 v[200:203], v180 offset:36960
	ds_read_b128 v[208:211], v90 offset:96
	s_waitcnt lgkmcnt(0)
	v_mfma_f32_32x32x16_bf16 v[2:17], v[200:203], v[208:211], v[2:17]
	ds_read_b128 v[200:203], v180 offset:9312
	ds_read_b128 v[208:211], v90 offset:36960
	s_waitcnt lgkmcnt(0)
	v_mfma_f32_32x32x16_bf16 v[18:33], v[200:203], v[208:211], v[18:33]
	ds_read_b128 v[208:211], v180 offset:96
	ds_read_b128 v[212:215], v90 offset:18528
	s_nop 5
	v_cndmask_b32_e64 v2, 0, v2, s[50:51]
	v_cndmask_b32_e64 v3, v3, 0, s[52:53]
	ds_write2_b32 v181, v2, v3 offset1:68
	v_cndmask_b32_e64 v3, 0, v4, s[56:57]
	v_cndmask_b32_e64 v4, 0, v5, s[60:61]
	v_cndmask_b32_e64 v5, 0, v6, s[64:65]
	ds_write_b32 v165, v3 offset:55296
	ds_write_b32 v166, v4 offset:55296
	ds_write_b32 v167, v5 offset:55296
	v_cndmask_b32_e64 v5, 0, v7, s[68:69]
	ds_write_b32 v168, v5 offset:55296
	v_cndmask_b32_e64 v5, 0, v8, s[72:73]
	ds_write_b32 v169, v5 offset:55296
	v_cndmask_b32_e64 v5, 0, v9, s[76:77]
	s_waitcnt lgkmcnt(6)
	v_mfma_f32_32x32x16_bf16 v[34:49], v[208:211], v[212:215], v[34:49]
	ds_write_b32 v170, v5 offset:55296
	v_cndmask_b32_e64 v5, 0, v10, s[80:81]
	ds_write_b32 v171, v5 offset:55296
	v_cndmask_b32_e64 v5, 0, v11, s[84:85]
	ds_write_b32 v172, v5 offset:55296
	v_cndmask_b32_e64 v5, 0, v12, s[88:89]
	ds_write_b32 v173, v5 offset:55296
	v_cndmask_b32_e64 v5, 0, v13, s[92:93]
	ds_write_b32 v174, v5 offset:55296
	v_cndmask_b32_e64 v5, 0, v14, s[96:97]
	ds_write_b32 v175, v5 offset:55296
	v_cndmask_b32_e64 v5, 0, v15, s[6:7]
	v_cndmask_b32_e64 v18, 0, v18, s[52:53]
	v_cndmask_b32_e64 v2, 0, v19, s[54:55]
	v_cndmask_b32_e64 v3, 0, v20, s[58:59]
	v_cndmask_b32_e64 v4, 0, v21, s[62:63]
	v_cndmask_b32_e64 v20, 0, v22, s[66:67]
	v_cndmask_b32_e64 v21, 0, v23, s[70:71]
	v_cndmask_b32_e64 v24, 0, v24, s[74:75]
	v_cndmask_b32_e64 v25, 0, v25, s[78:79]
	ds_write_b32 v176, v5 offset:55296
	v_cndmask_b32_e64 v5, 0, v16, s[10:11]
	v_cndmask_b32_e64 v26, 0, v26, s[82:83]
	v_cndmask_b32_e64 v27, 0, v27, s[86:87]
	v_cndmask_b32_e64 v28, 0, v28, s[90:91]
	v_cndmask_b32_e64 v29, 0, v29, s[94:95]
	v_cndmask_b32_e64 v30, 0, v30, s[4:5]
	v_cndmask_b32_e64 v31, 0, v31, s[8:9]
	ds_write_b32 v177, v5 offset:55296
	v_cndmask_b32_e64 v32, 0, v32, s[12:13]
	v_cndmask_b32_e64 v5, 0, v17, s[14:15]
	v_cndmask_b32_e64 v33, 0, v33, s[16:17]
	v_cvt_pk_bf16_f32 v18, v18, v2
	v_cvt_pk_bf16_f32 v19, v3, v4
	v_cvt_pk_bf16_f32 v20, v20, v21
	v_cvt_pk_bf16_f32 v21, v24, v25
	v_add_u32_e32 v24, 0xb000, v182
	v_cndmask_b32_e64 v34, v34, 0, s[50:51]
	v_cndmask_b32_e64 v35, 0, v35, s[52:53]
	v_cndmask_b32_e64 v36, v36, 0, s[56:57]
	v_cndmask_b32_e64 v37, v37, 0, s[60:61]
	v_cndmask_b32_e64 v22, v38, 0, s[64:65]
	v_cndmask_b32_e64 v23, v39, 0, s[68:69]
	v_cndmask_b32_e64 v38, v40, 0, s[72:73]
	v_cndmask_b32_e64 v39, v41, 0, s[76:77]
	ds_write_b32 v178, v5 offset:55296
	ds_write2_b64 v24, v[18:19], v[20:21] offset0:128 offset1:130
	v_cvt_pk_bf16_f32 v18, v26, v27
	v_cvt_pk_bf16_f32 v19, v28, v29
	v_cvt_pk_bf16_f32 v20, v30, v31
	v_cvt_pk_bf16_f32 v21, v32, v33
	v_cndmask_b32_e64 v40, v42, 0, s[80:81]
	v_cndmask_b32_e64 v41, v43, 0, s[84:85]
	v_cndmask_b32_e64 v42, v44, 0, s[88:89]
	v_cndmask_b32_e64 v43, v45, 0, s[92:93]
	v_cndmask_b32_e64 v44, v46, 0, s[96:97]
	v_cndmask_b32_e64 v45, v47, 0, s[6:7]
	v_cndmask_b32_e64 v46, v48, 0, s[10:11]
	v_cndmask_b32_e64 v47, v49, 0, s[14:15]
	ds_write2_b64 v24, v[18:19], v[20:21] offset0:132 offset1:134
	v_cvt_pk_bf16_f32 v18, v34, v35
	v_cvt_pk_bf16_f32 v19, v36, v37
	v_cvt_pk_bf16_f32 v20, v22, v23
	v_cvt_pk_bf16_f32 v21, v38, v39
	ds_write2_b64 v184, v[18:19], v[20:21] offset0:128 offset1:130
	v_cvt_pk_bf16_f32 v18, v40, v41
	v_cvt_pk_bf16_f32 v19, v42, v43
	v_cvt_pk_bf16_f32 v20, v44, v45
	v_cvt_pk_bf16_f32 v21, v46, v47
	v_mov_b32_e32 v23, v110
	ds_write2_b64 v184, v[18:19], v[20:21] offset0:132 offset1:134
	s_waitcnt lgkmcnt(0)
	s_barrier
	v_mfma_f32_32x32x16_bf16 v[2:17], v[92:95], v[96:99], 0
	v_mfma_f32_32x32x16_bf16 v[2:17], v[100:103], v[196:199], v[2:17]
	v_mfma_f32_32x32x16_bf16 v[2:17], v[186:189], v[204:207], v[2:17]
	v_mfma_f32_32x32x16_bf16 v[2:17], v[200:203], v[212:215], v[2:17]
	v_readfirstlane_b32 s98, v0
	v_and_b32_e32 v233, 15, v0
	v_lshl_add_u32 v232, v233, 2, v23
	s_lshr_b32 s99, s98, 1
	s_xor_b32 s99, s99, s98
	s_bitcmp1_b32 s99, 7
	s_cbranch_scc1 .Ls3_idle
	v_and_b32_e32 v233, 63, v0
	s_bfe_u32 s98, s98, 0x10006
	s_mul_i32 s99, s98, 0x2400
	s_add_i32 s99, s99, 0xffffb800
	v_lshl_add_u32 v234, v233, 1, v23
	v_add_u32_e32 v234, s99, v234
	v_lshl_or_b32 v235, s98, 6, v233
	v_mul_u32_u24_e32 v235, 0x90, v235
	s_mov_b32 s99, 0xffff2800
	v_add3_u32 v235, v235, v23, s99
	ds_read_u16 v18, v234
	ds_read_u16 v19, v234 offset:144
	ds_read_u16 v20, v234 offset:288
	ds_read_u16 v21, v234 offset:432
	ds_read_u16 v22, v234 offset:576
	ds_read_u16 v24, v234 offset:720
	ds_read_u16 v25, v234 offset:864
	ds_read_u16 v26, v234 offset:1008
	ds_read_u16 v27, v234 offset:1152
	ds_read_u16 v28, v234 offset:1296
	ds_read_u16 v29, v234 offset:1440
	ds_read_u16 v30, v234 offset:1584
	s_waitcnt lgkmcnt(0)
	ds_read_u16 v31, v234 offset:1728
	ds_read_u16 v32, v234 offset:1872
	ds_read_u16 v33, v234 offset:2016
	ds_read_u16 v34, v234 offset:2160
	ds_read_u16 v35, v234 offset:2304
	ds_read_u16 v36, v234 offset:2448
	ds_read_u16 v37, v234 offset:2592
	ds_read_u16 v38, v234 offset:2736
	ds_read_u16 v39, v234 offset:2880
	ds_read_u16 v40, v234 offset:3024
	ds_read_u16 v41, v234 offset:3168
	ds_read_u16 v42, v234 offset:3312
	v_lshlrev_b32_e32 v18, 16, v18
	v_lshlrev_b32_e32 v19, 16, v19
	v_lshlrev_b32_e32 v20, 16, v20
	v_lshlrev_b32_e32 v21, 16, v21
	v_lshlrev_b32_e32 v22, 16, v22
	v_lshlrev_b32_e32 v24, 16, v24
	v_lshlrev_b32_e32 v25, 16, v25
	v_lshlrev_b32_e32 v26, 16, v26
	v_lshlrev_b32_e32 v27, 16, v27
	v_lshlrev_b32_e32 v28, 16, v28
	v_lshlrev_b32_e32 v29, 16, v29
	v_lshlrev_b32_e32 v30, 16, v30
	s_waitcnt lgkmcnt(0)
	ds_read_u16 v43, v234 offset:3456
	ds_read_u16 v44, v234 offset:3600
	ds_read_u16 v45, v234 offset:3744
	ds_read_u16 v46, v234 offset:3888
	ds_read_u16 v47, v234 offset:4032
	ds_read_u16 v48, v234 offset:4176
	ds_read_u16 v49, v234 offset:4320
	ds_read_u16 v91, v234 offset:4464
	ds_read_u16 v92, v234 offset:4608
	ds_read_u16 v93, v234 offset:4752
	ds_read_u16 v94, v234 offset:4896
	ds_read_u16 v95, v234 offset:5040
	v_lshlrev_b32_e32 v31, 16, v31
	v_lshlrev_b32_e32 v32, 16, v32
	v_lshlrev_b32_e32 v33, 16, v33
	v_lshlrev_b32_e32 v34, 16, v34
	v_lshlrev_b32_e32 v35, 16, v35
	v_lshlrev_b32_e32 v36, 16, v36
	v_lshlrev_b32_e32 v37, 16, v37
	v_lshlrev_b32_e32 v38, 16, v38
	v_lshlrev_b32_e32 v39, 16, v39
	v_lshlrev_b32_e32 v40, 16, v40
	v_lshlrev_b32_e32 v41, 16, v41
	v_lshlrev_b32_e32 v42, 16, v42
	s_waitcnt lgkmcnt(0)
	ds_read_u16 v96, v234 offset:5184
	ds_read_u16 v97, v234 offset:5328
	ds_read_u16 v98, v234 offset:5472
	ds_read_u16 v99, v234 offset:5616
	ds_read_u16 v100, v234 offset:5760
	ds_read_u16 v101, v234 offset:5904
	ds_read_u16 v102, v234 offset:6048
	ds_read_u16 v103, v234 offset:6192
	ds_read_u16 v104, v234 offset:6336
	ds_read_u16 v105, v234 offset:6480
	ds_read_u16 v185, v234 offset:6624
	ds_read_u16 v186, v234 offset:6768
	v_lshlrev_b32_e32 v43, 16, v43
	v_lshlrev_b32_e32 v44, 16, v44
	v_lshlrev_b32_e32 v45, 16, v45
	v_lshlrev_b32_e32 v46, 16, v46
	v_lshlrev_b32_e32 v47, 16, v47
	v_lshlrev_b32_e32 v48, 16, v48
	v_lshlrev_b32_e32 v49, 16, v49
	v_lshlrev_b32_e32 v91, 16, v91
	v_lshlrev_b32_e32 v92, 16, v92
	v_lshlrev_b32_e32 v93, 16, v93
	v_lshlrev_b32_e32 v94, 16, v94
	v_lshlrev_b32_e32 v95, 16, v95
	s_waitcnt lgkmcnt(0)
	ds_read_u16 v187, v234 offset:6912
	ds_read_u16 v188, v234 offset:7056
	ds_read_u16 v189, v234 offset:7200
	ds_read_u16 v190, v234 offset:7344
	ds_read_u16 v192, v234 offset:7488
	ds_read_u16 v193, v234 offset:7632
	ds_read_u16 v194, v234 offset:7776
	ds_read_u16 v195, v234 offset:7920
	ds_read_u16 v196, v234 offset:8064
	ds_read_u16 v197, v234 offset:8208
	ds_read_u16 v198, v234 offset:8352
	ds_read_u16 v199, v234 offset:8496
	v_lshlrev_b32_e32 v96, 16, v96
	v_lshlrev_b32_e32 v97, 16, v97
	v_lshlrev_b32_e32 v98, 16, v98
	v_lshlrev_b32_e32 v99, 16, v99
	v_lshlrev_b32_e32 v100, 16, v100
	v_lshlrev_b32_e32 v101, 16, v101
	v_lshlrev_b32_e32 v102, 16, v102
	v_lshlrev_b32_e32 v103, 16, v103
	v_lshlrev_b32_e32 v104, 16, v104
	v_lshlrev_b32_e32 v105, 16, v105
	v_lshlrev_b32_e32 v185, 16, v185
	v_lshlrev_b32_e32 v186, 16, v186
	s_waitcnt lgkmcnt(0)
	ds_read_u16 v200, v234 offset:8640
	ds_read_u16 v201, v234 offset:8784
	ds_read_u16 v202, v234 offset:8928
	ds_read_u16 v203, v234 offset:9072
	v_lshlrev_b32_e32 v187, 16, v187
	v_lshlrev_b32_e32 v188, 16, v188
	v_lshlrev_b32_e32 v189, 16, v189
	v_lshlrev_b32_e32 v190, 16, v190
	v_lshlrev_b32_e32 v192, 16, v192
	v_lshlrev_b32_e32 v193, 16, v193
	v_lshlrev_b32_e32 v194, 16, v194
	v_lshlrev_b32_e32 v195, 16, v195
	v_lshlrev_b32_e32 v196, 16, v196
	v_lshlrev_b32_e32 v197, 16, v197
	v_lshlrev_b32_e32 v198, 16, v198
	v_lshlrev_b32_e32 v199, 16, v199
	s_waitcnt lgkmcnt(0)
	v_lshlrev_b32_e32 v200, 16, v200
	v_lshlrev_b32_e32 v201, 16, v201
	v_lshlrev_b32_e32 v202, 16, v202
	v_lshlrev_b32_e32 v203, 16, v203
	ds_read_b32 v204, v232 offset:272
	ds_read_b32 v205, v232 offset:544
	ds_read_b32 v206, v232 offset:816
	ds_read_b32 v207, v232 offset:1088
	ds_read_b32 v208, v232 offset:1360
	ds_read_b32 v209, v232 offset:1632
	ds_read_b32 v210, v232 offset:1904
	ds_read_b32 v211, v232 offset:2176
	ds_read_b32 v212, v232 offset:2448
	ds_read_b32 v213, v232 offset:2720
	ds_read_b32 v214, v232 offset:2992
	ds_read_b32 v215, v232 offset:3264
	s_waitcnt lgkmcnt(11)
	v_fmac_f32_dpp v19, v204, v18 row_newbcast:0 row_mask:0xf bank_mask:0xf
	ds_read_b32 v204, v232 offset:3536
	s_waitcnt lgkmcnt(11)
	v_fmac_f32_dpp v20, v205, v18 row_newbcast:0 row_mask:0xf bank_mask:0xf
	v_mul_f32_dpp v222, v205, v19 row_newbcast:1 row_mask:0xf bank_mask:0xf
	v_add_f32_e32 v20, v20, v222
	ds_read_b32 v205, v232 offset:3808
	s_waitcnt lgkmcnt(11)
	v_fmac_f32_dpp v21, v206, v18 row_newbcast:0 row_mask:0xf bank_mask:0xf
	v_mul_f32_dpp v225, v206, v19 row_newbcast:1 row_mask:0xf bank_mask:0xf
	v_mul_f32_dpp v228, v206, v20 row_newbcast:2 row_mask:0xf bank_mask:0xf
	v_add_f32_e32 v21, v21, v225
	v_add_f32_e32 v21, v21, v228
	ds_read_b32 v206, v232 offset:4080
	s_waitcnt lgkmcnt(11)
	v_fmac_f32_dpp v22, v207, v18 row_newbcast:0 row_mask:0xf bank_mask:0xf
	v_mul_f32_dpp v222, v207, v19 row_newbcast:1 row_mask:0xf bank_mask:0xf
	v_mul_f32_dpp v223, v207, v20 row_newbcast:2 row_mask:0xf bank_mask:0xf
	v_mul_f32_dpp v224, v207, v21 row_newbcast:3 row_mask:0xf bank_mask:0xf
	v_add_f32_e32 v22, v22, v222
	v_add_f32_e32 v223, v223, v224
	v_add_f32_e32 v22, v22, v223
	ds_read_b32 v207, v232 offset:4352
	s_waitcnt lgkmcnt(11)
	v_fmac_f32_dpp v24, v208, v18 row_newbcast:0 row_mask:0xf bank_mask:0xf
	v_mul_f32_dpp v225, v208, v19 row_newbcast:1 row_mask:0xf bank_mask:0xf
	v_mul_f32_dpp v228, v208, v20 row_newbcast:2 row_mask:0xf bank_mask:0xf
	v_mul_f32_dpp v229, v208, v21 row_newbcast:3 row_mask:0xf bank_mask:0xf
	v_fmac_f32_dpp v24, v208, v22 row_newbcast:4 row_mask:0xf bank_mask:0xf
	v_add_f32_e32 v24, v24, v225
	v_add_f32_e32 v228, v228, v229
	v_add_f32_e32 v24, v24, v228
	ds_read_b32 v208, v232 offset:4624
	s_waitcnt lgkmcnt(11)
	v_fmac_f32_dpp v25, v209, v18 row_newbcast:0 row_mask:0xf bank_mask:0xf
	v_mul_f32_dpp v222, v209, v19 row_newbcast:1 row_mask:0xf bank_mask:0xf
	v_mul_f32_dpp v223, v209, v20 row_newbcast:2 row_mask:0xf bank_mask:0xf
	v_mul_f32_dpp v224, v209, v21 row_newbcast:3 row_mask:0xf bank_mask:0xf
	v_fmac_f32_dpp v25, v209, v22 row_newbcast:4 row_mask:0xf bank_mask:0xf
	v_fmac_f32_dpp v222, v209, v24 row_newbcast:5 row_mask:0xf bank_mask:0xf
	v_add_f32_e32 v25, v25, v222
	v_add_f32_e32 v223, v223, v224
	v_add_f32_e32 v25, v25, v223
	ds_read_b32 v209, v232 offset:4688
	s_waitcnt lgkmcnt(11)
	v_fmac_f32_dpp v26, v210, v18 row_newbcast:0 row_mask:0xf bank_mask:0xf
	v_mul_f32_dpp v225, v210, v19 row_newbcast:1 row_mask:0xf bank_mask:0xf
	v_mul_f32_dpp v228, v210, v20 row_newbcast:2 row_mask:0xf bank_mask:0xf
	v_mul_f32_dpp v229, v210, v21 row_newbcast:3 row_mask:0xf bank_mask:0xf
	v_fmac_f32_dpp v26, v210, v22 row_newbcast:4 row_mask:0xf bank_mask:0xf
	v_fmac_f32_dpp v225, v210, v24 row_newbcast:5 row_mask:0xf bank_mask:0xf
	v_fmac_f32_dpp v228, v210, v25 row_newbcast:6 row_mask:0xf bank_mask:0xf
	v_add_f32_e32 v26, v26, v225
	v_add_f32_e32 v228, v228, v229
	v_add_f32_e32 v26, v26, v228
	ds_read_b32 v210, v232 offset:4896
	s_waitcnt lgkmcnt(11)
	v_fmac_f32_dpp v27, v211, v18 row_newbcast:0 row_mask:0xf bank_mask:0xf
	v_mul_f32_dpp v222, v211, v19 row_newbcast:1 row_mask:0xf bank_mask:0xf
	v_mul_f32_dpp v223, v211, v20 row_newbcast:2 row_mask:0xf bank_mask:0xf
	v_mul_f32_dpp v224, v211, v21 row_newbcast:3 row_mask:0xf bank_mask:0xf
	v_fmac_f32_dpp v27, v211, v22 row_newbcast:4 row_mask:0xf bank_mask:0xf
	v_fmac_f32_dpp v222, v211, v24 row_newbcast:5 row_mask:0xf bank_mask:0xf
	v_fmac_f32_dpp v223, v211, v25 row_newbcast:6 row_mask:0xf bank_mask:0xf
	v_fmac_f32_dpp v224, v211, v26 row_newbcast:7 row_mask:0xf bank_mask:0xf
	v_add_f32_e32 v27, v27, v222
	v_add_f32_e32 v223, v223, v224
	v_add_f32_e32 v27, v27, v223
	ds_read_b32 v211, v232 offset:4960
	s_waitcnt lgkmcnt(11)
	v_fmac_f32_dpp v28, v212, v18 row_newbcast:0 row_mask:0xf bank_mask:0xf
	v_mul_f32_dpp v225, v212, v19 row_newbcast:1 row_mask:0xf bank_mask:0xf
	v_mul_f32_dpp v228, v212, v20 row_newbcast:2 row_mask:0xf bank_mask:0xf
	v_mul_f32_dpp v229, v212, v21 row_newbcast:3 row_mask:0xf bank_mask:0xf
	v_fmac_f32_dpp v28, v212, v22 row_newbcast:4 row_mask:0xf bank_mask:0xf
	v_fmac_f32_dpp v225, v212, v24 row_newbcast:5 row_mask:0xf bank_mask:0xf
	v_fmac_f32_dpp v228, v212, v25 row_newbcast:6 row_mask:0xf bank_mask:0xf
	v_fmac_f32_dpp v229, v212, v26 row_newbcast:7 row_mask:0xf bank_mask:0xf
	v_fmac_f32_dpp v28, v212, v27 row_newbcast:8 row_mask:0xf bank_mask:0xf
	v_add_f32_e32 v28, v28, v225
	v_add_f32_e32 v228, v228, v229
	v_add_f32_e32 v28, v28, v228
	ds_read_b32 v212, v232 offset:5168
	s_waitcnt lgkmcnt(11)
	v_fmac_f32_dpp v29, v213, v18 row_newbcast:0 row_mask:0xf bank_mask:0xf
	v_mul_f32_dpp v222, v213, v19 row_newbcast:1 row_mask:0xf bank_mask:0xf
	v_mul_f32_dpp v223, v213, v20 row_newbcast:2 row_mask:0xf bank_mask:0xf
	v_mul_f32_dpp v224, v213, v21 row_newbcast:3 row_mask:0xf bank_mask:0xf
	v_fmac_f32_dpp v29, v213, v22 row_newbcast:4 row_mask:0xf bank_mask:0xf
	v_fmac_f32_dpp v222, v213, v24 row_newbcast:5 row_mask:0xf bank_mask:0xf
	v_fmac_f32_dpp v223, v213, v25 row_newbcast:6 row_mask:0xf bank_mask:0xf
	v_fmac_f32_dpp v224, v213, v26 row_newbcast:7 row_mask:0xf bank_mask:0xf
	v_fmac_f32_dpp v29, v213, v27 row_newbcast:8 row_mask:0xf bank_mask:0xf
	v_fmac_f32_dpp v222, v213, v28 row_newbcast:9 row_mask:0xf bank_mask:0xf
	v_add_f32_e32 v29, v29, v222
	v_add_f32_e32 v223, v223, v224
	v_add_f32_e32 v29, v29, v223
	ds_read_b32 v213, v232 offset:5232
	s_waitcnt lgkmcnt(11)
	v_fmac_f32_dpp v30, v214, v18 row_newbcast:0 row_mask:0xf bank_mask:0xf
	v_mul_f32_dpp v225, v214, v19 row_newbcast:1 row_mask:0xf bank_mask:0xf
	v_mul_f32_dpp v228, v214, v20 row_newbcast:2 row_mask:0xf bank_mask:0xf
	v_mul_f32_dpp v229, v214, v21 row_newbcast:3 row_mask:0xf bank_mask:0xf
	v_fmac_f32_dpp v30, v214, v22 row_newbcast:4 row_mask:0xf bank_mask:0xf
	v_fmac_f32_dpp v225, v214, v24 row_newbcast:5 row_mask:0xf bank_mask:0xf
	v_fmac_f32_dpp v228, v214, v25 row_newbcast:6 row_mask:0xf bank_mask:0xf
	v_fmac_f32_dpp v229, v214, v26 row_newbcast:7 row_mask:0xf bank_mask:0xf
	v_fmac_f32_dpp v30, v214, v27 row_newbcast:8 row_mask:0xf bank_mask:0xf
	v_fmac_f32_dpp v225, v214, v28 row_newbcast:9 row_mask:0xf bank_mask:0xf
	v_fmac_f32_dpp v228, v214, v29 row_newbcast:10 row_mask:0xf bank_mask:0xf
	v_add_f32_e32 v30, v30, v225
	v_add_f32_e32 v228, v228, v229
	v_add_f32_e32 v30, v30, v228
	ds_read_b32 v214, v232 offset:5440
	s_waitcnt lgkmcnt(11)
	v_fmac_f32_dpp v31, v215, v18 row_newbcast:0 row_mask:0xf bank_mask:0xf
	v_mul_f32_dpp v222, v215, v19 row_newbcast:1 row_mask:0xf bank_mask:0xf
	v_mul_f32_dpp v223, v215, v20 row_newbcast:2 row_mask:0xf bank_mask:0xf
	v_mul_f32_dpp v224, v215, v21 row_newbcast:3 row_mask:0xf bank_mask:0xf
	v_fmac_f32_dpp v31, v215, v22 row_newbcast:4 row_mask:0xf bank_mask:0xf
	v_fmac_f32_dpp v222, v215, v24 row_newbcast:5 row_mask:0xf bank_mask:0xf
	v_fmac_f32_dpp v223, v215, v25 row_newbcast:6 row_mask:0xf bank_mask:0xf
	v_fmac_f32_dpp v224, v215, v26 row_newbcast:7 row_mask:0xf bank_mask:0xf
	v_fmac_f32_dpp v31, v215, v27 row_newbcast:8 row_mask:0xf bank_mask:0xf
	v_fmac_f32_dpp v222, v215, v28 row_newbcast:9 row_mask:0xf bank_mask:0xf
	v_fmac_f32_dpp v223, v215, v29 row_newbcast:10 row_mask:0xf bank_mask:0xf
	v_fmac_f32_dpp v224, v215, v30 row_newbcast:11 row_mask:0xf bank_mask:0xf
	v_add_f32_e32 v31, v31, v222
	v_add_f32_e32 v223, v223, v224
	v_add_f32_e32 v31, v31, v223
	ds_read_b32 v215, v232 offset:5504
	s_waitcnt lgkmcnt(11)
	v_fmac_f32_dpp v32, v204, v18 row_newbcast:0 row_mask:0xf bank_mask:0xf
	v_mul_f32_dpp v225, v204, v19 row_newbcast:1 row_mask:0xf bank_mask:0xf
	v_mul_f32_dpp v228, v204, v20 row_newbcast:2 row_mask:0xf bank_mask:0xf
	v_mul_f32_dpp v229, v204, v21 row_newbcast:3 row_mask:0xf bank_mask:0xf
	v_fmac_f32_dpp v32, v204, v22 row_newbcast:4 row_mask:0xf bank_mask:0xf
	v_fmac_f32_dpp v225, v204, v24 row_newbcast:5 row_mask:0xf bank_mask:0xf
	v_fmac_f32_dpp v228, v204, v25 row_newbcast:6 row_mask:0xf bank_mask:0xf
	v_fmac_f32_dpp v229, v204, v26 row_newbcast:7 row_mask:0xf bank_mask:0xf
	v_fmac_f32_dpp v32, v204, v27 row_newbcast:8 row_mask:0xf bank_mask:0xf
	v_fmac_f32_dpp v225, v204, v28 row_newbcast:9 row_mask:0xf bank_mask:0xf
	v_fmac_f32_dpp v228, v204, v29 row_newbcast:10 row_mask:0xf bank_mask:0xf
	v_fmac_f32_dpp v229, v204, v30 row_newbcast:11 row_mask:0xf bank_mask:0xf
	v_fmac_f32_dpp v32, v204, v31 row_newbcast:12 row_mask:0xf bank_mask:0xf
	v_add_f32_e32 v32, v32, v225
	v_add_f32_e32 v228, v228, v229
	v_add_f32_e32 v32, v32, v228
	ds_read_b32 v204, v232 offset:5712
	s_waitcnt lgkmcnt(11)
	v_fmac_f32_dpp v33, v205, v18 row_newbcast:0 row_mask:0xf bank_mask:0xf
	v_mul_f32_dpp v222, v205, v19 row_newbcast:1 row_mask:0xf bank_mask:0xf
	v_mul_f32_dpp v223, v205, v20 row_newbcast:2 row_mask:0xf bank_mask:0xf
	v_mul_f32_dpp v224, v205, v21 row_newbcast:3 row_mask:0xf bank_mask:0xf
	v_fmac_f32_dpp v33, v205, v22 row_newbcast:4 row_mask:0xf bank_mask:0xf
	v_fmac_f32_dpp v222, v205, v24 row_newbcast:5 row_mask:0xf bank_mask:0xf
	v_fmac_f32_dpp v223, v205, v25 row_newbcast:6 row_mask:0xf bank_mask:0xf
	v_fmac_f32_dpp v224, v205, v26 row_newbcast:7 row_mask:0xf bank_mask:0xf
	v_fmac_f32_dpp v33, v205, v27 row_newbcast:8 row_mask:0xf bank_mask:0xf
	v_fmac_f32_dpp v222, v205, v28 row_newbcast:9 row_mask:0xf bank_mask:0xf
	v_fmac_f32_dpp v223, v205, v29 row_newbcast:10 row_mask:0xf bank_mask:0xf
	v_fmac_f32_dpp v224, v205, v30 row_newbcast:11 row_mask:0xf bank_mask:0xf
	v_fmac_f32_dpp v33, v205, v31 row_newbcast:12 row_mask:0xf bank_mask:0xf
	v_fmac_f32_dpp v222, v205, v32 row_newbcast:13 row_mask:0xf bank_mask:0xf
	v_add_f32_e32 v33, v33, v222
	v_add_f32_e32 v223, v223, v224
	v_add_f32_e32 v33, v33, v223
	ds_read_b32 v205, v232 offset:5776
	s_waitcnt lgkmcnt(11)
	v_fmac_f32_dpp v34, v206, v18 row_newbcast:0 row_mask:0xf bank_mask:0xf
	v_mul_f32_dpp v225, v206, v19 row_newbcast:1 row_mask:0xf bank_mask:0xf
	v_mul_f32_dpp v228, v206, v20 row_newbcast:2 row_mask:0xf bank_mask:0xf
	v_mul_f32_dpp v229, v206, v21 row_newbcast:3 row_mask:0xf bank_mask:0xf
	v_fmac_f32_dpp v34, v206, v22 row_newbcast:4 row_mask:0xf bank_mask:0xf
	v_fmac_f32_dpp v225, v206, v24 row_newbcast:5 row_mask:0xf bank_mask:0xf
	v_fmac_f32_dpp v228, v206, v25 row_newbcast:6 row_mask:0xf bank_mask:0xf
	v_fmac_f32_dpp v229, v206, v26 row_newbcast:7 row_mask:0xf bank_mask:0xf
	v_fmac_f32_dpp v34, v206, v27 row_newbcast:8 row_mask:0xf bank_mask:0xf
	v_fmac_f32_dpp v225, v206, v28 row_newbcast:9 row_mask:0xf bank_mask:0xf
	v_fmac_f32_dpp v228, v206, v29 row_newbcast:10 row_mask:0xf bank_mask:0xf
	v_fmac_f32_dpp v229, v206, v30 row_newbcast:11 row_mask:0xf bank_mask:0xf
	v_fmac_f32_dpp v34, v206, v31 row_newbcast:12 row_mask:0xf bank_mask:0xf
	v_fmac_f32_dpp v225, v206, v32 row_newbcast:13 row_mask:0xf bank_mask:0xf
	v_fmac_f32_dpp v228, v206, v33 row_newbcast:14 row_mask:0xf bank_mask:0xf
	v_add_f32_e32 v34, v34, v225
	v_add_f32_e32 v228, v228, v229
	v_add_f32_e32 v34, v34, v228
	ds_read_b32 v206, v232 offset:5984
	s_waitcnt lgkmcnt(11)
	v_fmac_f32_dpp v35, v207, v18 row_newbcast:0 row_mask:0xf bank_mask:0xf
	v_mul_f32_dpp v222, v207, v19 row_newbcast:1 row_mask:0xf bank_mask:0xf
	v_mul_f32_dpp v223, v207, v20 row_newbcast:2 row_mask:0xf bank_mask:0xf
	v_mul_f32_dpp v224, v207, v21 row_newbcast:3 row_mask:0xf bank_mask:0xf
	v_fmac_f32_dpp v35, v207, v22 row_newbcast:4 row_mask:0xf bank_mask:0xf
	v_fmac_f32_dpp v222, v207, v24 row_newbcast:5 row_mask:0xf bank_mask:0xf
	v_fmac_f32_dpp v223, v207, v25 row_newbcast:6 row_mask:0xf bank_mask:0xf
	v_fmac_f32_dpp v224, v207, v26 row_newbcast:7 row_mask:0xf bank_mask:0xf
	v_fmac_f32_dpp v35, v207, v27 row_newbcast:8 row_mask:0xf bank_mask:0xf
	v_fmac_f32_dpp v222, v207, v28 row_newbcast:9 row_mask:0xf bank_mask:0xf
	v_fmac_f32_dpp v223, v207, v29 row_newbcast:10 row_mask:0xf bank_mask:0xf
	v_fmac_f32_dpp v224, v207, v30 row_newbcast:11 row_mask:0xf bank_mask:0xf
	v_fmac_f32_dpp v35, v207, v31 row_newbcast:12 row_mask:0xf bank_mask:0xf
	v_fmac_f32_dpp v222, v207, v32 row_newbcast:13 row_mask:0xf bank_mask:0xf
	v_fmac_f32_dpp v223, v207, v33 row_newbcast:14 row_mask:0xf bank_mask:0xf
	v_fmac_f32_dpp v224, v207, v34 row_newbcast:15 row_mask:0xf bank_mask:0xf
	v_add_f32_e32 v35, v35, v222
	v_add_f32_e32 v223, v223, v224
	v_add_f32_e32 v35, v35, v223
	ds_read_b32 v207, v232 offset:6048
	s_waitcnt lgkmcnt(11)
	v_fmac_f32_dpp v36, v208, v18 row_newbcast:0 row_mask:0xf bank_mask:0xf
	v_mul_f32_dpp v225, v208, v19 row_newbcast:1 row_mask:0xf bank_mask:0xf
	v_mul_f32_dpp v228, v208, v20 row_newbcast:2 row_mask:0xf bank_mask:0xf
	v_mul_f32_dpp v229, v208, v21 row_newbcast:3 row_mask:0xf bank_mask:0xf
	v_fmac_f32_dpp v36, v208, v22 row_newbcast:4 row_mask:0xf bank_mask:0xf
	v_fmac_f32_dpp v225, v208, v24 row_newbcast:5 row_mask:0xf bank_mask:0xf
	v_fmac_f32_dpp v228, v208, v25 row_newbcast:6 row_mask:0xf bank_mask:0xf
	v_fmac_f32_dpp v229, v208, v26 row_newbcast:7 row_mask:0xf bank_mask:0xf
	v_fmac_f32_dpp v36, v208, v27 row_newbcast:8 row_mask:0xf bank_mask:0xf
	v_fmac_f32_dpp v225, v208, v28 row_newbcast:9 row_mask:0xf bank_mask:0xf
	v_fmac_f32_dpp v228, v208, v29 row_newbcast:10 row_mask:0xf bank_mask:0xf
	v_fmac_f32_dpp v229, v208, v30 row_newbcast:11 row_mask:0xf bank_mask:0xf
	v_fmac_f32_dpp v36, v208, v31 row_newbcast:12 row_mask:0xf bank_mask:0xf
	v_fmac_f32_dpp v225, v208, v32 row_newbcast:13 row_mask:0xf bank_mask:0xf
	v_fmac_f32_dpp v228, v208, v33 row_newbcast:14 row_mask:0xf bank_mask:0xf
	v_fmac_f32_dpp v229, v208, v34 row_newbcast:15 row_mask:0xf bank_mask:0xf
	ds_read_b32 v208, v232 offset:6256
	s_waitcnt lgkmcnt(11)
	v_fmac_f32_dpp v36, v209, v35 row_newbcast:0 row_mask:0xf bank_mask:0xf
	v_add_f32_e32 v36, v36, v225
	v_add_f32_e32 v228, v228, v229
	v_add_f32_e32 v36, v36, v228
	ds_read_b32 v209, v232 offset:6320
	s_waitcnt lgkmcnt(11)
	v_fmac_f32_dpp v37, v210, v18 row_newbcast:0 row_mask:0xf bank_mask:0xf
	v_mul_f32_dpp v222, v210, v19 row_newbcast:1 row_mask:0xf bank_mask:0xf
	v_mul_f32_dpp v223, v210, v20 row_newbcast:2 row_mask:0xf bank_mask:0xf
	v_mul_f32_dpp v224, v210, v21 row_newbcast:3 row_mask:0xf bank_mask:0xf
	v_fmac_f32_dpp v37, v210, v22 row_newbcast:4 row_mask:0xf bank_mask:0xf
	v_fmac_f32_dpp v222, v210, v24 row_newbcast:5 row_mask:0xf bank_mask:0xf
	v_fmac_f32_dpp v223, v210, v25 row_newbcast:6 row_mask:0xf bank_mask:0xf
	v_fmac_f32_dpp v224, v210, v26 row_newbcast:7 row_mask:0xf bank_mask:0xf
	v_fmac_f32_dpp v37, v210, v27 row_newbcast:8 row_mask:0xf bank_mask:0xf
	v_fmac_f32_dpp v222, v210, v28 row_newbcast:9 row_mask:0xf bank_mask:0xf
	v_fmac_f32_dpp v223, v210, v29 row_newbcast:10 row_mask:0xf bank_mask:0xf
	v_fmac_f32_dpp v224, v210, v30 row_newbcast:11 row_mask:0xf bank_mask:0xf
	v_fmac_f32_dpp v37, v210, v31 row_newbcast:12 row_mask:0xf bank_mask:0xf
	v_fmac_f32_dpp v222, v210, v32 row_newbcast:13 row_mask:0xf bank_mask:0xf
	v_fmac_f32_dpp v223, v210, v33 row_newbcast:14 row_mask:0xf bank_mask:0xf
	v_fmac_f32_dpp v224, v210, v34 row_newbcast:15 row_mask:0xf bank_mask:0xf
	ds_read_b32 v210, v232 offset:6528
	s_waitcnt lgkmcnt(11)
	v_fmac_f32_dpp v37, v211, v35 row_newbcast:0 row_mask:0xf bank_mask:0xf
	v_fmac_f32_dpp v222, v211, v36 row_newbcast:1 row_mask:0xf bank_mask:0xf
	v_add_f32_e32 v37, v37, v222
	v_add_f32_e32 v223, v223, v224
	v_add_f32_e32 v37, v37, v223
	ds_read_b32 v211, v232 offset:6592
	s_waitcnt lgkmcnt(11)
	v_fmac_f32_dpp v38, v212, v18 row_newbcast:0 row_mask:0xf bank_mask:0xf
	v_mul_f32_dpp v225, v212, v19 row_newbcast:1 row_mask:0xf bank_mask:0xf
	v_mul_f32_dpp v228, v212, v20 row_newbcast:2 row_mask:0xf bank_mask:0xf
	v_mul_f32_dpp v229, v212, v21 row_newbcast:3 row_mask:0xf bank_mask:0xf
	v_fmac_f32_dpp v38, v212, v22 row_newbcast:4 row_mask:0xf bank_mask:0xf
	v_fmac_f32_dpp v225, v212, v24 row_newbcast:5 row_mask:0xf bank_mask:0xf
	v_fmac_f32_dpp v228, v212, v25 row_newbcast:6 row_mask:0xf bank_mask:0xf
	v_fmac_f32_dpp v229, v212, v26 row_newbcast:7 row_mask:0xf bank_mask:0xf
	v_fmac_f32_dpp v38, v212, v27 row_newbcast:8 row_mask:0xf bank_mask:0xf
	v_fmac_f32_dpp v225, v212, v28 row_newbcast:9 row_mask:0xf bank_mask:0xf
	v_fmac_f32_dpp v228, v212, v29 row_newbcast:10 row_mask:0xf bank_mask:0xf
	v_fmac_f32_dpp v229, v212, v30 row_newbcast:11 row_mask:0xf bank_mask:0xf
	v_fmac_f32_dpp v38, v212, v31 row_newbcast:12 row_mask:0xf bank_mask:0xf
	v_fmac_f32_dpp v225, v212, v32 row_newbcast:13 row_mask:0xf bank_mask:0xf
	v_fmac_f32_dpp v228, v212, v33 row_newbcast:14 row_mask:0xf bank_mask:0xf
	v_fmac_f32_dpp v229, v212, v34 row_newbcast:15 row_mask:0xf bank_mask:0xf
	ds_read_b32 v212, v232 offset:6800
	s_waitcnt lgkmcnt(11)
	v_fmac_f32_dpp v38, v213, v35 row_newbcast:0 row_mask:0xf bank_mask:0xf
	v_fmac_f32_dpp v225, v213, v36 row_newbcast:1 row_mask:0xf bank_mask:0xf
	v_fmac_f32_dpp v228, v213, v37 row_newbcast:2 row_mask:0xf bank_mask:0xf
	v_add_f32_e32 v38, v38, v225
	v_add_f32_e32 v228, v228, v229
	v_add_f32_e32 v38, v38, v228
	ds_read_b32 v213, v232 offset:6864
	s_waitcnt lgkmcnt(11)
	v_fmac_f32_dpp v39, v214, v18 row_newbcast:0 row_mask:0xf bank_mask:0xf
	v_mul_f32_dpp v222, v214, v19 row_newbcast:1 row_mask:0xf bank_mask:0xf
	v_mul_f32_dpp v223, v214, v20 row_newbcast:2 row_mask:0xf bank_mask:0xf
	v_mul_f32_dpp v224, v214, v21 row_newbcast:3 row_mask:0xf bank_mask:0xf
	v_fmac_f32_dpp v39, v214, v22 row_newbcast:4 row_mask:0xf bank_mask:0xf
	v_fmac_f32_dpp v222, v214, v24 row_newbcast:5 row_mask:0xf bank_mask:0xf
	v_fmac_f32_dpp v223, v214, v25 row_newbcast:6 row_mask:0xf bank_mask:0xf
	v_fmac_f32_dpp v224, v214, v26 row_newbcast:7 row_mask:0xf bank_mask:0xf
	v_fmac_f32_dpp v39, v214, v27 row_newbcast:8 row_mask:0xf bank_mask:0xf
	v_fmac_f32_dpp v222, v214, v28 row_newbcast:9 row_mask:0xf bank_mask:0xf
	v_fmac_f32_dpp v223, v214, v29 row_newbcast:10 row_mask:0xf bank_mask:0xf
	v_fmac_f32_dpp v224, v214, v30 row_newbcast:11 row_mask:0xf bank_mask:0xf
	v_fmac_f32_dpp v39, v214, v31 row_newbcast:12 row_mask:0xf bank_mask:0xf
	v_fmac_f32_dpp v222, v214, v32 row_newbcast:13 row_mask:0xf bank_mask:0xf
	v_fmac_f32_dpp v223, v214, v33 row_newbcast:14 row_mask:0xf bank_mask:0xf
	v_fmac_f32_dpp v224, v214, v34 row_newbcast:15 row_mask:0xf bank_mask:0xf
	ds_read_b32 v214, v232 offset:7072
	s_waitcnt lgkmcnt(11)
	v_fmac_f32_dpp v39, v215, v35 row_newbcast:0 row_mask:0xf bank_mask:0xf
	v_fmac_f32_dpp v222, v215, v36 row_newbcast:1 row_mask:0xf bank_mask:0xf
	v_fmac_f32_dpp v223, v215, v37 row_newbcast:2 row_mask:0xf bank_mask:0xf
	v_fmac_f32_dpp v224, v215, v38 row_newbcast:3 row_mask:0xf bank_mask:0xf
	v_add_f32_e32 v39, v39, v222
	v_add_f32_e32 v223, v223, v224
	v_add_f32_e32 v39, v39, v223
	ds_read_b32 v215, v232 offset:7136
	s_waitcnt lgkmcnt(11)
	v_fmac_f32_dpp v40, v204, v18 row_newbcast:0 row_mask:0xf bank_mask:0xf
	v_mul_f32_dpp v225, v204, v19 row_newbcast:1 row_mask:0xf bank_mask:0xf
	v_mul_f32_dpp v228, v204, v20 row_newbcast:2 row_mask:0xf bank_mask:0xf
	v_mul_f32_dpp v229, v204, v21 row_newbcast:3 row_mask:0xf bank_mask:0xf
	v_fmac_f32_dpp v40, v204, v22 row_newbcast:4 row_mask:0xf bank_mask:0xf
	v_fmac_f32_dpp v225, v204, v24 row_newbcast:5 row_mask:0xf bank_mask:0xf
	v_fmac_f32_dpp v228, v204, v25 row_newbcast:6 row_mask:0xf bank_mask:0xf
	v_fmac_f32_dpp v229, v204, v26 row_newbcast:7 row_mask:0xf bank_mask:0xf
	v_fmac_f32_dpp v40, v204, v27 row_newbcast:8 row_mask:0xf bank_mask:0xf
	v_fmac_f32_dpp v225, v204, v28 row_newbcast:9 row_mask:0xf bank_mask:0xf
	v_fmac_f32_dpp v228, v204, v29 row_newbcast:10 row_mask:0xf bank_mask:0xf
	v_fmac_f32_dpp v229, v204, v30 row_newbcast:11 row_mask:0xf bank_mask:0xf
	v_fmac_f32_dpp v40, v204, v31 row_newbcast:12 row_mask:0xf bank_mask:0xf
	v_fmac_f32_dpp v225, v204, v32 row_newbcast:13 row_mask:0xf bank_mask:0xf
	v_fmac_f32_dpp v228, v204, v33 row_newbcast:14 row_mask:0xf bank_mask:0xf
	v_fmac_f32_dpp v229, v204, v34 row_newbcast:15 row_mask:0xf bank_mask:0xf
	ds_read_b32 v204, v232 offset:7344
	s_waitcnt lgkmcnt(11)
	v_fmac_f32_dpp v40, v205, v35 row_newbcast:0 row_mask:0xf bank_mask:0xf
	v_fmac_f32_dpp v225, v205, v36 row_newbcast:1 row_mask:0xf bank_mask:0xf
	v_fmac_f32_dpp v228, v205, v37 row_newbcast:2 row_mask:0xf bank_mask:0xf
	v_fmac_f32_dpp v229, v205, v38 row_newbcast:3 row_mask:0xf bank_mask:0xf
	v_fmac_f32_dpp v40, v205, v39 row_newbcast:4 row_mask:0xf bank_mask:0xf
	v_add_f32_e32 v40, v40, v225
	v_add_f32_e32 v228, v228, v229
	v_add_f32_e32 v40, v40, v228
	ds_read_b32 v205, v232 offset:7408
	s_waitcnt lgkmcnt(11)
	v_fmac_f32_dpp v41, v206, v18 row_newbcast:0 row_mask:0xf bank_mask:0xf
	v_mul_f32_dpp v222, v206, v19 row_newbcast:1 row_mask:0xf bank_mask:0xf
	v_mul_f32_dpp v223, v206, v20 row_newbcast:2 row_mask:0xf bank_mask:0xf
	v_mul_f32_dpp v224, v206, v21 row_newbcast:3 row_mask:0xf bank_mask:0xf
	v_fmac_f32_dpp v41, v206, v22 row_newbcast:4 row_mask:0xf bank_mask:0xf
	v_fmac_f32_dpp v222, v206, v24 row_newbcast:5 row_mask:0xf bank_mask:0xf
	v_fmac_f32_dpp v223, v206, v25 row_newbcast:6 row_mask:0xf bank_mask:0xf
	v_fmac_f32_dpp v224, v206, v26 row_newbcast:7 row_mask:0xf bank_mask:0xf
	v_fmac_f32_dpp v41, v206, v27 row_newbcast:8 row_mask:0xf bank_mask:0xf
	v_fmac_f32_dpp v222, v206, v28 row_newbcast:9 row_mask:0xf bank_mask:0xf
	v_fmac_f32_dpp v223, v206, v29 row_newbcast:10 row_mask:0xf bank_mask:0xf
	v_fmac_f32_dpp v224, v206, v30 row_newbcast:11 row_mask:0xf bank_mask:0xf
	v_fmac_f32_dpp v41, v206, v31 row_newbcast:12 row_mask:0xf bank_mask:0xf
	v_fmac_f32_dpp v222, v206, v32 row_newbcast:13 row_mask:0xf bank_mask:0xf
	v_fmac_f32_dpp v223, v206, v33 row_newbcast:14 row_mask:0xf bank_mask:0xf
	v_fmac_f32_dpp v224, v206, v34 row_newbcast:15 row_mask:0xf bank_mask:0xf
	ds_read_b32 v206, v232 offset:7616
	s_waitcnt lgkmcnt(11)
	v_fmac_f32_dpp v41, v207, v35 row_newbcast:0 row_mask:0xf bank_mask:0xf
	v_fmac_f32_dpp v222, v207, v36 row_newbcast:1 row_mask:0xf bank_mask:0xf
	v_fmac_f32_dpp v223, v207, v37 row_newbcast:2 row_mask:0xf bank_mask:0xf
	v_fmac_f32_dpp v224, v207, v38 row_newbcast:3 row_mask:0xf bank_mask:0xf
	v_fmac_f32_dpp v41, v207, v39 row_newbcast:4 row_mask:0xf bank_mask:0xf
	v_fmac_f32_dpp v222, v207, v40 row_newbcast:5 row_mask:0xf bank_mask:0xf
	v_add_f32_e32 v41, v41, v222
	v_add_f32_e32 v223, v223, v224
	v_add_f32_e32 v41, v41, v223
	ds_read_b32 v207, v232 offset:7680
	s_waitcnt lgkmcnt(11)
	v_fmac_f32_dpp v42, v208, v18 row_newbcast:0 row_mask:0xf bank_mask:0xf
	v_mul_f32_dpp v225, v208, v19 row_newbcast:1 row_mask:0xf bank_mask:0xf
	v_mul_f32_dpp v228, v208, v20 row_newbcast:2 row_mask:0xf bank_mask:0xf
	v_mul_f32_dpp v229, v208, v21 row_newbcast:3 row_mask:0xf bank_mask:0xf
	v_fmac_f32_dpp v42, v208, v22 row_newbcast:4 row_mask:0xf bank_mask:0xf
	v_fmac_f32_dpp v225, v208, v24 row_newbcast:5 row_mask:0xf bank_mask:0xf
	v_fmac_f32_dpp v228, v208, v25 row_newbcast:6 row_mask:0xf bank_mask:0xf
	v_fmac_f32_dpp v229, v208, v26 row_newbcast:7 row_mask:0xf bank_mask:0xf
	v_fmac_f32_dpp v42, v208, v27 row_newbcast:8 row_mask:0xf bank_mask:0xf
	v_fmac_f32_dpp v225, v208, v28 row_newbcast:9 row_mask:0xf bank_mask:0xf
	v_fmac_f32_dpp v228, v208, v29 row_newbcast:10 row_mask:0xf bank_mask:0xf
	v_fmac_f32_dpp v229, v208, v30 row_newbcast:11 row_mask:0xf bank_mask:0xf
	v_fmac_f32_dpp v42, v208, v31 row_newbcast:12 row_mask:0xf bank_mask:0xf
	v_fmac_f32_dpp v225, v208, v32 row_newbcast:13 row_mask:0xf bank_mask:0xf
	v_fmac_f32_dpp v228, v208, v33 row_newbcast:14 row_mask:0xf bank_mask:0xf
	v_fmac_f32_dpp v229, v208, v34 row_newbcast:15 row_mask:0xf bank_mask:0xf
	ds_read_b32 v208, v232 offset:7888
	s_waitcnt lgkmcnt(11)
	v_fmac_f32_dpp v42, v209, v35 row_newbcast:0 row_mask:0xf bank_mask:0xf
	v_fmac_f32_dpp v225, v209, v36 row_newbcast:1 row_mask:0xf bank_mask:0xf
	v_fmac_f32_dpp v228, v209, v37 row_newbcast:2 row_mask:0xf bank_mask:0xf
	v_fmac_f32_dpp v229, v209, v38 row_newbcast:3 row_mask:0xf bank_mask:0xf
	v_fmac_f32_dpp v42, v209, v39 row_newbcast:4 row_mask:0xf bank_mask:0xf
	v_fmac_f32_dpp v225, v209, v40 row_newbcast:5 row_mask:0xf bank_mask:0xf
	v_fmac_f32_dpp v228, v209, v41 row_newbcast:6 row_mask:0xf bank_mask:0xf
	v_add_f32_e32 v42, v42, v225
	v_add_f32_e32 v228, v228, v229
	v_add_f32_e32 v42, v42, v228
	ds_read_b32 v209, v232 offset:7952
	s_waitcnt lgkmcnt(11)
	v_fmac_f32_dpp v43, v210, v18 row_newbcast:0 row_mask:0xf bank_mask:0xf
	v_mul_f32_dpp v222, v210, v19 row_newbcast:1 row_mask:0xf bank_mask:0xf
	v_mul_f32_dpp v223, v210, v20 row_newbcast:2 row_mask:0xf bank_mask:0xf
	v_mul_f32_dpp v224, v210, v21 row_newbcast:3 row_mask:0xf bank_mask:0xf
	v_fmac_f32_dpp v43, v210, v22 row_newbcast:4 row_mask:0xf bank_mask:0xf
	v_fmac_f32_dpp v222, v210, v24 row_newbcast:5 row_mask:0xf bank_mask:0xf
	v_fmac_f32_dpp v223, v210, v25 row_newbcast:6 row_mask:0xf bank_mask:0xf
	v_fmac_f32_dpp v224, v210, v26 row_newbcast:7 row_mask:0xf bank_mask:0xf
	v_fmac_f32_dpp v43, v210, v27 row_newbcast:8 row_mask:0xf bank_mask:0xf
	v_fmac_f32_dpp v222, v210, v28 row_newbcast:9 row_mask:0xf bank_mask:0xf
	v_fmac_f32_dpp v223, v210, v29 row_newbcast:10 row_mask:0xf bank_mask:0xf
	v_fmac_f32_dpp v224, v210, v30 row_newbcast:11 row_mask:0xf bank_mask:0xf
	v_fmac_f32_dpp v43, v210, v31 row_newbcast:12 row_mask:0xf bank_mask:0xf
	v_fmac_f32_dpp v222, v210, v32 row_newbcast:13 row_mask:0xf bank_mask:0xf
	v_fmac_f32_dpp v223, v210, v33 row_newbcast:14 row_mask:0xf bank_mask:0xf
	v_fmac_f32_dpp v224, v210, v34 row_newbcast:15 row_mask:0xf bank_mask:0xf
	ds_read_b32 v210, v232 offset:8160
	s_waitcnt lgkmcnt(11)
	v_fmac_f32_dpp v43, v211, v35 row_newbcast:0 row_mask:0xf bank_mask:0xf
	v_fmac_f32_dpp v222, v211, v36 row_newbcast:1 row_mask:0xf bank_mask:0xf
	v_fmac_f32_dpp v223, v211, v37 row_newbcast:2 row_mask:0xf bank_mask:0xf
	v_fmac_f32_dpp v224, v211, v38 row_newbcast:3 row_mask:0xf bank_mask:0xf
	v_fmac_f32_dpp v43, v211, v39 row_newbcast:4 row_mask:0xf bank_mask:0xf
	v_fmac_f32_dpp v222, v211, v40 row_newbcast:5 row_mask:0xf bank_mask:0xf
	v_fmac_f32_dpp v223, v211, v41 row_newbcast:6 row_mask:0xf bank_mask:0xf
	v_fmac_f32_dpp v224, v211, v42 row_newbcast:7 row_mask:0xf bank_mask:0xf
	v_add_f32_e32 v43, v43, v222
	v_add_f32_e32 v223, v223, v224
	v_add_f32_e32 v43, v43, v223
	ds_read_b32 v211, v232 offset:8224
	s_waitcnt lgkmcnt(11)
	v_fmac_f32_dpp v44, v212, v18 row_newbcast:0 row_mask:0xf bank_mask:0xf
	v_mul_f32_dpp v225, v212, v19 row_newbcast:1 row_mask:0xf bank_mask:0xf
	v_mul_f32_dpp v228, v212, v20 row_newbcast:2 row_mask:0xf bank_mask:0xf
	v_mul_f32_dpp v229, v212, v21 row_newbcast:3 row_mask:0xf bank_mask:0xf
	v_fmac_f32_dpp v44, v212, v22 row_newbcast:4 row_mask:0xf bank_mask:0xf
	v_fmac_f32_dpp v225, v212, v24 row_newbcast:5 row_mask:0xf bank_mask:0xf
	v_fmac_f32_dpp v228, v212, v25 row_newbcast:6 row_mask:0xf bank_mask:0xf
	v_fmac_f32_dpp v229, v212, v26 row_newbcast:7 row_mask:0xf bank_mask:0xf
	v_fmac_f32_dpp v44, v212, v27 row_newbcast:8 row_mask:0xf bank_mask:0xf
	v_fmac_f32_dpp v225, v212, v28 row_newbcast:9 row_mask:0xf bank_mask:0xf
	v_fmac_f32_dpp v228, v212, v29 row_newbcast:10 row_mask:0xf bank_mask:0xf
	v_fmac_f32_dpp v229, v212, v30 row_newbcast:11 row_mask:0xf bank_mask:0xf
	v_fmac_f32_dpp v44, v212, v31 row_newbcast:12 row_mask:0xf bank_mask:0xf
	v_fmac_f32_dpp v225, v212, v32 row_newbcast:13 row_mask:0xf bank_mask:0xf
	v_fmac_f32_dpp v228, v212, v33 row_newbcast:14 row_mask:0xf bank_mask:0xf
	v_fmac_f32_dpp v229, v212, v34 row_newbcast:15 row_mask:0xf bank_mask:0xf
	ds_read_b32 v212, v232 offset:8432
	s_waitcnt lgkmcnt(11)
	v_fmac_f32_dpp v44, v213, v35 row_newbcast:0 row_mask:0xf bank_mask:0xf
	v_fmac_f32_dpp v225, v213, v36 row_newbcast:1 row_mask:0xf bank_mask:0xf
	v_fmac_f32_dpp v228, v213, v37 row_newbcast:2 row_mask:0xf bank_mask:0xf
	v_fmac_f32_dpp v229, v213, v38 row_newbcast:3 row_mask:0xf bank_mask:0xf
	v_fmac_f32_dpp v44, v213, v39 row_newbcast:4 row_mask:0xf bank_mask:0xf
	v_fmac_f32_dpp v225, v213, v40 row_newbcast:5 row_mask:0xf bank_mask:0xf
	v_fmac_f32_dpp v228, v213, v41 row_newbcast:6 row_mask:0xf bank_mask:0xf
	v_fmac_f32_dpp v229, v213, v42 row_newbcast:7 row_mask:0xf bank_mask:0xf
	v_fmac_f32_dpp v44, v213, v43 row_newbcast:8 row_mask:0xf bank_mask:0xf
	v_add_f32_e32 v44, v44, v225
	v_add_f32_e32 v228, v228, v229
	v_add_f32_e32 v44, v44, v228
	ds_read_b32 v213, v232 offset:8496
	s_waitcnt lgkmcnt(11)
	v_fmac_f32_dpp v45, v214, v18 row_newbcast:0 row_mask:0xf bank_mask:0xf
	v_mul_f32_dpp v222, v214, v19 row_newbcast:1 row_mask:0xf bank_mask:0xf
	v_mul_f32_dpp v223, v214, v20 row_newbcast:2 row_mask:0xf bank_mask:0xf
	v_mul_f32_dpp v224, v214, v21 row_newbcast:3 row_mask:0xf bank_mask:0xf
	v_fmac_f32_dpp v45, v214, v22 row_newbcast:4 row_mask:0xf bank_mask:0xf
	v_fmac_f32_dpp v222, v214, v24 row_newbcast:5 row_mask:0xf bank_mask:0xf
	v_fmac_f32_dpp v223, v214, v25 row_newbcast:6 row_mask:0xf bank_mask:0xf
	v_fmac_f32_dpp v224, v214, v26 row_newbcast:7 row_mask:0xf bank_mask:0xf
	v_fmac_f32_dpp v45, v214, v27 row_newbcast:8 row_mask:0xf bank_mask:0xf
	v_fmac_f32_dpp v222, v214, v28 row_newbcast:9 row_mask:0xf bank_mask:0xf
	v_fmac_f32_dpp v223, v214, v29 row_newbcast:10 row_mask:0xf bank_mask:0xf
	v_fmac_f32_dpp v224, v214, v30 row_newbcast:11 row_mask:0xf bank_mask:0xf
	v_fmac_f32_dpp v45, v214, v31 row_newbcast:12 row_mask:0xf bank_mask:0xf
	v_fmac_f32_dpp v222, v214, v32 row_newbcast:13 row_mask:0xf bank_mask:0xf
	v_fmac_f32_dpp v223, v214, v33 row_newbcast:14 row_mask:0xf bank_mask:0xf
	v_fmac_f32_dpp v224, v214, v34 row_newbcast:15 row_mask:0xf bank_mask:0xf
	ds_read_b32 v214, v232 offset:8704
	s_waitcnt lgkmcnt(11)
	v_fmac_f32_dpp v45, v215, v35 row_newbcast:0 row_mask:0xf bank_mask:0xf
	v_fmac_f32_dpp v222, v215, v36 row_newbcast:1 row_mask:0xf bank_mask:0xf
	v_fmac_f32_dpp v223, v215, v37 row_newbcast:2 row_mask:0xf bank_mask:0xf
	v_fmac_f32_dpp v224, v215, v38 row_newbcast:3 row_mask:0xf bank_mask:0xf
	v_fmac_f32_dpp v45, v215, v39 row_newbcast:4 row_mask:0xf bank_mask:0xf
	v_fmac_f32_dpp v222, v215, v40 row_newbcast:5 row_mask:0xf bank_mask:0xf
	v_fmac_f32_dpp v223, v215, v41 row_newbcast:6 row_mask:0xf bank_mask:0xf
	v_fmac_f32_dpp v224, v215, v42 row_newbcast:7 row_mask:0xf bank_mask:0xf
	v_fmac_f32_dpp v45, v215, v43 row_newbcast:8 row_mask:0xf bank_mask:0xf
	v_fmac_f32_dpp v222, v215, v44 row_newbcast:9 row_mask:0xf bank_mask:0xf
	v_add_f32_e32 v45, v45, v222
	v_add_f32_e32 v223, v223, v224
	v_add_f32_e32 v45, v45, v223
	ds_read_b32 v215, v232 offset:8768
	s_waitcnt lgkmcnt(11)
	v_fmac_f32_dpp v46, v204, v18 row_newbcast:0 row_mask:0xf bank_mask:0xf
	v_mul_f32_dpp v225, v204, v19 row_newbcast:1 row_mask:0xf bank_mask:0xf
	v_mul_f32_dpp v228, v204, v20 row_newbcast:2 row_mask:0xf bank_mask:0xf
	v_mul_f32_dpp v229, v204, v21 row_newbcast:3 row_mask:0xf bank_mask:0xf
	v_fmac_f32_dpp v46, v204, v22 row_newbcast:4 row_mask:0xf bank_mask:0xf
	v_fmac_f32_dpp v225, v204, v24 row_newbcast:5 row_mask:0xf bank_mask:0xf
	v_fmac_f32_dpp v228, v204, v25 row_newbcast:6 row_mask:0xf bank_mask:0xf
	v_fmac_f32_dpp v229, v204, v26 row_newbcast:7 row_mask:0xf bank_mask:0xf
	v_fmac_f32_dpp v46, v204, v27 row_newbcast:8 row_mask:0xf bank_mask:0xf
	v_fmac_f32_dpp v225, v204, v28 row_newbcast:9 row_mask:0xf bank_mask:0xf
	v_fmac_f32_dpp v228, v204, v29 row_newbcast:10 row_mask:0xf bank_mask:0xf
	v_fmac_f32_dpp v229, v204, v30 row_newbcast:11 row_mask:0xf bank_mask:0xf
	v_fmac_f32_dpp v46, v204, v31 row_newbcast:12 row_mask:0xf bank_mask:0xf
	v_fmac_f32_dpp v225, v204, v32 row_newbcast:13 row_mask:0xf bank_mask:0xf
	v_fmac_f32_dpp v228, v204, v33 row_newbcast:14 row_mask:0xf bank_mask:0xf
	v_fmac_f32_dpp v229, v204, v34 row_newbcast:15 row_mask:0xf bank_mask:0xf
	ds_read_b32 v204, v232 offset:8976
	s_waitcnt lgkmcnt(11)
	v_fmac_f32_dpp v46, v205, v35 row_newbcast:0 row_mask:0xf bank_mask:0xf
	v_fmac_f32_dpp v225, v205, v36 row_newbcast:1 row_mask:0xf bank_mask:0xf
	v_fmac_f32_dpp v228, v205, v37 row_newbcast:2 row_mask:0xf bank_mask:0xf
	v_fmac_f32_dpp v229, v205, v38 row_newbcast:3 row_mask:0xf bank_mask:0xf
	v_fmac_f32_dpp v46, v205, v39 row_newbcast:4 row_mask:0xf bank_mask:0xf
	v_fmac_f32_dpp v225, v205, v40 row_newbcast:5 row_mask:0xf bank_mask:0xf
	v_fmac_f32_dpp v228, v205, v41 row_newbcast:6 row_mask:0xf bank_mask:0xf
	v_fmac_f32_dpp v229, v205, v42 row_newbcast:7 row_mask:0xf bank_mask:0xf
	v_fmac_f32_dpp v46, v205, v43 row_newbcast:8 row_mask:0xf bank_mask:0xf
	v_fmac_f32_dpp v225, v205, v44 row_newbcast:9 row_mask:0xf bank_mask:0xf
	v_fmac_f32_dpp v228, v205, v45 row_newbcast:10 row_mask:0xf bank_mask:0xf
	v_add_f32_e32 v46, v46, v225
	v_add_f32_e32 v228, v228, v229
	v_add_f32_e32 v46, v46, v228
	ds_read_b32 v205, v232 offset:9040
	s_waitcnt lgkmcnt(11)
	v_fmac_f32_dpp v47, v206, v18 row_newbcast:0 row_mask:0xf bank_mask:0xf
	v_mul_f32_dpp v222, v206, v19 row_newbcast:1 row_mask:0xf bank_mask:0xf
	v_mul_f32_dpp v223, v206, v20 row_newbcast:2 row_mask:0xf bank_mask:0xf
	v_mul_f32_dpp v224, v206, v21 row_newbcast:3 row_mask:0xf bank_mask:0xf
	v_fmac_f32_dpp v47, v206, v22 row_newbcast:4 row_mask:0xf bank_mask:0xf
	v_fmac_f32_dpp v222, v206, v24 row_newbcast:5 row_mask:0xf bank_mask:0xf
	v_fmac_f32_dpp v223, v206, v25 row_newbcast:6 row_mask:0xf bank_mask:0xf
	v_fmac_f32_dpp v224, v206, v26 row_newbcast:7 row_mask:0xf bank_mask:0xf
	v_fmac_f32_dpp v47, v206, v27 row_newbcast:8 row_mask:0xf bank_mask:0xf
	v_fmac_f32_dpp v222, v206, v28 row_newbcast:9 row_mask:0xf bank_mask:0xf
	v_fmac_f32_dpp v223, v206, v29 row_newbcast:10 row_mask:0xf bank_mask:0xf
	v_fmac_f32_dpp v224, v206, v30 row_newbcast:11 row_mask:0xf bank_mask:0xf
	v_fmac_f32_dpp v47, v206, v31 row_newbcast:12 row_mask:0xf bank_mask:0xf
	v_fmac_f32_dpp v222, v206, v32 row_newbcast:13 row_mask:0xf bank_mask:0xf
	v_fmac_f32_dpp v223, v206, v33 row_newbcast:14 row_mask:0xf bank_mask:0xf
	v_fmac_f32_dpp v224, v206, v34 row_newbcast:15 row_mask:0xf bank_mask:0xf
	ds_read_b32 v206, v232 offset:9104
	s_waitcnt lgkmcnt(11)
	v_fmac_f32_dpp v47, v207, v35 row_newbcast:0 row_mask:0xf bank_mask:0xf
	v_fmac_f32_dpp v222, v207, v36 row_newbcast:1 row_mask:0xf bank_mask:0xf
	v_fmac_f32_dpp v223, v207, v37 row_newbcast:2 row_mask:0xf bank_mask:0xf
	v_fmac_f32_dpp v224, v207, v38 row_newbcast:3 row_mask:0xf bank_mask:0xf
	v_fmac_f32_dpp v47, v207, v39 row_newbcast:4 row_mask:0xf bank_mask:0xf
	v_fmac_f32_dpp v222, v207, v40 row_newbcast:5 row_mask:0xf bank_mask:0xf
	v_fmac_f32_dpp v223, v207, v41 row_newbcast:6 row_mask:0xf bank_mask:0xf
	v_fmac_f32_dpp v224, v207, v42 row_newbcast:7 row_mask:0xf bank_mask:0xf
	v_fmac_f32_dpp v47, v207, v43 row_newbcast:8 row_mask:0xf bank_mask:0xf
	v_fmac_f32_dpp v222, v207, v44 row_newbcast:9 row_mask:0xf bank_mask:0xf
	v_fmac_f32_dpp v223, v207, v45 row_newbcast:10 row_mask:0xf bank_mask:0xf
	v_fmac_f32_dpp v224, v207, v46 row_newbcast:11 row_mask:0xf bank_mask:0xf
	v_add_f32_e32 v47, v47, v222
	v_add_f32_e32 v223, v223, v224
	v_add_f32_e32 v47, v47, v223
	ds_read_b32 v207, v232 offset:9248
	s_waitcnt lgkmcnt(11)
	v_fmac_f32_dpp v48, v208, v18 row_newbcast:0 row_mask:0xf bank_mask:0xf
	v_mul_f32_dpp v225, v208, v19 row_newbcast:1 row_mask:0xf bank_mask:0xf
	v_mul_f32_dpp v228, v208, v20 row_newbcast:2 row_mask:0xf bank_mask:0xf
	v_mul_f32_dpp v229, v208, v21 row_newbcast:3 row_mask:0xf bank_mask:0xf
	v_fmac_f32_dpp v48, v208, v22 row_newbcast:4 row_mask:0xf bank_mask:0xf
	v_fmac_f32_dpp v225, v208, v24 row_newbcast:5 row_mask:0xf bank_mask:0xf
	v_fmac_f32_dpp v228, v208, v25 row_newbcast:6 row_mask:0xf bank_mask:0xf
	v_fmac_f32_dpp v229, v208, v26 row_newbcast:7 row_mask:0xf bank_mask:0xf
	v_fmac_f32_dpp v48, v208, v27 row_newbcast:8 row_mask:0xf bank_mask:0xf
	v_fmac_f32_dpp v225, v208, v28 row_newbcast:9 row_mask:0xf bank_mask:0xf
	v_fmac_f32_dpp v228, v208, v29 row_newbcast:10 row_mask:0xf bank_mask:0xf
	v_fmac_f32_dpp v229, v208, v30 row_newbcast:11 row_mask:0xf bank_mask:0xf
	v_fmac_f32_dpp v48, v208, v31 row_newbcast:12 row_mask:0xf bank_mask:0xf
	v_fmac_f32_dpp v225, v208, v32 row_newbcast:13 row_mask:0xf bank_mask:0xf
	v_fmac_f32_dpp v228, v208, v33 row_newbcast:14 row_mask:0xf bank_mask:0xf
	v_fmac_f32_dpp v229, v208, v34 row_newbcast:15 row_mask:0xf bank_mask:0xf
	ds_read_b32 v208, v232 offset:9312
	s_waitcnt lgkmcnt(11)
	v_fmac_f32_dpp v48, v209, v35 row_newbcast:0 row_mask:0xf bank_mask:0xf
	v_fmac_f32_dpp v225, v209, v36 row_newbcast:1 row_mask:0xf bank_mask:0xf
	v_fmac_f32_dpp v228, v209, v37 row_newbcast:2 row_mask:0xf bank_mask:0xf
	v_fmac_f32_dpp v229, v209, v38 row_newbcast:3 row_mask:0xf bank_mask:0xf
	v_fmac_f32_dpp v48, v209, v39 row_newbcast:4 row_mask:0xf bank_mask:0xf
	v_fmac_f32_dpp v225, v209, v40 row_newbcast:5 row_mask:0xf bank_mask:0xf
	v_fmac_f32_dpp v228, v209, v41 row_newbcast:6 row_mask:0xf bank_mask:0xf
	v_fmac_f32_dpp v229, v209, v42 row_newbcast:7 row_mask:0xf bank_mask:0xf
	v_fmac_f32_dpp v48, v209, v43 row_newbcast:8 row_mask:0xf bank_mask:0xf
	v_fmac_f32_dpp v225, v209, v44 row_newbcast:9 row_mask:0xf bank_mask:0xf
	v_fmac_f32_dpp v228, v209, v45 row_newbcast:10 row_mask:0xf bank_mask:0xf
	v_fmac_f32_dpp v229, v209, v46 row_newbcast:11 row_mask:0xf bank_mask:0xf
	v_fmac_f32_dpp v48, v209, v47 row_newbcast:12 row_mask:0xf bank_mask:0xf
	v_add_f32_e32 v48, v48, v225
	v_add_f32_e32 v228, v228, v229
	v_add_f32_e32 v48, v48, v228
	ds_read_b32 v209, v232 offset:9376
	s_waitcnt lgkmcnt(11)
	v_fmac_f32_dpp v49, v210, v18 row_newbcast:0 row_mask:0xf bank_mask:0xf
	v_mul_f32_dpp v222, v210, v19 row_newbcast:1 row_mask:0xf bank_mask:0xf
	v_mul_f32_dpp v223, v210, v20 row_newbcast:2 row_mask:0xf bank_mask:0xf
	v_mul_f32_dpp v224, v210, v21 row_newbcast:3 row_mask:0xf bank_mask:0xf
	v_fmac_f32_dpp v49, v210, v22 row_newbcast:4 row_mask:0xf bank_mask:0xf
	v_fmac_f32_dpp v222, v210, v24 row_newbcast:5 row_mask:0xf bank_mask:0xf
	v_fmac_f32_dpp v223, v210, v25 row_newbcast:6 row_mask:0xf bank_mask:0xf
	v_fmac_f32_dpp v224, v210, v26 row_newbcast:7 row_mask:0xf bank_mask:0xf
	v_fmac_f32_dpp v49, v210, v27 row_newbcast:8 row_mask:0xf bank_mask:0xf
	v_fmac_f32_dpp v222, v210, v28 row_newbcast:9 row_mask:0xf bank_mask:0xf
	v_fmac_f32_dpp v223, v210, v29 row_newbcast:10 row_mask:0xf bank_mask:0xf
	v_fmac_f32_dpp v224, v210, v30 row_newbcast:11 row_mask:0xf bank_mask:0xf
	v_fmac_f32_dpp v49, v210, v31 row_newbcast:12 row_mask:0xf bank_mask:0xf
	v_fmac_f32_dpp v222, v210, v32 row_newbcast:13 row_mask:0xf bank_mask:0xf
	v_fmac_f32_dpp v223, v210, v33 row_newbcast:14 row_mask:0xf bank_mask:0xf
	v_fmac_f32_dpp v224, v210, v34 row_newbcast:15 row_mask:0xf bank_mask:0xf
	ds_read_b32 v210, v232 offset:9520
	s_waitcnt lgkmcnt(11)
	v_fmac_f32_dpp v49, v211, v35 row_newbcast:0 row_mask:0xf bank_mask:0xf
	v_fmac_f32_dpp v222, v211, v36 row_newbcast:1 row_mask:0xf bank_mask:0xf
	v_fmac_f32_dpp v223, v211, v37 row_newbcast:2 row_mask:0xf bank_mask:0xf
	v_fmac_f32_dpp v224, v211, v38 row_newbcast:3 row_mask:0xf bank_mask:0xf
	v_fmac_f32_dpp v49, v211, v39 row_newbcast:4 row_mask:0xf bank_mask:0xf
	v_fmac_f32_dpp v222, v211, v40 row_newbcast:5 row_mask:0xf bank_mask:0xf
	v_fmac_f32_dpp v223, v211, v41 row_newbcast:6 row_mask:0xf bank_mask:0xf
	v_fmac_f32_dpp v224, v211, v42 row_newbcast:7 row_mask:0xf bank_mask:0xf
	v_fmac_f32_dpp v49, v211, v43 row_newbcast:8 row_mask:0xf bank_mask:0xf
	v_fmac_f32_dpp v222, v211, v44 row_newbcast:9 row_mask:0xf bank_mask:0xf
	v_fmac_f32_dpp v223, v211, v45 row_newbcast:10 row_mask:0xf bank_mask:0xf
	v_fmac_f32_dpp v224, v211, v46 row_newbcast:11 row_mask:0xf bank_mask:0xf
	v_fmac_f32_dpp v49, v211, v47 row_newbcast:12 row_mask:0xf bank_mask:0xf
	v_fmac_f32_dpp v222, v211, v48 row_newbcast:13 row_mask:0xf bank_mask:0xf
	v_add_f32_e32 v49, v49, v222
	v_add_f32_e32 v223, v223, v224
	v_add_f32_e32 v49, v49, v223
	ds_read_b32 v211, v232 offset:9584
	s_waitcnt lgkmcnt(11)
	v_fmac_f32_dpp v91, v212, v18 row_newbcast:0 row_mask:0xf bank_mask:0xf
	v_mul_f32_dpp v225, v212, v19 row_newbcast:1 row_mask:0xf bank_mask:0xf
	v_mul_f32_dpp v228, v212, v20 row_newbcast:2 row_mask:0xf bank_mask:0xf
	v_mul_f32_dpp v229, v212, v21 row_newbcast:3 row_mask:0xf bank_mask:0xf
	v_fmac_f32_dpp v91, v212, v22 row_newbcast:4 row_mask:0xf bank_mask:0xf
	v_fmac_f32_dpp v225, v212, v24 row_newbcast:5 row_mask:0xf bank_mask:0xf
	v_fmac_f32_dpp v228, v212, v25 row_newbcast:6 row_mask:0xf bank_mask:0xf
	v_fmac_f32_dpp v229, v212, v26 row_newbcast:7 row_mask:0xf bank_mask:0xf
	v_fmac_f32_dpp v91, v212, v27 row_newbcast:8 row_mask:0xf bank_mask:0xf
	v_fmac_f32_dpp v225, v212, v28 row_newbcast:9 row_mask:0xf bank_mask:0xf
	v_fmac_f32_dpp v228, v212, v29 row_newbcast:10 row_mask:0xf bank_mask:0xf
	v_fmac_f32_dpp v229, v212, v30 row_newbcast:11 row_mask:0xf bank_mask:0xf
	v_fmac_f32_dpp v91, v212, v31 row_newbcast:12 row_mask:0xf bank_mask:0xf
	v_fmac_f32_dpp v225, v212, v32 row_newbcast:13 row_mask:0xf bank_mask:0xf
	v_fmac_f32_dpp v228, v212, v33 row_newbcast:14 row_mask:0xf bank_mask:0xf
	v_fmac_f32_dpp v229, v212, v34 row_newbcast:15 row_mask:0xf bank_mask:0xf
	ds_read_b32 v212, v232 offset:9648
	s_waitcnt lgkmcnt(11)
	v_fmac_f32_dpp v91, v213, v35 row_newbcast:0 row_mask:0xf bank_mask:0xf
	v_fmac_f32_dpp v225, v213, v36 row_newbcast:1 row_mask:0xf bank_mask:0xf
	v_fmac_f32_dpp v228, v213, v37 row_newbcast:2 row_mask:0xf bank_mask:0xf
	v_fmac_f32_dpp v229, v213, v38 row_newbcast:3 row_mask:0xf bank_mask:0xf
	v_fmac_f32_dpp v91, v213, v39 row_newbcast:4 row_mask:0xf bank_mask:0xf
	v_fmac_f32_dpp v225, v213, v40 row_newbcast:5 row_mask:0xf bank_mask:0xf
	v_fmac_f32_dpp v228, v213, v41 row_newbcast:6 row_mask:0xf bank_mask:0xf
	v_fmac_f32_dpp v229, v213, v42 row_newbcast:7 row_mask:0xf bank_mask:0xf
	v_fmac_f32_dpp v91, v213, v43 row_newbcast:8 row_mask:0xf bank_mask:0xf
	v_fmac_f32_dpp v225, v213, v44 row_newbcast:9 row_mask:0xf bank_mask:0xf
	v_fmac_f32_dpp v228, v213, v45 row_newbcast:10 row_mask:0xf bank_mask:0xf
	v_fmac_f32_dpp v229, v213, v46 row_newbcast:11 row_mask:0xf bank_mask:0xf
	v_fmac_f32_dpp v91, v213, v47 row_newbcast:12 row_mask:0xf bank_mask:0xf
	v_fmac_f32_dpp v225, v213, v48 row_newbcast:13 row_mask:0xf bank_mask:0xf
	v_fmac_f32_dpp v228, v213, v49 row_newbcast:14 row_mask:0xf bank_mask:0xf
	v_add_f32_e32 v91, v91, v225
	v_add_f32_e32 v228, v228, v229
	v_add_f32_e32 v91, v91, v228
	ds_read_b32 v213, v232 offset:9792
	s_waitcnt lgkmcnt(11)
	v_fmac_f32_dpp v92, v214, v18 row_newbcast:0 row_mask:0xf bank_mask:0xf
	v_mul_f32_dpp v222, v214, v19 row_newbcast:1 row_mask:0xf bank_mask:0xf
	v_mul_f32_dpp v223, v214, v20 row_newbcast:2 row_mask:0xf bank_mask:0xf
	v_mul_f32_dpp v224, v214, v21 row_newbcast:3 row_mask:0xf bank_mask:0xf
	v_fmac_f32_dpp v92, v214, v22 row_newbcast:4 row_mask:0xf bank_mask:0xf
	v_fmac_f32_dpp v222, v214, v24 row_newbcast:5 row_mask:0xf bank_mask:0xf
	v_fmac_f32_dpp v223, v214, v25 row_newbcast:6 row_mask:0xf bank_mask:0xf
	v_fmac_f32_dpp v224, v214, v26 row_newbcast:7 row_mask:0xf bank_mask:0xf
	v_fmac_f32_dpp v92, v214, v27 row_newbcast:8 row_mask:0xf bank_mask:0xf
	v_fmac_f32_dpp v222, v214, v28 row_newbcast:9 row_mask:0xf bank_mask:0xf
	v_fmac_f32_dpp v223, v214, v29 row_newbcast:10 row_mask:0xf bank_mask:0xf
	v_fmac_f32_dpp v224, v214, v30 row_newbcast:11 row_mask:0xf bank_mask:0xf
	v_fmac_f32_dpp v92, v214, v31 row_newbcast:12 row_mask:0xf bank_mask:0xf
	v_fmac_f32_dpp v222, v214, v32 row_newbcast:13 row_mask:0xf bank_mask:0xf
	v_fmac_f32_dpp v223, v214, v33 row_newbcast:14 row_mask:0xf bank_mask:0xf
	v_fmac_f32_dpp v224, v214, v34 row_newbcast:15 row_mask:0xf bank_mask:0xf
	ds_read_b32 v214, v232 offset:9856
	s_waitcnt lgkmcnt(11)
	v_fmac_f32_dpp v92, v215, v35 row_newbcast:0 row_mask:0xf bank_mask:0xf
	v_fmac_f32_dpp v222, v215, v36 row_newbcast:1 row_mask:0xf bank_mask:0xf
	v_fmac_f32_dpp v223, v215, v37 row_newbcast:2 row_mask:0xf bank_mask:0xf
	v_fmac_f32_dpp v224, v215, v38 row_newbcast:3 row_mask:0xf bank_mask:0xf
	v_fmac_f32_dpp v92, v215, v39 row_newbcast:4 row_mask:0xf bank_mask:0xf
	v_fmac_f32_dpp v222, v215, v40 row_newbcast:5 row_mask:0xf bank_mask:0xf
	v_fmac_f32_dpp v223, v215, v41 row_newbcast:6 row_mask:0xf bank_mask:0xf
	v_fmac_f32_dpp v224, v215, v42 row_newbcast:7 row_mask:0xf bank_mask:0xf
	v_fmac_f32_dpp v92, v215, v43 row_newbcast:8 row_mask:0xf bank_mask:0xf
	v_fmac_f32_dpp v222, v215, v44 row_newbcast:9 row_mask:0xf bank_mask:0xf
	v_fmac_f32_dpp v223, v215, v45 row_newbcast:10 row_mask:0xf bank_mask:0xf
	v_fmac_f32_dpp v224, v215, v46 row_newbcast:11 row_mask:0xf bank_mask:0xf
	v_fmac_f32_dpp v92, v215, v47 row_newbcast:12 row_mask:0xf bank_mask:0xf
	v_fmac_f32_dpp v222, v215, v48 row_newbcast:13 row_mask:0xf bank_mask:0xf
	v_fmac_f32_dpp v223, v215, v49 row_newbcast:14 row_mask:0xf bank_mask:0xf
	v_fmac_f32_dpp v224, v215, v91 row_newbcast:15 row_mask:0xf bank_mask:0xf
	v_add_f32_e32 v92, v92, v222
	v_add_f32_e32 v223, v223, v224
	v_add_f32_e32 v92, v92, v223
	ds_read_b32 v215, v232 offset:9920
	s_waitcnt lgkmcnt(11)
	v_fmac_f32_dpp v93, v204, v18 row_newbcast:0 row_mask:0xf bank_mask:0xf
	v_mul_f32_dpp v225, v204, v19 row_newbcast:1 row_mask:0xf bank_mask:0xf
	v_mul_f32_dpp v228, v204, v20 row_newbcast:2 row_mask:0xf bank_mask:0xf
	v_mul_f32_dpp v229, v204, v21 row_newbcast:3 row_mask:0xf bank_mask:0xf
	v_fmac_f32_dpp v93, v204, v22 row_newbcast:4 row_mask:0xf bank_mask:0xf
	v_fmac_f32_dpp v225, v204, v24 row_newbcast:5 row_mask:0xf bank_mask:0xf
	v_fmac_f32_dpp v228, v204, v25 row_newbcast:6 row_mask:0xf bank_mask:0xf
	v_fmac_f32_dpp v229, v204, v26 row_newbcast:7 row_mask:0xf bank_mask:0xf
	v_fmac_f32_dpp v93, v204, v27 row_newbcast:8 row_mask:0xf bank_mask:0xf
	v_fmac_f32_dpp v225, v204, v28 row_newbcast:9 row_mask:0xf bank_mask:0xf
	v_fmac_f32_dpp v228, v204, v29 row_newbcast:10 row_mask:0xf bank_mask:0xf
	v_fmac_f32_dpp v229, v204, v30 row_newbcast:11 row_mask:0xf bank_mask:0xf
	v_fmac_f32_dpp v93, v204, v31 row_newbcast:12 row_mask:0xf bank_mask:0xf
	v_fmac_f32_dpp v225, v204, v32 row_newbcast:13 row_mask:0xf bank_mask:0xf
	v_fmac_f32_dpp v228, v204, v33 row_newbcast:14 row_mask:0xf bank_mask:0xf
	v_fmac_f32_dpp v229, v204, v34 row_newbcast:15 row_mask:0xf bank_mask:0xf
	ds_read_b32 v204, v232 offset:10064
	s_waitcnt lgkmcnt(11)
	v_fmac_f32_dpp v93, v205, v35 row_newbcast:0 row_mask:0xf bank_mask:0xf
	v_fmac_f32_dpp v225, v205, v36 row_newbcast:1 row_mask:0xf bank_mask:0xf
	v_fmac_f32_dpp v228, v205, v37 row_newbcast:2 row_mask:0xf bank_mask:0xf
	v_fmac_f32_dpp v229, v205, v38 row_newbcast:3 row_mask:0xf bank_mask:0xf
	v_fmac_f32_dpp v93, v205, v39 row_newbcast:4 row_mask:0xf bank_mask:0xf
	v_fmac_f32_dpp v225, v205, v40 row_newbcast:5 row_mask:0xf bank_mask:0xf
	v_fmac_f32_dpp v228, v205, v41 row_newbcast:6 row_mask:0xf bank_mask:0xf
	v_fmac_f32_dpp v229, v205, v42 row_newbcast:7 row_mask:0xf bank_mask:0xf
	v_fmac_f32_dpp v93, v205, v43 row_newbcast:8 row_mask:0xf bank_mask:0xf
	v_fmac_f32_dpp v225, v205, v44 row_newbcast:9 row_mask:0xf bank_mask:0xf
	v_fmac_f32_dpp v228, v205, v45 row_newbcast:10 row_mask:0xf bank_mask:0xf
	v_fmac_f32_dpp v229, v205, v46 row_newbcast:11 row_mask:0xf bank_mask:0xf
	v_fmac_f32_dpp v93, v205, v47 row_newbcast:12 row_mask:0xf bank_mask:0xf
	v_fmac_f32_dpp v225, v205, v48 row_newbcast:13 row_mask:0xf bank_mask:0xf
	v_fmac_f32_dpp v228, v205, v49 row_newbcast:14 row_mask:0xf bank_mask:0xf
	v_fmac_f32_dpp v229, v205, v91 row_newbcast:15 row_mask:0xf bank_mask:0xf
	ds_read_b32 v205, v232 offset:10128
	s_waitcnt lgkmcnt(11)
	v_fmac_f32_dpp v93, v206, v92 row_newbcast:0 row_mask:0xf bank_mask:0xf
	v_add_f32_e32 v93, v93, v225
	v_add_f32_e32 v228, v228, v229
	v_add_f32_e32 v93, v93, v228
	ds_read_b32 v206, v232 offset:10192
	s_waitcnt lgkmcnt(11)
	v_fmac_f32_dpp v94, v207, v18 row_newbcast:0 row_mask:0xf bank_mask:0xf
	v_mul_f32_dpp v222, v207, v19 row_newbcast:1 row_mask:0xf bank_mask:0xf
	v_mul_f32_dpp v223, v207, v20 row_newbcast:2 row_mask:0xf bank_mask:0xf
	v_mul_f32_dpp v224, v207, v21 row_newbcast:3 row_mask:0xf bank_mask:0xf
	v_fmac_f32_dpp v94, v207, v22 row_newbcast:4 row_mask:0xf bank_mask:0xf
	v_fmac_f32_dpp v222, v207, v24 row_newbcast:5 row_mask:0xf bank_mask:0xf
	v_fmac_f32_dpp v223, v207, v25 row_newbcast:6 row_mask:0xf bank_mask:0xf
	v_fmac_f32_dpp v224, v207, v26 row_newbcast:7 row_mask:0xf bank_mask:0xf
	v_fmac_f32_dpp v94, v207, v27 row_newbcast:8 row_mask:0xf bank_mask:0xf
	v_fmac_f32_dpp v222, v207, v28 row_newbcast:9 row_mask:0xf bank_mask:0xf
	v_fmac_f32_dpp v223, v207, v29 row_newbcast:10 row_mask:0xf bank_mask:0xf
	v_fmac_f32_dpp v224, v207, v30 row_newbcast:11 row_mask:0xf bank_mask:0xf
	v_fmac_f32_dpp v94, v207, v31 row_newbcast:12 row_mask:0xf bank_mask:0xf
	v_fmac_f32_dpp v222, v207, v32 row_newbcast:13 row_mask:0xf bank_mask:0xf
	v_fmac_f32_dpp v223, v207, v33 row_newbcast:14 row_mask:0xf bank_mask:0xf
	v_fmac_f32_dpp v224, v207, v34 row_newbcast:15 row_mask:0xf bank_mask:0xf
	ds_read_b32 v207, v232 offset:10336
	s_waitcnt lgkmcnt(11)
	v_fmac_f32_dpp v94, v208, v35 row_newbcast:0 row_mask:0xf bank_mask:0xf
	v_fmac_f32_dpp v222, v208, v36 row_newbcast:1 row_mask:0xf bank_mask:0xf
	v_fmac_f32_dpp v223, v208, v37 row_newbcast:2 row_mask:0xf bank_mask:0xf
	v_fmac_f32_dpp v224, v208, v38 row_newbcast:3 row_mask:0xf bank_mask:0xf
	v_fmac_f32_dpp v94, v208, v39 row_newbcast:4 row_mask:0xf bank_mask:0xf
	v_fmac_f32_dpp v222, v208, v40 row_newbcast:5 row_mask:0xf bank_mask:0xf
	v_fmac_f32_dpp v223, v208, v41 row_newbcast:6 row_mask:0xf bank_mask:0xf
	v_fmac_f32_dpp v224, v208, v42 row_newbcast:7 row_mask:0xf bank_mask:0xf
	v_fmac_f32_dpp v94, v208, v43 row_newbcast:8 row_mask:0xf bank_mask:0xf
	v_fmac_f32_dpp v222, v208, v44 row_newbcast:9 row_mask:0xf bank_mask:0xf
	v_fmac_f32_dpp v223, v208, v45 row_newbcast:10 row_mask:0xf bank_mask:0xf
	v_fmac_f32_dpp v224, v208, v46 row_newbcast:11 row_mask:0xf bank_mask:0xf
	v_fmac_f32_dpp v94, v208, v47 row_newbcast:12 row_mask:0xf bank_mask:0xf
	v_fmac_f32_dpp v222, v208, v48 row_newbcast:13 row_mask:0xf bank_mask:0xf
	v_fmac_f32_dpp v223, v208, v49 row_newbcast:14 row_mask:0xf bank_mask:0xf
	v_fmac_f32_dpp v224, v208, v91 row_newbcast:15 row_mask:0xf bank_mask:0xf
	ds_read_b32 v208, v232 offset:10400
	s_waitcnt lgkmcnt(11)
	v_fmac_f32_dpp v94, v209, v92 row_newbcast:0 row_mask:0xf bank_mask:0xf
	v_fmac_f32_dpp v222, v209, v93 row_newbcast:1 row_mask:0xf bank_mask:0xf
	v_add_f32_e32 v94, v94, v222
	v_add_f32_e32 v223, v223, v224
	v_add_f32_e32 v94, v94, v223
	ds_read_b32 v209, v232 offset:10464
	s_waitcnt lgkmcnt(11)
	v_fmac_f32_dpp v95, v210, v18 row_newbcast:0 row_mask:0xf bank_mask:0xf
	v_mul_f32_dpp v225, v210, v19 row_newbcast:1 row_mask:0xf bank_mask:0xf
	v_mul_f32_dpp v228, v210, v20 row_newbcast:2 row_mask:0xf bank_mask:0xf
	v_mul_f32_dpp v229, v210, v21 row_newbcast:3 row_mask:0xf bank_mask:0xf
	v_fmac_f32_dpp v95, v210, v22 row_newbcast:4 row_mask:0xf bank_mask:0xf
	v_fmac_f32_dpp v225, v210, v24 row_newbcast:5 row_mask:0xf bank_mask:0xf
	v_fmac_f32_dpp v228, v210, v25 row_newbcast:6 row_mask:0xf bank_mask:0xf
	v_fmac_f32_dpp v229, v210, v26 row_newbcast:7 row_mask:0xf bank_mask:0xf
	v_fmac_f32_dpp v95, v210, v27 row_newbcast:8 row_mask:0xf bank_mask:0xf
	v_fmac_f32_dpp v225, v210, v28 row_newbcast:9 row_mask:0xf bank_mask:0xf
	v_fmac_f32_dpp v228, v210, v29 row_newbcast:10 row_mask:0xf bank_mask:0xf
	v_fmac_f32_dpp v229, v210, v30 row_newbcast:11 row_mask:0xf bank_mask:0xf
	v_fmac_f32_dpp v95, v210, v31 row_newbcast:12 row_mask:0xf bank_mask:0xf
	v_fmac_f32_dpp v225, v210, v32 row_newbcast:13 row_mask:0xf bank_mask:0xf
	v_fmac_f32_dpp v228, v210, v33 row_newbcast:14 row_mask:0xf bank_mask:0xf
	v_fmac_f32_dpp v229, v210, v34 row_newbcast:15 row_mask:0xf bank_mask:0xf
	ds_read_b32 v210, v232 offset:10608
	s_waitcnt lgkmcnt(11)
	v_fmac_f32_dpp v95, v211, v35 row_newbcast:0 row_mask:0xf bank_mask:0xf
	v_fmac_f32_dpp v225, v211, v36 row_newbcast:1 row_mask:0xf bank_mask:0xf
	v_fmac_f32_dpp v228, v211, v37 row_newbcast:2 row_mask:0xf bank_mask:0xf
	v_fmac_f32_dpp v229, v211, v38 row_newbcast:3 row_mask:0xf bank_mask:0xf
	v_fmac_f32_dpp v95, v211, v39 row_newbcast:4 row_mask:0xf bank_mask:0xf
	v_fmac_f32_dpp v225, v211, v40 row_newbcast:5 row_mask:0xf bank_mask:0xf
	v_fmac_f32_dpp v228, v211, v41 row_newbcast:6 row_mask:0xf bank_mask:0xf
	v_fmac_f32_dpp v229, v211, v42 row_newbcast:7 row_mask:0xf bank_mask:0xf
	v_fmac_f32_dpp v95, v211, v43 row_newbcast:8 row_mask:0xf bank_mask:0xf
	v_fmac_f32_dpp v225, v211, v44 row_newbcast:9 row_mask:0xf bank_mask:0xf
	v_fmac_f32_dpp v228, v211, v45 row_newbcast:10 row_mask:0xf bank_mask:0xf
	v_fmac_f32_dpp v229, v211, v46 row_newbcast:11 row_mask:0xf bank_mask:0xf
	v_fmac_f32_dpp v95, v211, v47 row_newbcast:12 row_mask:0xf bank_mask:0xf
	v_fmac_f32_dpp v225, v211, v48 row_newbcast:13 row_mask:0xf bank_mask:0xf
	v_fmac_f32_dpp v228, v211, v49 row_newbcast:14 row_mask:0xf bank_mask:0xf
	v_fmac_f32_dpp v229, v211, v91 row_newbcast:15 row_mask:0xf bank_mask:0xf
	ds_read_b32 v211, v232 offset:10672
	s_waitcnt lgkmcnt(11)
	v_fmac_f32_dpp v95, v212, v92 row_newbcast:0 row_mask:0xf bank_mask:0xf
	v_fmac_f32_dpp v225, v212, v93 row_newbcast:1 row_mask:0xf bank_mask:0xf
	v_fmac_f32_dpp v228, v212, v94 row_newbcast:2 row_mask:0xf bank_mask:0xf
	v_add_f32_e32 v95, v95, v225
	v_add_f32_e32 v228, v228, v229
	v_add_f32_e32 v95, v95, v228
	ds_read_b32 v212, v232 offset:10736
	s_waitcnt lgkmcnt(11)
	v_fmac_f32_dpp v96, v213, v18 row_newbcast:0 row_mask:0xf bank_mask:0xf
	v_mul_f32_dpp v222, v213, v19 row_newbcast:1 row_mask:0xf bank_mask:0xf
	v_mul_f32_dpp v223, v213, v20 row_newbcast:2 row_mask:0xf bank_mask:0xf
	v_mul_f32_dpp v224, v213, v21 row_newbcast:3 row_mask:0xf bank_mask:0xf
	v_fmac_f32_dpp v96, v213, v22 row_newbcast:4 row_mask:0xf bank_mask:0xf
	v_fmac_f32_dpp v222, v213, v24 row_newbcast:5 row_mask:0xf bank_mask:0xf
	v_fmac_f32_dpp v223, v213, v25 row_newbcast:6 row_mask:0xf bank_mask:0xf
	v_fmac_f32_dpp v224, v213, v26 row_newbcast:7 row_mask:0xf bank_mask:0xf
	v_fmac_f32_dpp v96, v213, v27 row_newbcast:8 row_mask:0xf bank_mask:0xf
	v_fmac_f32_dpp v222, v213, v28 row_newbcast:9 row_mask:0xf bank_mask:0xf
	v_fmac_f32_dpp v223, v213, v29 row_newbcast:10 row_mask:0xf bank_mask:0xf
	v_fmac_f32_dpp v224, v213, v30 row_newbcast:11 row_mask:0xf bank_mask:0xf
	v_fmac_f32_dpp v96, v213, v31 row_newbcast:12 row_mask:0xf bank_mask:0xf
	v_fmac_f32_dpp v222, v213, v32 row_newbcast:13 row_mask:0xf bank_mask:0xf
	v_fmac_f32_dpp v223, v213, v33 row_newbcast:14 row_mask:0xf bank_mask:0xf
	v_fmac_f32_dpp v224, v213, v34 row_newbcast:15 row_mask:0xf bank_mask:0xf
	ds_read_b32 v213, v232 offset:10880
	s_waitcnt lgkmcnt(11)
	v_fmac_f32_dpp v96, v214, v35 row_newbcast:0 row_mask:0xf bank_mask:0xf
	v_fmac_f32_dpp v222, v214, v36 row_newbcast:1 row_mask:0xf bank_mask:0xf
	v_fmac_f32_dpp v223, v214, v37 row_newbcast:2 row_mask:0xf bank_mask:0xf
	v_fmac_f32_dpp v224, v214, v38 row_newbcast:3 row_mask:0xf bank_mask:0xf
	v_fmac_f32_dpp v96, v214, v39 row_newbcast:4 row_mask:0xf bank_mask:0xf
	v_fmac_f32_dpp v222, v214, v40 row_newbcast:5 row_mask:0xf bank_mask:0xf
	v_fmac_f32_dpp v223, v214, v41 row_newbcast:6 row_mask:0xf bank_mask:0xf
	v_fmac_f32_dpp v224, v214, v42 row_newbcast:7 row_mask:0xf bank_mask:0xf
	v_fmac_f32_dpp v96, v214, v43 row_newbcast:8 row_mask:0xf bank_mask:0xf
	v_fmac_f32_dpp v222, v214, v44 row_newbcast:9 row_mask:0xf bank_mask:0xf
	v_fmac_f32_dpp v223, v214, v45 row_newbcast:10 row_mask:0xf bank_mask:0xf
	v_fmac_f32_dpp v224, v214, v46 row_newbcast:11 row_mask:0xf bank_mask:0xf
	v_fmac_f32_dpp v96, v214, v47 row_newbcast:12 row_mask:0xf bank_mask:0xf
	v_fmac_f32_dpp v222, v214, v48 row_newbcast:13 row_mask:0xf bank_mask:0xf
	v_fmac_f32_dpp v223, v214, v49 row_newbcast:14 row_mask:0xf bank_mask:0xf
	v_fmac_f32_dpp v224, v214, v91 row_newbcast:15 row_mask:0xf bank_mask:0xf
	ds_read_b32 v214, v232 offset:10944
	s_waitcnt lgkmcnt(11)
	v_fmac_f32_dpp v96, v215, v92 row_newbcast:0 row_mask:0xf bank_mask:0xf
	v_fmac_f32_dpp v222, v215, v93 row_newbcast:1 row_mask:0xf bank_mask:0xf
	v_fmac_f32_dpp v223, v215, v94 row_newbcast:2 row_mask:0xf bank_mask:0xf
	v_fmac_f32_dpp v224, v215, v95 row_newbcast:3 row_mask:0xf bank_mask:0xf
	v_add_f32_e32 v96, v96, v222
	v_add_f32_e32 v223, v223, v224
	v_add_f32_e32 v96, v96, v223
	ds_read_b32 v215, v232 offset:11008
	s_waitcnt lgkmcnt(11)
	v_fmac_f32_dpp v97, v204, v18 row_newbcast:0 row_mask:0xf bank_mask:0xf
	v_mul_f32_dpp v225, v204, v19 row_newbcast:1 row_mask:0xf bank_mask:0xf
	v_mul_f32_dpp v228, v204, v20 row_newbcast:2 row_mask:0xf bank_mask:0xf
	v_mul_f32_dpp v229, v204, v21 row_newbcast:3 row_mask:0xf bank_mask:0xf
	v_fmac_f32_dpp v97, v204, v22 row_newbcast:4 row_mask:0xf bank_mask:0xf
	v_fmac_f32_dpp v225, v204, v24 row_newbcast:5 row_mask:0xf bank_mask:0xf
	v_fmac_f32_dpp v228, v204, v25 row_newbcast:6 row_mask:0xf bank_mask:0xf
	v_fmac_f32_dpp v229, v204, v26 row_newbcast:7 row_mask:0xf bank_mask:0xf
	v_fmac_f32_dpp v97, v204, v27 row_newbcast:8 row_mask:0xf bank_mask:0xf
	v_fmac_f32_dpp v225, v204, v28 row_newbcast:9 row_mask:0xf bank_mask:0xf
	v_fmac_f32_dpp v228, v204, v29 row_newbcast:10 row_mask:0xf bank_mask:0xf
	v_fmac_f32_dpp v229, v204, v30 row_newbcast:11 row_mask:0xf bank_mask:0xf
	v_fmac_f32_dpp v97, v204, v31 row_newbcast:12 row_mask:0xf bank_mask:0xf
	v_fmac_f32_dpp v225, v204, v32 row_newbcast:13 row_mask:0xf bank_mask:0xf
	v_fmac_f32_dpp v228, v204, v33 row_newbcast:14 row_mask:0xf bank_mask:0xf
	v_fmac_f32_dpp v229, v204, v34 row_newbcast:15 row_mask:0xf bank_mask:0xf
	ds_read_b32 v204, v232 offset:11152
	s_waitcnt lgkmcnt(11)
	v_fmac_f32_dpp v97, v205, v35 row_newbcast:0 row_mask:0xf bank_mask:0xf
	v_fmac_f32_dpp v225, v205, v36 row_newbcast:1 row_mask:0xf bank_mask:0xf
	v_fmac_f32_dpp v228, v205, v37 row_newbcast:2 row_mask:0xf bank_mask:0xf
	v_fmac_f32_dpp v229, v205, v38 row_newbcast:3 row_mask:0xf bank_mask:0xf
	v_fmac_f32_dpp v97, v205, v39 row_newbcast:4 row_mask:0xf bank_mask:0xf
	v_fmac_f32_dpp v225, v205, v40 row_newbcast:5 row_mask:0xf bank_mask:0xf
	v_fmac_f32_dpp v228, v205, v41 row_newbcast:6 row_mask:0xf bank_mask:0xf
	v_fmac_f32_dpp v229, v205, v42 row_newbcast:7 row_mask:0xf bank_mask:0xf
	v_fmac_f32_dpp v97, v205, v43 row_newbcast:8 row_mask:0xf bank_mask:0xf
	v_fmac_f32_dpp v225, v205, v44 row_newbcast:9 row_mask:0xf bank_mask:0xf
	v_fmac_f32_dpp v228, v205, v45 row_newbcast:10 row_mask:0xf bank_mask:0xf
	v_fmac_f32_dpp v229, v205, v46 row_newbcast:11 row_mask:0xf bank_mask:0xf
	v_fmac_f32_dpp v97, v205, v47 row_newbcast:12 row_mask:0xf bank_mask:0xf
	v_fmac_f32_dpp v225, v205, v48 row_newbcast:13 row_mask:0xf bank_mask:0xf
	v_fmac_f32_dpp v228, v205, v49 row_newbcast:14 row_mask:0xf bank_mask:0xf
	v_fmac_f32_dpp v229, v205, v91 row_newbcast:15 row_mask:0xf bank_mask:0xf
	ds_read_b32 v205, v232 offset:11216
	s_waitcnt lgkmcnt(11)
	v_fmac_f32_dpp v97, v206, v92 row_newbcast:0 row_mask:0xf bank_mask:0xf
	v_fmac_f32_dpp v225, v206, v93 row_newbcast:1 row_mask:0xf bank_mask:0xf
	v_fmac_f32_dpp v228, v206, v94 row_newbcast:2 row_mask:0xf bank_mask:0xf
	v_fmac_f32_dpp v229, v206, v95 row_newbcast:3 row_mask:0xf bank_mask:0xf
	v_fmac_f32_dpp v97, v206, v96 row_newbcast:4 row_mask:0xf bank_mask:0xf
	v_add_f32_e32 v97, v97, v225
	v_add_f32_e32 v228, v228, v229
	v_add_f32_e32 v97, v97, v228
	ds_read_b32 v206, v232 offset:11280
	s_waitcnt lgkmcnt(11)
	v_fmac_f32_dpp v98, v207, v18 row_newbcast:0 row_mask:0xf bank_mask:0xf
	v_mul_f32_dpp v222, v207, v19 row_newbcast:1 row_mask:0xf bank_mask:0xf
	v_mul_f32_dpp v223, v207, v20 row_newbcast:2 row_mask:0xf bank_mask:0xf
	v_mul_f32_dpp v224, v207, v21 row_newbcast:3 row_mask:0xf bank_mask:0xf
	v_fmac_f32_dpp v98, v207, v22 row_newbcast:4 row_mask:0xf bank_mask:0xf
	v_fmac_f32_dpp v222, v207, v24 row_newbcast:5 row_mask:0xf bank_mask:0xf
	v_fmac_f32_dpp v223, v207, v25 row_newbcast:6 row_mask:0xf bank_mask:0xf
	v_fmac_f32_dpp v224, v207, v26 row_newbcast:7 row_mask:0xf bank_mask:0xf
	v_fmac_f32_dpp v98, v207, v27 row_newbcast:8 row_mask:0xf bank_mask:0xf
	v_fmac_f32_dpp v222, v207, v28 row_newbcast:9 row_mask:0xf bank_mask:0xf
	v_fmac_f32_dpp v223, v207, v29 row_newbcast:10 row_mask:0xf bank_mask:0xf
	v_fmac_f32_dpp v224, v207, v30 row_newbcast:11 row_mask:0xf bank_mask:0xf
	v_fmac_f32_dpp v98, v207, v31 row_newbcast:12 row_mask:0xf bank_mask:0xf
	v_fmac_f32_dpp v222, v207, v32 row_newbcast:13 row_mask:0xf bank_mask:0xf
	v_fmac_f32_dpp v223, v207, v33 row_newbcast:14 row_mask:0xf bank_mask:0xf
	v_fmac_f32_dpp v224, v207, v34 row_newbcast:15 row_mask:0xf bank_mask:0xf
	ds_read_b32 v207, v232 offset:11424
	s_waitcnt lgkmcnt(11)
	v_fmac_f32_dpp v98, v208, v35 row_newbcast:0 row_mask:0xf bank_mask:0xf
	v_fmac_f32_dpp v222, v208, v36 row_newbcast:1 row_mask:0xf bank_mask:0xf
	v_fmac_f32_dpp v223, v208, v37 row_newbcast:2 row_mask:0xf bank_mask:0xf
	v_fmac_f32_dpp v224, v208, v38 row_newbcast:3 row_mask:0xf bank_mask:0xf
	v_fmac_f32_dpp v98, v208, v39 row_newbcast:4 row_mask:0xf bank_mask:0xf
	v_fmac_f32_dpp v222, v208, v40 row_newbcast:5 row_mask:0xf bank_mask:0xf
	v_fmac_f32_dpp v223, v208, v41 row_newbcast:6 row_mask:0xf bank_mask:0xf
	v_fmac_f32_dpp v224, v208, v42 row_newbcast:7 row_mask:0xf bank_mask:0xf
	v_fmac_f32_dpp v98, v208, v43 row_newbcast:8 row_mask:0xf bank_mask:0xf
	v_fmac_f32_dpp v222, v208, v44 row_newbcast:9 row_mask:0xf bank_mask:0xf
	v_fmac_f32_dpp v223, v208, v45 row_newbcast:10 row_mask:0xf bank_mask:0xf
	v_fmac_f32_dpp v224, v208, v46 row_newbcast:11 row_mask:0xf bank_mask:0xf
	v_fmac_f32_dpp v98, v208, v47 row_newbcast:12 row_mask:0xf bank_mask:0xf
	v_fmac_f32_dpp v222, v208, v48 row_newbcast:13 row_mask:0xf bank_mask:0xf
	v_fmac_f32_dpp v223, v208, v49 row_newbcast:14 row_mask:0xf bank_mask:0xf
	v_fmac_f32_dpp v224, v208, v91 row_newbcast:15 row_mask:0xf bank_mask:0xf
	ds_read_b32 v208, v232 offset:11488
	s_waitcnt lgkmcnt(11)
	v_fmac_f32_dpp v98, v209, v92 row_newbcast:0 row_mask:0xf bank_mask:0xf
	v_fmac_f32_dpp v222, v209, v93 row_newbcast:1 row_mask:0xf bank_mask:0xf
	v_fmac_f32_dpp v223, v209, v94 row_newbcast:2 row_mask:0xf bank_mask:0xf
	v_fmac_f32_dpp v224, v209, v95 row_newbcast:3 row_mask:0xf bank_mask:0xf
	v_fmac_f32_dpp v98, v209, v96 row_newbcast:4 row_mask:0xf bank_mask:0xf
	v_fmac_f32_dpp v222, v209, v97 row_newbcast:5 row_mask:0xf bank_mask:0xf
	v_add_f32_e32 v98, v98, v222
	v_add_f32_e32 v223, v223, v224
	v_add_f32_e32 v98, v98, v223
	ds_read_b32 v209, v232 offset:11552
	s_waitcnt lgkmcnt(11)
	v_fmac_f32_dpp v99, v210, v18 row_newbcast:0 row_mask:0xf bank_mask:0xf
	v_mul_f32_dpp v225, v210, v19 row_newbcast:1 row_mask:0xf bank_mask:0xf
	v_mul_f32_dpp v228, v210, v20 row_newbcast:2 row_mask:0xf bank_mask:0xf
	v_mul_f32_dpp v229, v210, v21 row_newbcast:3 row_mask:0xf bank_mask:0xf
	v_fmac_f32_dpp v99, v210, v22 row_newbcast:4 row_mask:0xf bank_mask:0xf
	v_fmac_f32_dpp v225, v210, v24 row_newbcast:5 row_mask:0xf bank_mask:0xf
	v_fmac_f32_dpp v228, v210, v25 row_newbcast:6 row_mask:0xf bank_mask:0xf
	v_fmac_f32_dpp v229, v210, v26 row_newbcast:7 row_mask:0xf bank_mask:0xf
	v_fmac_f32_dpp v99, v210, v27 row_newbcast:8 row_mask:0xf bank_mask:0xf
	v_fmac_f32_dpp v225, v210, v28 row_newbcast:9 row_mask:0xf bank_mask:0xf
	v_fmac_f32_dpp v228, v210, v29 row_newbcast:10 row_mask:0xf bank_mask:0xf
	v_fmac_f32_dpp v229, v210, v30 row_newbcast:11 row_mask:0xf bank_mask:0xf
	v_fmac_f32_dpp v99, v210, v31 row_newbcast:12 row_mask:0xf bank_mask:0xf
	v_fmac_f32_dpp v225, v210, v32 row_newbcast:13 row_mask:0xf bank_mask:0xf
	v_fmac_f32_dpp v228, v210, v33 row_newbcast:14 row_mask:0xf bank_mask:0xf
	v_fmac_f32_dpp v229, v210, v34 row_newbcast:15 row_mask:0xf bank_mask:0xf
	ds_read_b32 v210, v232 offset:11696
	s_waitcnt lgkmcnt(11)
	v_fmac_f32_dpp v99, v211, v35 row_newbcast:0 row_mask:0xf bank_mask:0xf
	v_fmac_f32_dpp v225, v211, v36 row_newbcast:1 row_mask:0xf bank_mask:0xf
	v_fmac_f32_dpp v228, v211, v37 row_newbcast:2 row_mask:0xf bank_mask:0xf
	v_fmac_f32_dpp v229, v211, v38 row_newbcast:3 row_mask:0xf bank_mask:0xf
	v_fmac_f32_dpp v99, v211, v39 row_newbcast:4 row_mask:0xf bank_mask:0xf
	v_fmac_f32_dpp v225, v211, v40 row_newbcast:5 row_mask:0xf bank_mask:0xf
	v_fmac_f32_dpp v228, v211, v41 row_newbcast:6 row_mask:0xf bank_mask:0xf
	v_fmac_f32_dpp v229, v211, v42 row_newbcast:7 row_mask:0xf bank_mask:0xf
	v_fmac_f32_dpp v99, v211, v43 row_newbcast:8 row_mask:0xf bank_mask:0xf
	v_fmac_f32_dpp v225, v211, v44 row_newbcast:9 row_mask:0xf bank_mask:0xf
	v_fmac_f32_dpp v228, v211, v45 row_newbcast:10 row_mask:0xf bank_mask:0xf
	v_fmac_f32_dpp v229, v211, v46 row_newbcast:11 row_mask:0xf bank_mask:0xf
	v_fmac_f32_dpp v99, v211, v47 row_newbcast:12 row_mask:0xf bank_mask:0xf
	v_fmac_f32_dpp v225, v211, v48 row_newbcast:13 row_mask:0xf bank_mask:0xf
	v_fmac_f32_dpp v228, v211, v49 row_newbcast:14 row_mask:0xf bank_mask:0xf
	v_fmac_f32_dpp v229, v211, v91 row_newbcast:15 row_mask:0xf bank_mask:0xf
	ds_read_b32 v211, v232 offset:11760
	s_waitcnt lgkmcnt(11)
	v_fmac_f32_dpp v99, v212, v92 row_newbcast:0 row_mask:0xf bank_mask:0xf
	v_fmac_f32_dpp v225, v212, v93 row_newbcast:1 row_mask:0xf bank_mask:0xf
	v_fmac_f32_dpp v228, v212, v94 row_newbcast:2 row_mask:0xf bank_mask:0xf
	v_fmac_f32_dpp v229, v212, v95 row_newbcast:3 row_mask:0xf bank_mask:0xf
	v_fmac_f32_dpp v99, v212, v96 row_newbcast:4 row_mask:0xf bank_mask:0xf
	v_fmac_f32_dpp v225, v212, v97 row_newbcast:5 row_mask:0xf bank_mask:0xf
	v_fmac_f32_dpp v228, v212, v98 row_newbcast:6 row_mask:0xf bank_mask:0xf
	v_add_f32_e32 v99, v99, v225
	v_add_f32_e32 v228, v228, v229
	v_add_f32_e32 v99, v99, v228
	ds_read_b32 v212, v232 offset:11824
	s_waitcnt lgkmcnt(11)
	v_fmac_f32_dpp v100, v213, v18 row_newbcast:0 row_mask:0xf bank_mask:0xf
	v_mul_f32_dpp v222, v213, v19 row_newbcast:1 row_mask:0xf bank_mask:0xf
	v_mul_f32_dpp v223, v213, v20 row_newbcast:2 row_mask:0xf bank_mask:0xf
	v_mul_f32_dpp v224, v213, v21 row_newbcast:3 row_mask:0xf bank_mask:0xf
	v_fmac_f32_dpp v100, v213, v22 row_newbcast:4 row_mask:0xf bank_mask:0xf
	v_fmac_f32_dpp v222, v213, v24 row_newbcast:5 row_mask:0xf bank_mask:0xf
	v_fmac_f32_dpp v223, v213, v25 row_newbcast:6 row_mask:0xf bank_mask:0xf
	v_fmac_f32_dpp v224, v213, v26 row_newbcast:7 row_mask:0xf bank_mask:0xf
	v_fmac_f32_dpp v100, v213, v27 row_newbcast:8 row_mask:0xf bank_mask:0xf
	v_fmac_f32_dpp v222, v213, v28 row_newbcast:9 row_mask:0xf bank_mask:0xf
	v_fmac_f32_dpp v223, v213, v29 row_newbcast:10 row_mask:0xf bank_mask:0xf
	v_fmac_f32_dpp v224, v213, v30 row_newbcast:11 row_mask:0xf bank_mask:0xf
	v_fmac_f32_dpp v100, v213, v31 row_newbcast:12 row_mask:0xf bank_mask:0xf
	v_fmac_f32_dpp v222, v213, v32 row_newbcast:13 row_mask:0xf bank_mask:0xf
	v_fmac_f32_dpp v223, v213, v33 row_newbcast:14 row_mask:0xf bank_mask:0xf
	v_fmac_f32_dpp v224, v213, v34 row_newbcast:15 row_mask:0xf bank_mask:0xf
	ds_read_b32 v213, v232 offset:11968
	s_waitcnt lgkmcnt(11)
	v_fmac_f32_dpp v100, v214, v35 row_newbcast:0 row_mask:0xf bank_mask:0xf
	v_fmac_f32_dpp v222, v214, v36 row_newbcast:1 row_mask:0xf bank_mask:0xf
	v_fmac_f32_dpp v223, v214, v37 row_newbcast:2 row_mask:0xf bank_mask:0xf
	v_fmac_f32_dpp v224, v214, v38 row_newbcast:3 row_mask:0xf bank_mask:0xf
	v_fmac_f32_dpp v100, v214, v39 row_newbcast:4 row_mask:0xf bank_mask:0xf
	v_fmac_f32_dpp v222, v214, v40 row_newbcast:5 row_mask:0xf bank_mask:0xf
	v_fmac_f32_dpp v223, v214, v41 row_newbcast:6 row_mask:0xf bank_mask:0xf
	v_fmac_f32_dpp v224, v214, v42 row_newbcast:7 row_mask:0xf bank_mask:0xf
	v_fmac_f32_dpp v100, v214, v43 row_newbcast:8 row_mask:0xf bank_mask:0xf
	v_fmac_f32_dpp v222, v214, v44 row_newbcast:9 row_mask:0xf bank_mask:0xf
	v_fmac_f32_dpp v223, v214, v45 row_newbcast:10 row_mask:0xf bank_mask:0xf
	v_fmac_f32_dpp v224, v214, v46 row_newbcast:11 row_mask:0xf bank_mask:0xf
	v_fmac_f32_dpp v100, v214, v47 row_newbcast:12 row_mask:0xf bank_mask:0xf
	v_fmac_f32_dpp v222, v214, v48 row_newbcast:13 row_mask:0xf bank_mask:0xf
	v_fmac_f32_dpp v223, v214, v49 row_newbcast:14 row_mask:0xf bank_mask:0xf
	v_fmac_f32_dpp v224, v214, v91 row_newbcast:15 row_mask:0xf bank_mask:0xf
	ds_read_b32 v214, v232 offset:12032
	s_waitcnt lgkmcnt(11)
	v_fmac_f32_dpp v100, v215, v92 row_newbcast:0 row_mask:0xf bank_mask:0xf
	v_fmac_f32_dpp v222, v215, v93 row_newbcast:1 row_mask:0xf bank_mask:0xf
	v_fmac_f32_dpp v223, v215, v94 row_newbcast:2 row_mask:0xf bank_mask:0xf
	v_fmac_f32_dpp v224, v215, v95 row_newbcast:3 row_mask:0xf bank_mask:0xf
	v_fmac_f32_dpp v100, v215, v96 row_newbcast:4 row_mask:0xf bank_mask:0xf
	v_fmac_f32_dpp v222, v215, v97 row_newbcast:5 row_mask:0xf bank_mask:0xf
	v_fmac_f32_dpp v223, v215, v98 row_newbcast:6 row_mask:0xf bank_mask:0xf
	v_fmac_f32_dpp v224, v215, v99 row_newbcast:7 row_mask:0xf bank_mask:0xf
	v_add_f32_e32 v100, v100, v222
	v_add_f32_e32 v223, v223, v224
	v_add_f32_e32 v100, v100, v223
	ds_read_b32 v215, v232 offset:12096
	s_waitcnt lgkmcnt(11)
	v_fmac_f32_dpp v101, v204, v18 row_newbcast:0 row_mask:0xf bank_mask:0xf
	v_mul_f32_dpp v225, v204, v19 row_newbcast:1 row_mask:0xf bank_mask:0xf
	v_mul_f32_dpp v228, v204, v20 row_newbcast:2 row_mask:0xf bank_mask:0xf
	v_mul_f32_dpp v229, v204, v21 row_newbcast:3 row_mask:0xf bank_mask:0xf
	v_fmac_f32_dpp v101, v204, v22 row_newbcast:4 row_mask:0xf bank_mask:0xf
	v_fmac_f32_dpp v225, v204, v24 row_newbcast:5 row_mask:0xf bank_mask:0xf
	v_fmac_f32_dpp v228, v204, v25 row_newbcast:6 row_mask:0xf bank_mask:0xf
	v_fmac_f32_dpp v229, v204, v26 row_newbcast:7 row_mask:0xf bank_mask:0xf
	v_fmac_f32_dpp v101, v204, v27 row_newbcast:8 row_mask:0xf bank_mask:0xf
	v_fmac_f32_dpp v225, v204, v28 row_newbcast:9 row_mask:0xf bank_mask:0xf
	v_fmac_f32_dpp v228, v204, v29 row_newbcast:10 row_mask:0xf bank_mask:0xf
	v_fmac_f32_dpp v229, v204, v30 row_newbcast:11 row_mask:0xf bank_mask:0xf
	v_fmac_f32_dpp v101, v204, v31 row_newbcast:12 row_mask:0xf bank_mask:0xf
	v_fmac_f32_dpp v225, v204, v32 row_newbcast:13 row_mask:0xf bank_mask:0xf
	v_fmac_f32_dpp v228, v204, v33 row_newbcast:14 row_mask:0xf bank_mask:0xf
	v_fmac_f32_dpp v229, v204, v34 row_newbcast:15 row_mask:0xf bank_mask:0xf
	ds_read_b32 v204, v232 offset:12240
	s_waitcnt lgkmcnt(11)
	v_fmac_f32_dpp v101, v205, v35 row_newbcast:0 row_mask:0xf bank_mask:0xf
	v_fmac_f32_dpp v225, v205, v36 row_newbcast:1 row_mask:0xf bank_mask:0xf
	v_fmac_f32_dpp v228, v205, v37 row_newbcast:2 row_mask:0xf bank_mask:0xf
	v_fmac_f32_dpp v229, v205, v38 row_newbcast:3 row_mask:0xf bank_mask:0xf
	v_fmac_f32_dpp v101, v205, v39 row_newbcast:4 row_mask:0xf bank_mask:0xf
	v_fmac_f32_dpp v225, v205, v40 row_newbcast:5 row_mask:0xf bank_mask:0xf
	v_fmac_f32_dpp v228, v205, v41 row_newbcast:6 row_mask:0xf bank_mask:0xf
	v_fmac_f32_dpp v229, v205, v42 row_newbcast:7 row_mask:0xf bank_mask:0xf
	v_fmac_f32_dpp v101, v205, v43 row_newbcast:8 row_mask:0xf bank_mask:0xf
	v_fmac_f32_dpp v225, v205, v44 row_newbcast:9 row_mask:0xf bank_mask:0xf
	v_fmac_f32_dpp v228, v205, v45 row_newbcast:10 row_mask:0xf bank_mask:0xf
	v_fmac_f32_dpp v229, v205, v46 row_newbcast:11 row_mask:0xf bank_mask:0xf
	v_fmac_f32_dpp v101, v205, v47 row_newbcast:12 row_mask:0xf bank_mask:0xf
	v_fmac_f32_dpp v225, v205, v48 row_newbcast:13 row_mask:0xf bank_mask:0xf
	v_fmac_f32_dpp v228, v205, v49 row_newbcast:14 row_mask:0xf bank_mask:0xf
	v_fmac_f32_dpp v229, v205, v91 row_newbcast:15 row_mask:0xf bank_mask:0xf
	ds_read_b32 v205, v232 offset:12304
	s_waitcnt lgkmcnt(11)
	v_fmac_f32_dpp v101, v206, v92 row_newbcast:0 row_mask:0xf bank_mask:0xf
	v_fmac_f32_dpp v225, v206, v93 row_newbcast:1 row_mask:0xf bank_mask:0xf
	v_fmac_f32_dpp v228, v206, v94 row_newbcast:2 row_mask:0xf bank_mask:0xf
	v_fmac_f32_dpp v229, v206, v95 row_newbcast:3 row_mask:0xf bank_mask:0xf
	v_fmac_f32_dpp v101, v206, v96 row_newbcast:4 row_mask:0xf bank_mask:0xf
	v_fmac_f32_dpp v225, v206, v97 row_newbcast:5 row_mask:0xf bank_mask:0xf
	v_fmac_f32_dpp v228, v206, v98 row_newbcast:6 row_mask:0xf bank_mask:0xf
	v_fmac_f32_dpp v229, v206, v99 row_newbcast:7 row_mask:0xf bank_mask:0xf
	v_fmac_f32_dpp v101, v206, v100 row_newbcast:8 row_mask:0xf bank_mask:0xf
	v_add_f32_e32 v101, v101, v225
	v_add_f32_e32 v228, v228, v229
	v_add_f32_e32 v101, v101, v228
	ds_read_b32 v206, v232 offset:12368
	s_waitcnt lgkmcnt(11)
	v_fmac_f32_dpp v102, v207, v18 row_newbcast:0 row_mask:0xf bank_mask:0xf
	v_mul_f32_dpp v222, v207, v19 row_newbcast:1 row_mask:0xf bank_mask:0xf
	v_mul_f32_dpp v223, v207, v20 row_newbcast:2 row_mask:0xf bank_mask:0xf
	v_mul_f32_dpp v224, v207, v21 row_newbcast:3 row_mask:0xf bank_mask:0xf
	v_fmac_f32_dpp v102, v207, v22 row_newbcast:4 row_mask:0xf bank_mask:0xf
	v_fmac_f32_dpp v222, v207, v24 row_newbcast:5 row_mask:0xf bank_mask:0xf
	v_fmac_f32_dpp v223, v207, v25 row_newbcast:6 row_mask:0xf bank_mask:0xf
	v_fmac_f32_dpp v224, v207, v26 row_newbcast:7 row_mask:0xf bank_mask:0xf
	v_fmac_f32_dpp v102, v207, v27 row_newbcast:8 row_mask:0xf bank_mask:0xf
	v_fmac_f32_dpp v222, v207, v28 row_newbcast:9 row_mask:0xf bank_mask:0xf
	v_fmac_f32_dpp v223, v207, v29 row_newbcast:10 row_mask:0xf bank_mask:0xf
	v_fmac_f32_dpp v224, v207, v30 row_newbcast:11 row_mask:0xf bank_mask:0xf
	v_fmac_f32_dpp v102, v207, v31 row_newbcast:12 row_mask:0xf bank_mask:0xf
	v_fmac_f32_dpp v222, v207, v32 row_newbcast:13 row_mask:0xf bank_mask:0xf
	v_fmac_f32_dpp v223, v207, v33 row_newbcast:14 row_mask:0xf bank_mask:0xf
	v_fmac_f32_dpp v224, v207, v34 row_newbcast:15 row_mask:0xf bank_mask:0xf
	ds_read_b32 v207, v232 offset:12512
	s_waitcnt lgkmcnt(11)
	v_fmac_f32_dpp v102, v208, v35 row_newbcast:0 row_mask:0xf bank_mask:0xf
	v_fmac_f32_dpp v222, v208, v36 row_newbcast:1 row_mask:0xf bank_mask:0xf
	v_fmac_f32_dpp v223, v208, v37 row_newbcast:2 row_mask:0xf bank_mask:0xf
	v_fmac_f32_dpp v224, v208, v38 row_newbcast:3 row_mask:0xf bank_mask:0xf
	v_fmac_f32_dpp v102, v208, v39 row_newbcast:4 row_mask:0xf bank_mask:0xf
	v_fmac_f32_dpp v222, v208, v40 row_newbcast:5 row_mask:0xf bank_mask:0xf
	v_fmac_f32_dpp v223, v208, v41 row_newbcast:6 row_mask:0xf bank_mask:0xf
	v_fmac_f32_dpp v224, v208, v42 row_newbcast:7 row_mask:0xf bank_mask:0xf
	v_fmac_f32_dpp v102, v208, v43 row_newbcast:8 row_mask:0xf bank_mask:0xf
	v_fmac_f32_dpp v222, v208, v44 row_newbcast:9 row_mask:0xf bank_mask:0xf
	v_fmac_f32_dpp v223, v208, v45 row_newbcast:10 row_mask:0xf bank_mask:0xf
	v_fmac_f32_dpp v224, v208, v46 row_newbcast:11 row_mask:0xf bank_mask:0xf
	v_fmac_f32_dpp v102, v208, v47 row_newbcast:12 row_mask:0xf bank_mask:0xf
	v_fmac_f32_dpp v222, v208, v48 row_newbcast:13 row_mask:0xf bank_mask:0xf
	v_fmac_f32_dpp v223, v208, v49 row_newbcast:14 row_mask:0xf bank_mask:0xf
	v_fmac_f32_dpp v224, v208, v91 row_newbcast:15 row_mask:0xf bank_mask:0xf
	ds_read_b32 v208, v232 offset:12576
	s_waitcnt lgkmcnt(11)
	v_fmac_f32_dpp v102, v209, v92 row_newbcast:0 row_mask:0xf bank_mask:0xf
	v_fmac_f32_dpp v222, v209, v93 row_newbcast:1 row_mask:0xf bank_mask:0xf
	v_fmac_f32_dpp v223, v209, v94 row_newbcast:2 row_mask:0xf bank_mask:0xf
	v_fmac_f32_dpp v224, v209, v95 row_newbcast:3 row_mask:0xf bank_mask:0xf
	v_fmac_f32_dpp v102, v209, v96 row_newbcast:4 row_mask:0xf bank_mask:0xf
	v_fmac_f32_dpp v222, v209, v97 row_newbcast:5 row_mask:0xf bank_mask:0xf
	v_fmac_f32_dpp v223, v209, v98 row_newbcast:6 row_mask:0xf bank_mask:0xf
	v_fmac_f32_dpp v224, v209, v99 row_newbcast:7 row_mask:0xf bank_mask:0xf
	v_fmac_f32_dpp v102, v209, v100 row_newbcast:8 row_mask:0xf bank_mask:0xf
	v_fmac_f32_dpp v222, v209, v101 row_newbcast:9 row_mask:0xf bank_mask:0xf
	v_add_f32_e32 v102, v102, v222
	v_add_f32_e32 v223, v223, v224
	v_add_f32_e32 v102, v102, v223
	ds_read_b32 v209, v232 offset:12640
	s_waitcnt lgkmcnt(11)
	v_fmac_f32_dpp v103, v210, v18 row_newbcast:0 row_mask:0xf bank_mask:0xf
	v_mul_f32_dpp v225, v210, v19 row_newbcast:1 row_mask:0xf bank_mask:0xf
	v_mul_f32_dpp v228, v210, v20 row_newbcast:2 row_mask:0xf bank_mask:0xf
	v_mul_f32_dpp v229, v210, v21 row_newbcast:3 row_mask:0xf bank_mask:0xf
	v_fmac_f32_dpp v103, v210, v22 row_newbcast:4 row_mask:0xf bank_mask:0xf
	v_fmac_f32_dpp v225, v210, v24 row_newbcast:5 row_mask:0xf bank_mask:0xf
	v_fmac_f32_dpp v228, v210, v25 row_newbcast:6 row_mask:0xf bank_mask:0xf
	v_fmac_f32_dpp v229, v210, v26 row_newbcast:7 row_mask:0xf bank_mask:0xf
	v_fmac_f32_dpp v103, v210, v27 row_newbcast:8 row_mask:0xf bank_mask:0xf
	v_fmac_f32_dpp v225, v210, v28 row_newbcast:9 row_mask:0xf bank_mask:0xf
	v_fmac_f32_dpp v228, v210, v29 row_newbcast:10 row_mask:0xf bank_mask:0xf
	v_fmac_f32_dpp v229, v210, v30 row_newbcast:11 row_mask:0xf bank_mask:0xf
	v_fmac_f32_dpp v103, v210, v31 row_newbcast:12 row_mask:0xf bank_mask:0xf
	v_fmac_f32_dpp v225, v210, v32 row_newbcast:13 row_mask:0xf bank_mask:0xf
	v_fmac_f32_dpp v228, v210, v33 row_newbcast:14 row_mask:0xf bank_mask:0xf
	v_fmac_f32_dpp v229, v210, v34 row_newbcast:15 row_mask:0xf bank_mask:0xf
	ds_read_b32 v210, v232 offset:12784
	s_waitcnt lgkmcnt(11)
	v_fmac_f32_dpp v103, v211, v35 row_newbcast:0 row_mask:0xf bank_mask:0xf
	v_fmac_f32_dpp v225, v211, v36 row_newbcast:1 row_mask:0xf bank_mask:0xf
	v_fmac_f32_dpp v228, v211, v37 row_newbcast:2 row_mask:0xf bank_mask:0xf
	v_fmac_f32_dpp v229, v211, v38 row_newbcast:3 row_mask:0xf bank_mask:0xf
	v_fmac_f32_dpp v103, v211, v39 row_newbcast:4 row_mask:0xf bank_mask:0xf
	v_fmac_f32_dpp v225, v211, v40 row_newbcast:5 row_mask:0xf bank_mask:0xf
	v_fmac_f32_dpp v228, v211, v41 row_newbcast:6 row_mask:0xf bank_mask:0xf
	v_fmac_f32_dpp v229, v211, v42 row_newbcast:7 row_mask:0xf bank_mask:0xf
	v_fmac_f32_dpp v103, v211, v43 row_newbcast:8 row_mask:0xf bank_mask:0xf
	v_fmac_f32_dpp v225, v211, v44 row_newbcast:9 row_mask:0xf bank_mask:0xf
	v_fmac_f32_dpp v228, v211, v45 row_newbcast:10 row_mask:0xf bank_mask:0xf
	v_fmac_f32_dpp v229, v211, v46 row_newbcast:11 row_mask:0xf bank_mask:0xf
	v_fmac_f32_dpp v103, v211, v47 row_newbcast:12 row_mask:0xf bank_mask:0xf
	v_fmac_f32_dpp v225, v211, v48 row_newbcast:13 row_mask:0xf bank_mask:0xf
	v_fmac_f32_dpp v228, v211, v49 row_newbcast:14 row_mask:0xf bank_mask:0xf
	v_fmac_f32_dpp v229, v211, v91 row_newbcast:15 row_mask:0xf bank_mask:0xf
	ds_read_b32 v211, v232 offset:12848
	s_waitcnt lgkmcnt(11)
	v_fmac_f32_dpp v103, v212, v92 row_newbcast:0 row_mask:0xf bank_mask:0xf
	v_fmac_f32_dpp v225, v212, v93 row_newbcast:1 row_mask:0xf bank_mask:0xf
	v_fmac_f32_dpp v228, v212, v94 row_newbcast:2 row_mask:0xf bank_mask:0xf
	v_fmac_f32_dpp v229, v212, v95 row_newbcast:3 row_mask:0xf bank_mask:0xf
	v_fmac_f32_dpp v103, v212, v96 row_newbcast:4 row_mask:0xf bank_mask:0xf
	v_fmac_f32_dpp v225, v212, v97 row_newbcast:5 row_mask:0xf bank_mask:0xf
	v_fmac_f32_dpp v228, v212, v98 row_newbcast:6 row_mask:0xf bank_mask:0xf
	v_fmac_f32_dpp v229, v212, v99 row_newbcast:7 row_mask:0xf bank_mask:0xf
	v_fmac_f32_dpp v103, v212, v100 row_newbcast:8 row_mask:0xf bank_mask:0xf
	v_fmac_f32_dpp v225, v212, v101 row_newbcast:9 row_mask:0xf bank_mask:0xf
	v_fmac_f32_dpp v228, v212, v102 row_newbcast:10 row_mask:0xf bank_mask:0xf
	v_add_f32_e32 v103, v103, v225
	v_add_f32_e32 v228, v228, v229
	v_add_f32_e32 v103, v103, v228
	ds_read_b32 v212, v232 offset:12912
	s_waitcnt lgkmcnt(11)
	v_fmac_f32_dpp v104, v213, v18 row_newbcast:0 row_mask:0xf bank_mask:0xf
	v_mul_f32_dpp v222, v213, v19 row_newbcast:1 row_mask:0xf bank_mask:0xf
	v_mul_f32_dpp v223, v213, v20 row_newbcast:2 row_mask:0xf bank_mask:0xf
	v_mul_f32_dpp v224, v213, v21 row_newbcast:3 row_mask:0xf bank_mask:0xf
	v_fmac_f32_dpp v104, v213, v22 row_newbcast:4 row_mask:0xf bank_mask:0xf
	v_fmac_f32_dpp v222, v213, v24 row_newbcast:5 row_mask:0xf bank_mask:0xf
	v_fmac_f32_dpp v223, v213, v25 row_newbcast:6 row_mask:0xf bank_mask:0xf
	v_fmac_f32_dpp v224, v213, v26 row_newbcast:7 row_mask:0xf bank_mask:0xf
	v_fmac_f32_dpp v104, v213, v27 row_newbcast:8 row_mask:0xf bank_mask:0xf
	v_fmac_f32_dpp v222, v213, v28 row_newbcast:9 row_mask:0xf bank_mask:0xf
	v_fmac_f32_dpp v223, v213, v29 row_newbcast:10 row_mask:0xf bank_mask:0xf
	v_fmac_f32_dpp v224, v213, v30 row_newbcast:11 row_mask:0xf bank_mask:0xf
	v_fmac_f32_dpp v104, v213, v31 row_newbcast:12 row_mask:0xf bank_mask:0xf
	v_fmac_f32_dpp v222, v213, v32 row_newbcast:13 row_mask:0xf bank_mask:0xf
	v_fmac_f32_dpp v223, v213, v33 row_newbcast:14 row_mask:0xf bank_mask:0xf
	v_fmac_f32_dpp v224, v213, v34 row_newbcast:15 row_mask:0xf bank_mask:0xf
	ds_read_b32 v213, v232 offset:13056
	s_waitcnt lgkmcnt(11)
	v_fmac_f32_dpp v104, v214, v35 row_newbcast:0 row_mask:0xf bank_mask:0xf
	v_fmac_f32_dpp v222, v214, v36 row_newbcast:1 row_mask:0xf bank_mask:0xf
	v_fmac_f32_dpp v223, v214, v37 row_newbcast:2 row_mask:0xf bank_mask:0xf
	v_fmac_f32_dpp v224, v214, v38 row_newbcast:3 row_mask:0xf bank_mask:0xf
	v_fmac_f32_dpp v104, v214, v39 row_newbcast:4 row_mask:0xf bank_mask:0xf
	v_fmac_f32_dpp v222, v214, v40 row_newbcast:5 row_mask:0xf bank_mask:0xf
	v_fmac_f32_dpp v223, v214, v41 row_newbcast:6 row_mask:0xf bank_mask:0xf
	v_fmac_f32_dpp v224, v214, v42 row_newbcast:7 row_mask:0xf bank_mask:0xf
	v_fmac_f32_dpp v104, v214, v43 row_newbcast:8 row_mask:0xf bank_mask:0xf
	v_fmac_f32_dpp v222, v214, v44 row_newbcast:9 row_mask:0xf bank_mask:0xf
	v_fmac_f32_dpp v223, v214, v45 row_newbcast:10 row_mask:0xf bank_mask:0xf
	v_fmac_f32_dpp v224, v214, v46 row_newbcast:11 row_mask:0xf bank_mask:0xf
	v_fmac_f32_dpp v104, v214, v47 row_newbcast:12 row_mask:0xf bank_mask:0xf
	v_fmac_f32_dpp v222, v214, v48 row_newbcast:13 row_mask:0xf bank_mask:0xf
	v_fmac_f32_dpp v223, v214, v49 row_newbcast:14 row_mask:0xf bank_mask:0xf
	v_fmac_f32_dpp v224, v214, v91 row_newbcast:15 row_mask:0xf bank_mask:0xf
	ds_read_b32 v214, v232 offset:13120
	s_waitcnt lgkmcnt(11)
	v_fmac_f32_dpp v104, v215, v92 row_newbcast:0 row_mask:0xf bank_mask:0xf
	v_fmac_f32_dpp v222, v215, v93 row_newbcast:1 row_mask:0xf bank_mask:0xf
	v_fmac_f32_dpp v223, v215, v94 row_newbcast:2 row_mask:0xf bank_mask:0xf
	v_fmac_f32_dpp v224, v215, v95 row_newbcast:3 row_mask:0xf bank_mask:0xf
	v_fmac_f32_dpp v104, v215, v96 row_newbcast:4 row_mask:0xf bank_mask:0xf
	v_fmac_f32_dpp v222, v215, v97 row_newbcast:5 row_mask:0xf bank_mask:0xf
	v_fmac_f32_dpp v223, v215, v98 row_newbcast:6 row_mask:0xf bank_mask:0xf
	v_fmac_f32_dpp v224, v215, v99 row_newbcast:7 row_mask:0xf bank_mask:0xf
	v_fmac_f32_dpp v104, v215, v100 row_newbcast:8 row_mask:0xf bank_mask:0xf
	v_fmac_f32_dpp v222, v215, v101 row_newbcast:9 row_mask:0xf bank_mask:0xf
	v_fmac_f32_dpp v223, v215, v102 row_newbcast:10 row_mask:0xf bank_mask:0xf
	v_fmac_f32_dpp v224, v215, v103 row_newbcast:11 row_mask:0xf bank_mask:0xf
	v_add_f32_e32 v104, v104, v222
	v_add_f32_e32 v223, v223, v224
	v_add_f32_e32 v104, v104, v223
	ds_read_b32 v215, v232 offset:13184
	s_waitcnt lgkmcnt(11)
	v_fmac_f32_dpp v105, v204, v18 row_newbcast:0 row_mask:0xf bank_mask:0xf
	v_mul_f32_dpp v225, v204, v19 row_newbcast:1 row_mask:0xf bank_mask:0xf
	v_mul_f32_dpp v228, v204, v20 row_newbcast:2 row_mask:0xf bank_mask:0xf
	v_mul_f32_dpp v229, v204, v21 row_newbcast:3 row_mask:0xf bank_mask:0xf
	v_fmac_f32_dpp v105, v204, v22 row_newbcast:4 row_mask:0xf bank_mask:0xf
	v_fmac_f32_dpp v225, v204, v24 row_newbcast:5 row_mask:0xf bank_mask:0xf
	v_fmac_f32_dpp v228, v204, v25 row_newbcast:6 row_mask:0xf bank_mask:0xf
	v_fmac_f32_dpp v229, v204, v26 row_newbcast:7 row_mask:0xf bank_mask:0xf
	v_fmac_f32_dpp v105, v204, v27 row_newbcast:8 row_mask:0xf bank_mask:0xf
	v_fmac_f32_dpp v225, v204, v28 row_newbcast:9 row_mask:0xf bank_mask:0xf
	v_fmac_f32_dpp v228, v204, v29 row_newbcast:10 row_mask:0xf bank_mask:0xf
	v_fmac_f32_dpp v229, v204, v30 row_newbcast:11 row_mask:0xf bank_mask:0xf
	v_fmac_f32_dpp v105, v204, v31 row_newbcast:12 row_mask:0xf bank_mask:0xf
	v_fmac_f32_dpp v225, v204, v32 row_newbcast:13 row_mask:0xf bank_mask:0xf
	v_fmac_f32_dpp v228, v204, v33 row_newbcast:14 row_mask:0xf bank_mask:0xf
	v_fmac_f32_dpp v229, v204, v34 row_newbcast:15 row_mask:0xf bank_mask:0xf
	ds_read_b32 v204, v232 offset:13328
	s_waitcnt lgkmcnt(11)
	v_fmac_f32_dpp v105, v205, v35 row_newbcast:0 row_mask:0xf bank_mask:0xf
	v_fmac_f32_dpp v225, v205, v36 row_newbcast:1 row_mask:0xf bank_mask:0xf
	v_fmac_f32_dpp v228, v205, v37 row_newbcast:2 row_mask:0xf bank_mask:0xf
	v_fmac_f32_dpp v229, v205, v38 row_newbcast:3 row_mask:0xf bank_mask:0xf
	v_fmac_f32_dpp v105, v205, v39 row_newbcast:4 row_mask:0xf bank_mask:0xf
	v_fmac_f32_dpp v225, v205, v40 row_newbcast:5 row_mask:0xf bank_mask:0xf
	v_fmac_f32_dpp v228, v205, v41 row_newbcast:6 row_mask:0xf bank_mask:0xf
	v_fmac_f32_dpp v229, v205, v42 row_newbcast:7 row_mask:0xf bank_mask:0xf
	v_fmac_f32_dpp v105, v205, v43 row_newbcast:8 row_mask:0xf bank_mask:0xf
	v_fmac_f32_dpp v225, v205, v44 row_newbcast:9 row_mask:0xf bank_mask:0xf
	v_fmac_f32_dpp v228, v205, v45 row_newbcast:10 row_mask:0xf bank_mask:0xf
	v_fmac_f32_dpp v229, v205, v46 row_newbcast:11 row_mask:0xf bank_mask:0xf
	v_fmac_f32_dpp v105, v205, v47 row_newbcast:12 row_mask:0xf bank_mask:0xf
	v_fmac_f32_dpp v225, v205, v48 row_newbcast:13 row_mask:0xf bank_mask:0xf
	v_fmac_f32_dpp v228, v205, v49 row_newbcast:14 row_mask:0xf bank_mask:0xf
	v_fmac_f32_dpp v229, v205, v91 row_newbcast:15 row_mask:0xf bank_mask:0xf
	ds_read_b32 v205, v232 offset:13392
	s_waitcnt lgkmcnt(11)
	v_fmac_f32_dpp v105, v206, v92 row_newbcast:0 row_mask:0xf bank_mask:0xf
	v_fmac_f32_dpp v225, v206, v93 row_newbcast:1 row_mask:0xf bank_mask:0xf
	v_fmac_f32_dpp v228, v206, v94 row_newbcast:2 row_mask:0xf bank_mask:0xf
	v_fmac_f32_dpp v229, v206, v95 row_newbcast:3 row_mask:0xf bank_mask:0xf
	v_fmac_f32_dpp v105, v206, v96 row_newbcast:4 row_mask:0xf bank_mask:0xf
	v_fmac_f32_dpp v225, v206, v97 row_newbcast:5 row_mask:0xf bank_mask:0xf
	v_fmac_f32_dpp v228, v206, v98 row_newbcast:6 row_mask:0xf bank_mask:0xf
	v_fmac_f32_dpp v229, v206, v99 row_newbcast:7 row_mask:0xf bank_mask:0xf
	v_fmac_f32_dpp v105, v206, v100 row_newbcast:8 row_mask:0xf bank_mask:0xf
	v_fmac_f32_dpp v225, v206, v101 row_newbcast:9 row_mask:0xf bank_mask:0xf
	v_fmac_f32_dpp v228, v206, v102 row_newbcast:10 row_mask:0xf bank_mask:0xf
	v_fmac_f32_dpp v229, v206, v103 row_newbcast:11 row_mask:0xf bank_mask:0xf
	v_fmac_f32_dpp v105, v206, v104 row_newbcast:12 row_mask:0xf bank_mask:0xf
	v_add_f32_e32 v105, v105, v225
	v_add_f32_e32 v228, v228, v229
	v_add_f32_e32 v105, v105, v228
	ds_read_b32 v206, v232 offset:13456
	s_waitcnt lgkmcnt(11)
	v_fmac_f32_dpp v185, v207, v18 row_newbcast:0 row_mask:0xf bank_mask:0xf
	v_mul_f32_dpp v222, v207, v19 row_newbcast:1 row_mask:0xf bank_mask:0xf
	v_mul_f32_dpp v223, v207, v20 row_newbcast:2 row_mask:0xf bank_mask:0xf
	v_mul_f32_dpp v224, v207, v21 row_newbcast:3 row_mask:0xf bank_mask:0xf
	v_fmac_f32_dpp v185, v207, v22 row_newbcast:4 row_mask:0xf bank_mask:0xf
	v_fmac_f32_dpp v222, v207, v24 row_newbcast:5 row_mask:0xf bank_mask:0xf
	v_fmac_f32_dpp v223, v207, v25 row_newbcast:6 row_mask:0xf bank_mask:0xf
	v_fmac_f32_dpp v224, v207, v26 row_newbcast:7 row_mask:0xf bank_mask:0xf
	v_fmac_f32_dpp v185, v207, v27 row_newbcast:8 row_mask:0xf bank_mask:0xf
	v_fmac_f32_dpp v222, v207, v28 row_newbcast:9 row_mask:0xf bank_mask:0xf
	v_fmac_f32_dpp v223, v207, v29 row_newbcast:10 row_mask:0xf bank_mask:0xf
	v_fmac_f32_dpp v224, v207, v30 row_newbcast:11 row_mask:0xf bank_mask:0xf
	v_fmac_f32_dpp v185, v207, v31 row_newbcast:12 row_mask:0xf bank_mask:0xf
	v_fmac_f32_dpp v222, v207, v32 row_newbcast:13 row_mask:0xf bank_mask:0xf
	v_fmac_f32_dpp v223, v207, v33 row_newbcast:14 row_mask:0xf bank_mask:0xf
	v_fmac_f32_dpp v224, v207, v34 row_newbcast:15 row_mask:0xf bank_mask:0xf
	ds_read_b32 v207, v232 offset:13520
	s_waitcnt lgkmcnt(11)
	v_fmac_f32_dpp v185, v208, v35 row_newbcast:0 row_mask:0xf bank_mask:0xf
	v_fmac_f32_dpp v222, v208, v36 row_newbcast:1 row_mask:0xf bank_mask:0xf
	v_fmac_f32_dpp v223, v208, v37 row_newbcast:2 row_mask:0xf bank_mask:0xf
	v_fmac_f32_dpp v224, v208, v38 row_newbcast:3 row_mask:0xf bank_mask:0xf
	v_fmac_f32_dpp v185, v208, v39 row_newbcast:4 row_mask:0xf bank_mask:0xf
	v_fmac_f32_dpp v222, v208, v40 row_newbcast:5 row_mask:0xf bank_mask:0xf
	v_fmac_f32_dpp v223, v208, v41 row_newbcast:6 row_mask:0xf bank_mask:0xf
	v_fmac_f32_dpp v224, v208, v42 row_newbcast:7 row_mask:0xf bank_mask:0xf
	v_fmac_f32_dpp v185, v208, v43 row_newbcast:8 row_mask:0xf bank_mask:0xf
	v_fmac_f32_dpp v222, v208, v44 row_newbcast:9 row_mask:0xf bank_mask:0xf
	v_fmac_f32_dpp v223, v208, v45 row_newbcast:10 row_mask:0xf bank_mask:0xf
	v_fmac_f32_dpp v224, v208, v46 row_newbcast:11 row_mask:0xf bank_mask:0xf
	v_fmac_f32_dpp v185, v208, v47 row_newbcast:12 row_mask:0xf bank_mask:0xf
	v_fmac_f32_dpp v222, v208, v48 row_newbcast:13 row_mask:0xf bank_mask:0xf
	v_fmac_f32_dpp v223, v208, v49 row_newbcast:14 row_mask:0xf bank_mask:0xf
	v_fmac_f32_dpp v224, v208, v91 row_newbcast:15 row_mask:0xf bank_mask:0xf
	ds_read_b32 v208, v232 offset:13600
	s_waitcnt lgkmcnt(11)
	v_fmac_f32_dpp v185, v209, v92 row_newbcast:0 row_mask:0xf bank_mask:0xf
	v_fmac_f32_dpp v222, v209, v93 row_newbcast:1 row_mask:0xf bank_mask:0xf
	v_fmac_f32_dpp v223, v209, v94 row_newbcast:2 row_mask:0xf bank_mask:0xf
	v_fmac_f32_dpp v224, v209, v95 row_newbcast:3 row_mask:0xf bank_mask:0xf
	v_fmac_f32_dpp v185, v209, v96 row_newbcast:4 row_mask:0xf bank_mask:0xf
	v_fmac_f32_dpp v222, v209, v97 row_newbcast:5 row_mask:0xf bank_mask:0xf
	v_fmac_f32_dpp v223, v209, v98 row_newbcast:6 row_mask:0xf bank_mask:0xf
	v_fmac_f32_dpp v224, v209, v99 row_newbcast:7 row_mask:0xf bank_mask:0xf
	v_fmac_f32_dpp v185, v209, v100 row_newbcast:8 row_mask:0xf bank_mask:0xf
	v_fmac_f32_dpp v222, v209, v101 row_newbcast:9 row_mask:0xf bank_mask:0xf
	v_fmac_f32_dpp v223, v209, v102 row_newbcast:10 row_mask:0xf bank_mask:0xf
	v_fmac_f32_dpp v224, v209, v103 row_newbcast:11 row_mask:0xf bank_mask:0xf
	v_fmac_f32_dpp v185, v209, v104 row_newbcast:12 row_mask:0xf bank_mask:0xf
	v_fmac_f32_dpp v222, v209, v105 row_newbcast:13 row_mask:0xf bank_mask:0xf
	v_add_f32_e32 v185, v185, v222
	v_add_f32_e32 v223, v223, v224
	v_add_f32_e32 v185, v185, v223
	ds_read_b32 v209, v232 offset:13664
	s_waitcnt lgkmcnt(11)
	v_fmac_f32_dpp v186, v210, v18 row_newbcast:0 row_mask:0xf bank_mask:0xf
	v_mul_f32_dpp v225, v210, v19 row_newbcast:1 row_mask:0xf bank_mask:0xf
	v_mul_f32_dpp v228, v210, v20 row_newbcast:2 row_mask:0xf bank_mask:0xf
	v_mul_f32_dpp v229, v210, v21 row_newbcast:3 row_mask:0xf bank_mask:0xf
	v_fmac_f32_dpp v186, v210, v22 row_newbcast:4 row_mask:0xf bank_mask:0xf
	v_fmac_f32_dpp v225, v210, v24 row_newbcast:5 row_mask:0xf bank_mask:0xf
	v_fmac_f32_dpp v228, v210, v25 row_newbcast:6 row_mask:0xf bank_mask:0xf
	v_fmac_f32_dpp v229, v210, v26 row_newbcast:7 row_mask:0xf bank_mask:0xf
	v_fmac_f32_dpp v186, v210, v27 row_newbcast:8 row_mask:0xf bank_mask:0xf
	v_fmac_f32_dpp v225, v210, v28 row_newbcast:9 row_mask:0xf bank_mask:0xf
	v_fmac_f32_dpp v228, v210, v29 row_newbcast:10 row_mask:0xf bank_mask:0xf
	v_fmac_f32_dpp v229, v210, v30 row_newbcast:11 row_mask:0xf bank_mask:0xf
	v_fmac_f32_dpp v186, v210, v31 row_newbcast:12 row_mask:0xf bank_mask:0xf
	v_fmac_f32_dpp v225, v210, v32 row_newbcast:13 row_mask:0xf bank_mask:0xf
	v_fmac_f32_dpp v228, v210, v33 row_newbcast:14 row_mask:0xf bank_mask:0xf
	v_fmac_f32_dpp v229, v210, v34 row_newbcast:15 row_mask:0xf bank_mask:0xf
	ds_read_b32 v210, v232 offset:13728
	s_waitcnt lgkmcnt(11)
	v_fmac_f32_dpp v186, v211, v35 row_newbcast:0 row_mask:0xf bank_mask:0xf
	v_fmac_f32_dpp v225, v211, v36 row_newbcast:1 row_mask:0xf bank_mask:0xf
	v_fmac_f32_dpp v228, v211, v37 row_newbcast:2 row_mask:0xf bank_mask:0xf
	v_fmac_f32_dpp v229, v211, v38 row_newbcast:3 row_mask:0xf bank_mask:0xf
	v_fmac_f32_dpp v186, v211, v39 row_newbcast:4 row_mask:0xf bank_mask:0xf
	v_fmac_f32_dpp v225, v211, v40 row_newbcast:5 row_mask:0xf bank_mask:0xf
	v_fmac_f32_dpp v228, v211, v41 row_newbcast:6 row_mask:0xf bank_mask:0xf
	v_fmac_f32_dpp v229, v211, v42 row_newbcast:7 row_mask:0xf bank_mask:0xf
	v_fmac_f32_dpp v186, v211, v43 row_newbcast:8 row_mask:0xf bank_mask:0xf
	v_fmac_f32_dpp v225, v211, v44 row_newbcast:9 row_mask:0xf bank_mask:0xf
	v_fmac_f32_dpp v228, v211, v45 row_newbcast:10 row_mask:0xf bank_mask:0xf
	v_fmac_f32_dpp v229, v211, v46 row_newbcast:11 row_mask:0xf bank_mask:0xf
	v_fmac_f32_dpp v186, v211, v47 row_newbcast:12 row_mask:0xf bank_mask:0xf
	v_fmac_f32_dpp v225, v211, v48 row_newbcast:13 row_mask:0xf bank_mask:0xf
	v_fmac_f32_dpp v228, v211, v49 row_newbcast:14 row_mask:0xf bank_mask:0xf
	v_fmac_f32_dpp v229, v211, v91 row_newbcast:15 row_mask:0xf bank_mask:0xf
	ds_read_b32 v211, v232 offset:13792
	s_waitcnt lgkmcnt(11)
	v_fmac_f32_dpp v186, v212, v92 row_newbcast:0 row_mask:0xf bank_mask:0xf
	v_fmac_f32_dpp v225, v212, v93 row_newbcast:1 row_mask:0xf bank_mask:0xf
	v_fmac_f32_dpp v228, v212, v94 row_newbcast:2 row_mask:0xf bank_mask:0xf
	v_fmac_f32_dpp v229, v212, v95 row_newbcast:3 row_mask:0xf bank_mask:0xf
	v_fmac_f32_dpp v186, v212, v96 row_newbcast:4 row_mask:0xf bank_mask:0xf
	v_fmac_f32_dpp v225, v212, v97 row_newbcast:5 row_mask:0xf bank_mask:0xf
	v_fmac_f32_dpp v228, v212, v98 row_newbcast:6 row_mask:0xf bank_mask:0xf
	v_fmac_f32_dpp v229, v212, v99 row_newbcast:7 row_mask:0xf bank_mask:0xf
	v_fmac_f32_dpp v186, v212, v100 row_newbcast:8 row_mask:0xf bank_mask:0xf
	v_fmac_f32_dpp v225, v212, v101 row_newbcast:9 row_mask:0xf bank_mask:0xf
	v_fmac_f32_dpp v228, v212, v102 row_newbcast:10 row_mask:0xf bank_mask:0xf
	v_fmac_f32_dpp v229, v212, v103 row_newbcast:11 row_mask:0xf bank_mask:0xf
	v_fmac_f32_dpp v186, v212, v104 row_newbcast:12 row_mask:0xf bank_mask:0xf
	v_fmac_f32_dpp v225, v212, v105 row_newbcast:13 row_mask:0xf bank_mask:0xf
	v_fmac_f32_dpp v228, v212, v185 row_newbcast:14 row_mask:0xf bank_mask:0xf
	v_add_f32_e32 v186, v186, v225
	v_add_f32_e32 v228, v228, v229
	v_add_f32_e32 v186, v186, v228
	ds_read_b32 v212, v232 offset:13872
	s_waitcnt lgkmcnt(11)
	v_fmac_f32_dpp v187, v213, v18 row_newbcast:0 row_mask:0xf bank_mask:0xf
	v_mul_f32_dpp v222, v213, v19 row_newbcast:1 row_mask:0xf bank_mask:0xf
	v_mul_f32_dpp v223, v213, v20 row_newbcast:2 row_mask:0xf bank_mask:0xf
	v_mul_f32_dpp v224, v213, v21 row_newbcast:3 row_mask:0xf bank_mask:0xf
	v_fmac_f32_dpp v187, v213, v22 row_newbcast:4 row_mask:0xf bank_mask:0xf
	v_fmac_f32_dpp v222, v213, v24 row_newbcast:5 row_mask:0xf bank_mask:0xf
	v_fmac_f32_dpp v223, v213, v25 row_newbcast:6 row_mask:0xf bank_mask:0xf
	v_fmac_f32_dpp v224, v213, v26 row_newbcast:7 row_mask:0xf bank_mask:0xf
	v_fmac_f32_dpp v187, v213, v27 row_newbcast:8 row_mask:0xf bank_mask:0xf
	v_fmac_f32_dpp v222, v213, v28 row_newbcast:9 row_mask:0xf bank_mask:0xf
	v_fmac_f32_dpp v223, v213, v29 row_newbcast:10 row_mask:0xf bank_mask:0xf
	v_fmac_f32_dpp v224, v213, v30 row_newbcast:11 row_mask:0xf bank_mask:0xf
	v_fmac_f32_dpp v187, v213, v31 row_newbcast:12 row_mask:0xf bank_mask:0xf
	v_fmac_f32_dpp v222, v213, v32 row_newbcast:13 row_mask:0xf bank_mask:0xf
	v_fmac_f32_dpp v223, v213, v33 row_newbcast:14 row_mask:0xf bank_mask:0xf
	v_fmac_f32_dpp v224, v213, v34 row_newbcast:15 row_mask:0xf bank_mask:0xf
	ds_read_b32 v213, v232 offset:13936
	s_waitcnt lgkmcnt(11)
	v_fmac_f32_dpp v187, v214, v35 row_newbcast:0 row_mask:0xf bank_mask:0xf
	v_fmac_f32_dpp v222, v214, v36 row_newbcast:1 row_mask:0xf bank_mask:0xf
	v_fmac_f32_dpp v223, v214, v37 row_newbcast:2 row_mask:0xf bank_mask:0xf
	v_fmac_f32_dpp v224, v214, v38 row_newbcast:3 row_mask:0xf bank_mask:0xf
	v_fmac_f32_dpp v187, v214, v39 row_newbcast:4 row_mask:0xf bank_mask:0xf
	v_fmac_f32_dpp v222, v214, v40 row_newbcast:5 row_mask:0xf bank_mask:0xf
	v_fmac_f32_dpp v223, v214, v41 row_newbcast:6 row_mask:0xf bank_mask:0xf
	v_fmac_f32_dpp v224, v214, v42 row_newbcast:7 row_mask:0xf bank_mask:0xf
	v_fmac_f32_dpp v187, v214, v43 row_newbcast:8 row_mask:0xf bank_mask:0xf
	v_fmac_f32_dpp v222, v214, v44 row_newbcast:9 row_mask:0xf bank_mask:0xf
	v_fmac_f32_dpp v223, v214, v45 row_newbcast:10 row_mask:0xf bank_mask:0xf
	v_fmac_f32_dpp v224, v214, v46 row_newbcast:11 row_mask:0xf bank_mask:0xf
	v_fmac_f32_dpp v187, v214, v47 row_newbcast:12 row_mask:0xf bank_mask:0xf
	v_fmac_f32_dpp v222, v214, v48 row_newbcast:13 row_mask:0xf bank_mask:0xf
	v_fmac_f32_dpp v223, v214, v49 row_newbcast:14 row_mask:0xf bank_mask:0xf
	v_fmac_f32_dpp v224, v214, v91 row_newbcast:15 row_mask:0xf bank_mask:0xf
	ds_read_b32 v214, v232 offset:14000
	s_waitcnt lgkmcnt(11)
	v_fmac_f32_dpp v187, v215, v92 row_newbcast:0 row_mask:0xf bank_mask:0xf
	v_fmac_f32_dpp v222, v215, v93 row_newbcast:1 row_mask:0xf bank_mask:0xf
	v_fmac_f32_dpp v223, v215, v94 row_newbcast:2 row_mask:0xf bank_mask:0xf
	v_fmac_f32_dpp v224, v215, v95 row_newbcast:3 row_mask:0xf bank_mask:0xf
	v_fmac_f32_dpp v187, v215, v96 row_newbcast:4 row_mask:0xf bank_mask:0xf
	v_fmac_f32_dpp v222, v215, v97 row_newbcast:5 row_mask:0xf bank_mask:0xf
	v_fmac_f32_dpp v223, v215, v98 row_newbcast:6 row_mask:0xf bank_mask:0xf
	v_fmac_f32_dpp v224, v215, v99 row_newbcast:7 row_mask:0xf bank_mask:0xf
	v_fmac_f32_dpp v187, v215, v100 row_newbcast:8 row_mask:0xf bank_mask:0xf
	v_fmac_f32_dpp v222, v215, v101 row_newbcast:9 row_mask:0xf bank_mask:0xf
	v_fmac_f32_dpp v223, v215, v102 row_newbcast:10 row_mask:0xf bank_mask:0xf
	v_fmac_f32_dpp v224, v215, v103 row_newbcast:11 row_mask:0xf bank_mask:0xf
	v_fmac_f32_dpp v187, v215, v104 row_newbcast:12 row_mask:0xf bank_mask:0xf
	v_fmac_f32_dpp v222, v215, v105 row_newbcast:13 row_mask:0xf bank_mask:0xf
	v_fmac_f32_dpp v223, v215, v185 row_newbcast:14 row_mask:0xf bank_mask:0xf
	v_fmac_f32_dpp v224, v215, v186 row_newbcast:15 row_mask:0xf bank_mask:0xf
	v_add_f32_e32 v187, v187, v222
	v_add_f32_e32 v223, v223, v224
	v_add_f32_e32 v187, v187, v223
	ds_read_b32 v215, v232 offset:14064
	s_waitcnt lgkmcnt(11)
	v_fmac_f32_dpp v188, v204, v18 row_newbcast:0 row_mask:0xf bank_mask:0xf
	v_mul_f32_dpp v225, v204, v19 row_newbcast:1 row_mask:0xf bank_mask:0xf
	v_mul_f32_dpp v228, v204, v20 row_newbcast:2 row_mask:0xf bank_mask:0xf
	v_mul_f32_dpp v229, v204, v21 row_newbcast:3 row_mask:0xf bank_mask:0xf
	v_fmac_f32_dpp v188, v204, v22 row_newbcast:4 row_mask:0xf bank_mask:0xf
	v_fmac_f32_dpp v225, v204, v24 row_newbcast:5 row_mask:0xf bank_mask:0xf
	v_fmac_f32_dpp v228, v204, v25 row_newbcast:6 row_mask:0xf bank_mask:0xf
	v_fmac_f32_dpp v229, v204, v26 row_newbcast:7 row_mask:0xf bank_mask:0xf
	v_fmac_f32_dpp v188, v204, v27 row_newbcast:8 row_mask:0xf bank_mask:0xf
	v_fmac_f32_dpp v225, v204, v28 row_newbcast:9 row_mask:0xf bank_mask:0xf
	v_fmac_f32_dpp v228, v204, v29 row_newbcast:10 row_mask:0xf bank_mask:0xf
	v_fmac_f32_dpp v229, v204, v30 row_newbcast:11 row_mask:0xf bank_mask:0xf
	v_fmac_f32_dpp v188, v204, v31 row_newbcast:12 row_mask:0xf bank_mask:0xf
	v_fmac_f32_dpp v225, v204, v32 row_newbcast:13 row_mask:0xf bank_mask:0xf
	v_fmac_f32_dpp v228, v204, v33 row_newbcast:14 row_mask:0xf bank_mask:0xf
	v_fmac_f32_dpp v229, v204, v34 row_newbcast:15 row_mask:0xf bank_mask:0xf
	ds_read_b32 v204, v232 offset:14144
	s_waitcnt lgkmcnt(11)
	v_fmac_f32_dpp v188, v205, v35 row_newbcast:0 row_mask:0xf bank_mask:0xf
	v_fmac_f32_dpp v225, v205, v36 row_newbcast:1 row_mask:0xf bank_mask:0xf
	v_fmac_f32_dpp v228, v205, v37 row_newbcast:2 row_mask:0xf bank_mask:0xf
	v_fmac_f32_dpp v229, v205, v38 row_newbcast:3 row_mask:0xf bank_mask:0xf
	v_fmac_f32_dpp v188, v205, v39 row_newbcast:4 row_mask:0xf bank_mask:0xf
	v_fmac_f32_dpp v225, v205, v40 row_newbcast:5 row_mask:0xf bank_mask:0xf
	v_fmac_f32_dpp v228, v205, v41 row_newbcast:6 row_mask:0xf bank_mask:0xf
	v_fmac_f32_dpp v229, v205, v42 row_newbcast:7 row_mask:0xf bank_mask:0xf
	v_fmac_f32_dpp v188, v205, v43 row_newbcast:8 row_mask:0xf bank_mask:0xf
	v_fmac_f32_dpp v225, v205, v44 row_newbcast:9 row_mask:0xf bank_mask:0xf
	v_fmac_f32_dpp v228, v205, v45 row_newbcast:10 row_mask:0xf bank_mask:0xf
	v_fmac_f32_dpp v229, v205, v46 row_newbcast:11 row_mask:0xf bank_mask:0xf
	v_fmac_f32_dpp v188, v205, v47 row_newbcast:12 row_mask:0xf bank_mask:0xf
	v_fmac_f32_dpp v225, v205, v48 row_newbcast:13 row_mask:0xf bank_mask:0xf
	v_fmac_f32_dpp v228, v205, v49 row_newbcast:14 row_mask:0xf bank_mask:0xf
	v_fmac_f32_dpp v229, v205, v91 row_newbcast:15 row_mask:0xf bank_mask:0xf
	ds_read_b32 v205, v232 offset:14208
	s_waitcnt lgkmcnt(11)
	v_fmac_f32_dpp v188, v206, v92 row_newbcast:0 row_mask:0xf bank_mask:0xf
	v_fmac_f32_dpp v225, v206, v93 row_newbcast:1 row_mask:0xf bank_mask:0xf
	v_fmac_f32_dpp v228, v206, v94 row_newbcast:2 row_mask:0xf bank_mask:0xf
	v_fmac_f32_dpp v229, v206, v95 row_newbcast:3 row_mask:0xf bank_mask:0xf
	v_fmac_f32_dpp v188, v206, v96 row_newbcast:4 row_mask:0xf bank_mask:0xf
	v_fmac_f32_dpp v225, v206, v97 row_newbcast:5 row_mask:0xf bank_mask:0xf
	v_fmac_f32_dpp v228, v206, v98 row_newbcast:6 row_mask:0xf bank_mask:0xf
	v_fmac_f32_dpp v229, v206, v99 row_newbcast:7 row_mask:0xf bank_mask:0xf
	v_fmac_f32_dpp v188, v206, v100 row_newbcast:8 row_mask:0xf bank_mask:0xf
	v_fmac_f32_dpp v225, v206, v101 row_newbcast:9 row_mask:0xf bank_mask:0xf
	v_fmac_f32_dpp v228, v206, v102 row_newbcast:10 row_mask:0xf bank_mask:0xf
	v_fmac_f32_dpp v229, v206, v103 row_newbcast:11 row_mask:0xf bank_mask:0xf
	v_fmac_f32_dpp v188, v206, v104 row_newbcast:12 row_mask:0xf bank_mask:0xf
	v_fmac_f32_dpp v225, v206, v105 row_newbcast:13 row_mask:0xf bank_mask:0xf
	v_fmac_f32_dpp v228, v206, v185 row_newbcast:14 row_mask:0xf bank_mask:0xf
	v_fmac_f32_dpp v229, v206, v186 row_newbcast:15 row_mask:0xf bank_mask:0xf
	ds_read_b32 v206, v232 offset:14272
	s_waitcnt lgkmcnt(11)
	v_fmac_f32_dpp v188, v207, v187 row_newbcast:0 row_mask:0xf bank_mask:0xf
	v_add_f32_e32 v188, v188, v225
	v_add_f32_e32 v228, v228, v229
	v_add_f32_e32 v188, v188, v228
	ds_read_b32 v207, v232 offset:14336
	s_waitcnt lgkmcnt(11)
	v_fmac_f32_dpp v189, v208, v18 row_newbcast:0 row_mask:0xf bank_mask:0xf
	v_mul_f32_dpp v222, v208, v19 row_newbcast:1 row_mask:0xf bank_mask:0xf
	v_mul_f32_dpp v223, v208, v20 row_newbcast:2 row_mask:0xf bank_mask:0xf
	v_mul_f32_dpp v224, v208, v21 row_newbcast:3 row_mask:0xf bank_mask:0xf
	v_fmac_f32_dpp v189, v208, v22 row_newbcast:4 row_mask:0xf bank_mask:0xf
	v_fmac_f32_dpp v222, v208, v24 row_newbcast:5 row_mask:0xf bank_mask:0xf
	v_fmac_f32_dpp v223, v208, v25 row_newbcast:6 row_mask:0xf bank_mask:0xf
	v_fmac_f32_dpp v224, v208, v26 row_newbcast:7 row_mask:0xf bank_mask:0xf
	v_fmac_f32_dpp v189, v208, v27 row_newbcast:8 row_mask:0xf bank_mask:0xf
	v_fmac_f32_dpp v222, v208, v28 row_newbcast:9 row_mask:0xf bank_mask:0xf
	v_fmac_f32_dpp v223, v208, v29 row_newbcast:10 row_mask:0xf bank_mask:0xf
	v_fmac_f32_dpp v224, v208, v30 row_newbcast:11 row_mask:0xf bank_mask:0xf
	v_fmac_f32_dpp v189, v208, v31 row_newbcast:12 row_mask:0xf bank_mask:0xf
	v_fmac_f32_dpp v222, v208, v32 row_newbcast:13 row_mask:0xf bank_mask:0xf
	v_fmac_f32_dpp v223, v208, v33 row_newbcast:14 row_mask:0xf bank_mask:0xf
	v_fmac_f32_dpp v224, v208, v34 row_newbcast:15 row_mask:0xf bank_mask:0xf
	ds_read_b32 v208, v232 offset:14416
	s_waitcnt lgkmcnt(11)
	v_fmac_f32_dpp v189, v209, v35 row_newbcast:0 row_mask:0xf bank_mask:0xf
	v_fmac_f32_dpp v222, v209, v36 row_newbcast:1 row_mask:0xf bank_mask:0xf
	v_fmac_f32_dpp v223, v209, v37 row_newbcast:2 row_mask:0xf bank_mask:0xf
	v_fmac_f32_dpp v224, v209, v38 row_newbcast:3 row_mask:0xf bank_mask:0xf
	v_fmac_f32_dpp v189, v209, v39 row_newbcast:4 row_mask:0xf bank_mask:0xf
	v_fmac_f32_dpp v222, v209, v40 row_newbcast:5 row_mask:0xf bank_mask:0xf
	v_fmac_f32_dpp v223, v209, v41 row_newbcast:6 row_mask:0xf bank_mask:0xf
	v_fmac_f32_dpp v224, v209, v42 row_newbcast:7 row_mask:0xf bank_mask:0xf
	v_fmac_f32_dpp v189, v209, v43 row_newbcast:8 row_mask:0xf bank_mask:0xf
	v_fmac_f32_dpp v222, v209, v44 row_newbcast:9 row_mask:0xf bank_mask:0xf
	v_fmac_f32_dpp v223, v209, v45 row_newbcast:10 row_mask:0xf bank_mask:0xf
	v_fmac_f32_dpp v224, v209, v46 row_newbcast:11 row_mask:0xf bank_mask:0xf
	v_fmac_f32_dpp v189, v209, v47 row_newbcast:12 row_mask:0xf bank_mask:0xf
	v_fmac_f32_dpp v222, v209, v48 row_newbcast:13 row_mask:0xf bank_mask:0xf
	v_fmac_f32_dpp v223, v209, v49 row_newbcast:14 row_mask:0xf bank_mask:0xf
	v_fmac_f32_dpp v224, v209, v91 row_newbcast:15 row_mask:0xf bank_mask:0xf
	ds_read_b32 v209, v232 offset:14480
	s_waitcnt lgkmcnt(11)
	v_fmac_f32_dpp v189, v210, v92 row_newbcast:0 row_mask:0xf bank_mask:0xf
	v_fmac_f32_dpp v222, v210, v93 row_newbcast:1 row_mask:0xf bank_mask:0xf
	v_fmac_f32_dpp v223, v210, v94 row_newbcast:2 row_mask:0xf bank_mask:0xf
	v_fmac_f32_dpp v224, v210, v95 row_newbcast:3 row_mask:0xf bank_mask:0xf
	v_fmac_f32_dpp v189, v210, v96 row_newbcast:4 row_mask:0xf bank_mask:0xf
	v_fmac_f32_dpp v222, v210, v97 row_newbcast:5 row_mask:0xf bank_mask:0xf
	v_fmac_f32_dpp v223, v210, v98 row_newbcast:6 row_mask:0xf bank_mask:0xf
	v_fmac_f32_dpp v224, v210, v99 row_newbcast:7 row_mask:0xf bank_mask:0xf
	v_fmac_f32_dpp v189, v210, v100 row_newbcast:8 row_mask:0xf bank_mask:0xf
	v_fmac_f32_dpp v222, v210, v101 row_newbcast:9 row_mask:0xf bank_mask:0xf
	v_fmac_f32_dpp v223, v210, v102 row_newbcast:10 row_mask:0xf bank_mask:0xf
	v_fmac_f32_dpp v224, v210, v103 row_newbcast:11 row_mask:0xf bank_mask:0xf
	v_fmac_f32_dpp v189, v210, v104 row_newbcast:12 row_mask:0xf bank_mask:0xf
	v_fmac_f32_dpp v222, v210, v105 row_newbcast:13 row_mask:0xf bank_mask:0xf
	v_fmac_f32_dpp v223, v210, v185 row_newbcast:14 row_mask:0xf bank_mask:0xf
	v_fmac_f32_dpp v224, v210, v186 row_newbcast:15 row_mask:0xf bank_mask:0xf
	ds_read_b32 v210, v232 offset:14544
	s_waitcnt lgkmcnt(11)
	v_fmac_f32_dpp v189, v211, v187 row_newbcast:0 row_mask:0xf bank_mask:0xf
	v_fmac_f32_dpp v222, v211, v188 row_newbcast:1 row_mask:0xf bank_mask:0xf
	v_add_f32_e32 v189, v189, v222
	v_add_f32_e32 v223, v223, v224
	v_add_f32_e32 v189, v189, v223
	ds_read_b32 v211, v232 offset:14608
	s_waitcnt lgkmcnt(11)
	v_fmac_f32_dpp v190, v212, v18 row_newbcast:0 row_mask:0xf bank_mask:0xf
	v_mul_f32_dpp v225, v212, v19 row_newbcast:1 row_mask:0xf bank_mask:0xf
	v_mul_f32_dpp v228, v212, v20 row_newbcast:2 row_mask:0xf bank_mask:0xf
	v_mul_f32_dpp v229, v212, v21 row_newbcast:3 row_mask:0xf bank_mask:0xf
	v_fmac_f32_dpp v190, v212, v22 row_newbcast:4 row_mask:0xf bank_mask:0xf
	v_fmac_f32_dpp v225, v212, v24 row_newbcast:5 row_mask:0xf bank_mask:0xf
	v_fmac_f32_dpp v228, v212, v25 row_newbcast:6 row_mask:0xf bank_mask:0xf
	v_fmac_f32_dpp v229, v212, v26 row_newbcast:7 row_mask:0xf bank_mask:0xf
	v_fmac_f32_dpp v190, v212, v27 row_newbcast:8 row_mask:0xf bank_mask:0xf
	v_fmac_f32_dpp v225, v212, v28 row_newbcast:9 row_mask:0xf bank_mask:0xf
	v_fmac_f32_dpp v228, v212, v29 row_newbcast:10 row_mask:0xf bank_mask:0xf
	v_fmac_f32_dpp v229, v212, v30 row_newbcast:11 row_mask:0xf bank_mask:0xf
	v_fmac_f32_dpp v190, v212, v31 row_newbcast:12 row_mask:0xf bank_mask:0xf
	v_fmac_f32_dpp v225, v212, v32 row_newbcast:13 row_mask:0xf bank_mask:0xf
	v_fmac_f32_dpp v228, v212, v33 row_newbcast:14 row_mask:0xf bank_mask:0xf
	v_fmac_f32_dpp v229, v212, v34 row_newbcast:15 row_mask:0xf bank_mask:0xf
	ds_read_b32 v212, v232 offset:14688
	s_waitcnt lgkmcnt(11)
	v_fmac_f32_dpp v190, v213, v35 row_newbcast:0 row_mask:0xf bank_mask:0xf
	v_fmac_f32_dpp v225, v213, v36 row_newbcast:1 row_mask:0xf bank_mask:0xf
	v_fmac_f32_dpp v228, v213, v37 row_newbcast:2 row_mask:0xf bank_mask:0xf
	v_fmac_f32_dpp v229, v213, v38 row_newbcast:3 row_mask:0xf bank_mask:0xf
	v_fmac_f32_dpp v190, v213, v39 row_newbcast:4 row_mask:0xf bank_mask:0xf
	v_fmac_f32_dpp v225, v213, v40 row_newbcast:5 row_mask:0xf bank_mask:0xf
	v_fmac_f32_dpp v228, v213, v41 row_newbcast:6 row_mask:0xf bank_mask:0xf
	v_fmac_f32_dpp v229, v213, v42 row_newbcast:7 row_mask:0xf bank_mask:0xf
	v_fmac_f32_dpp v190, v213, v43 row_newbcast:8 row_mask:0xf bank_mask:0xf
	v_fmac_f32_dpp v225, v213, v44 row_newbcast:9 row_mask:0xf bank_mask:0xf
	v_fmac_f32_dpp v228, v213, v45 row_newbcast:10 row_mask:0xf bank_mask:0xf
	v_fmac_f32_dpp v229, v213, v46 row_newbcast:11 row_mask:0xf bank_mask:0xf
	v_fmac_f32_dpp v190, v213, v47 row_newbcast:12 row_mask:0xf bank_mask:0xf
	v_fmac_f32_dpp v225, v213, v48 row_newbcast:13 row_mask:0xf bank_mask:0xf
	v_fmac_f32_dpp v228, v213, v49 row_newbcast:14 row_mask:0xf bank_mask:0xf
	v_fmac_f32_dpp v229, v213, v91 row_newbcast:15 row_mask:0xf bank_mask:0xf
	ds_read_b32 v213, v232 offset:14752
	s_waitcnt lgkmcnt(11)
	v_fmac_f32_dpp v190, v214, v92 row_newbcast:0 row_mask:0xf bank_mask:0xf
	v_fmac_f32_dpp v225, v214, v93 row_newbcast:1 row_mask:0xf bank_mask:0xf
	v_fmac_f32_dpp v228, v214, v94 row_newbcast:2 row_mask:0xf bank_mask:0xf
	v_fmac_f32_dpp v229, v214, v95 row_newbcast:3 row_mask:0xf bank_mask:0xf
	v_fmac_f32_dpp v190, v214, v96 row_newbcast:4 row_mask:0xf bank_mask:0xf
	v_fmac_f32_dpp v225, v214, v97 row_newbcast:5 row_mask:0xf bank_mask:0xf
	v_fmac_f32_dpp v228, v214, v98 row_newbcast:6 row_mask:0xf bank_mask:0xf
	v_fmac_f32_dpp v229, v214, v99 row_newbcast:7 row_mask:0xf bank_mask:0xf
	v_fmac_f32_dpp v190, v214, v100 row_newbcast:8 row_mask:0xf bank_mask:0xf
	v_fmac_f32_dpp v225, v214, v101 row_newbcast:9 row_mask:0xf bank_mask:0xf
	v_fmac_f32_dpp v228, v214, v102 row_newbcast:10 row_mask:0xf bank_mask:0xf
	v_fmac_f32_dpp v229, v214, v103 row_newbcast:11 row_mask:0xf bank_mask:0xf
	v_fmac_f32_dpp v190, v214, v104 row_newbcast:12 row_mask:0xf bank_mask:0xf
	v_fmac_f32_dpp v225, v214, v105 row_newbcast:13 row_mask:0xf bank_mask:0xf
	v_fmac_f32_dpp v228, v214, v185 row_newbcast:14 row_mask:0xf bank_mask:0xf
	v_fmac_f32_dpp v229, v214, v186 row_newbcast:15 row_mask:0xf bank_mask:0xf
	ds_read_b32 v214, v232 offset:14816
	s_waitcnt lgkmcnt(11)
	v_fmac_f32_dpp v190, v215, v187 row_newbcast:0 row_mask:0xf bank_mask:0xf
	v_fmac_f32_dpp v225, v215, v188 row_newbcast:1 row_mask:0xf bank_mask:0xf
	v_fmac_f32_dpp v228, v215, v189 row_newbcast:2 row_mask:0xf bank_mask:0xf
	v_add_f32_e32 v190, v190, v225
	v_add_f32_e32 v228, v228, v229
	v_add_f32_e32 v190, v190, v228
	ds_read_b32 v215, v232 offset:14880
	s_waitcnt lgkmcnt(11)
	v_fmac_f32_dpp v192, v204, v18 row_newbcast:0 row_mask:0xf bank_mask:0xf
	v_mul_f32_dpp v222, v204, v19 row_newbcast:1 row_mask:0xf bank_mask:0xf
	v_mul_f32_dpp v223, v204, v20 row_newbcast:2 row_mask:0xf bank_mask:0xf
	v_mul_f32_dpp v224, v204, v21 row_newbcast:3 row_mask:0xf bank_mask:0xf
	v_fmac_f32_dpp v192, v204, v22 row_newbcast:4 row_mask:0xf bank_mask:0xf
	v_fmac_f32_dpp v222, v204, v24 row_newbcast:5 row_mask:0xf bank_mask:0xf
	v_fmac_f32_dpp v223, v204, v25 row_newbcast:6 row_mask:0xf bank_mask:0xf
	v_fmac_f32_dpp v224, v204, v26 row_newbcast:7 row_mask:0xf bank_mask:0xf
	v_fmac_f32_dpp v192, v204, v27 row_newbcast:8 row_mask:0xf bank_mask:0xf
	v_fmac_f32_dpp v222, v204, v28 row_newbcast:9 row_mask:0xf bank_mask:0xf
	v_fmac_f32_dpp v223, v204, v29 row_newbcast:10 row_mask:0xf bank_mask:0xf
	v_fmac_f32_dpp v224, v204, v30 row_newbcast:11 row_mask:0xf bank_mask:0xf
	v_fmac_f32_dpp v192, v204, v31 row_newbcast:12 row_mask:0xf bank_mask:0xf
	v_fmac_f32_dpp v222, v204, v32 row_newbcast:13 row_mask:0xf bank_mask:0xf
	v_fmac_f32_dpp v223, v204, v33 row_newbcast:14 row_mask:0xf bank_mask:0xf
	v_fmac_f32_dpp v224, v204, v34 row_newbcast:15 row_mask:0xf bank_mask:0xf
	ds_read_b32 v204, v232 offset:14960
	s_waitcnt lgkmcnt(11)
	v_fmac_f32_dpp v192, v205, v35 row_newbcast:0 row_mask:0xf bank_mask:0xf
	v_fmac_f32_dpp v222, v205, v36 row_newbcast:1 row_mask:0xf bank_mask:0xf
	v_fmac_f32_dpp v223, v205, v37 row_newbcast:2 row_mask:0xf bank_mask:0xf
	v_fmac_f32_dpp v224, v205, v38 row_newbcast:3 row_mask:0xf bank_mask:0xf
	v_fmac_f32_dpp v192, v205, v39 row_newbcast:4 row_mask:0xf bank_mask:0xf
	v_fmac_f32_dpp v222, v205, v40 row_newbcast:5 row_mask:0xf bank_mask:0xf
	v_fmac_f32_dpp v223, v205, v41 row_newbcast:6 row_mask:0xf bank_mask:0xf
	v_fmac_f32_dpp v224, v205, v42 row_newbcast:7 row_mask:0xf bank_mask:0xf
	v_fmac_f32_dpp v192, v205, v43 row_newbcast:8 row_mask:0xf bank_mask:0xf
	v_fmac_f32_dpp v222, v205, v44 row_newbcast:9 row_mask:0xf bank_mask:0xf
	v_fmac_f32_dpp v223, v205, v45 row_newbcast:10 row_mask:0xf bank_mask:0xf
	v_fmac_f32_dpp v224, v205, v46 row_newbcast:11 row_mask:0xf bank_mask:0xf
	v_fmac_f32_dpp v192, v205, v47 row_newbcast:12 row_mask:0xf bank_mask:0xf
	v_fmac_f32_dpp v222, v205, v48 row_newbcast:13 row_mask:0xf bank_mask:0xf
	v_fmac_f32_dpp v223, v205, v49 row_newbcast:14 row_mask:0xf bank_mask:0xf
	v_fmac_f32_dpp v224, v205, v91 row_newbcast:15 row_mask:0xf bank_mask:0xf
	ds_read_b32 v205, v232 offset:15024
	s_waitcnt lgkmcnt(11)
	v_fmac_f32_dpp v192, v206, v92 row_newbcast:0 row_mask:0xf bank_mask:0xf
	v_fmac_f32_dpp v222, v206, v93 row_newbcast:1 row_mask:0xf bank_mask:0xf
	v_fmac_f32_dpp v223, v206, v94 row_newbcast:2 row_mask:0xf bank_mask:0xf
	v_fmac_f32_dpp v224, v206, v95 row_newbcast:3 row_mask:0xf bank_mask:0xf
	v_fmac_f32_dpp v192, v206, v96 row_newbcast:4 row_mask:0xf bank_mask:0xf
	v_fmac_f32_dpp v222, v206, v97 row_newbcast:5 row_mask:0xf bank_mask:0xf
	v_fmac_f32_dpp v223, v206, v98 row_newbcast:6 row_mask:0xf bank_mask:0xf
	v_fmac_f32_dpp v224, v206, v99 row_newbcast:7 row_mask:0xf bank_mask:0xf
	v_fmac_f32_dpp v192, v206, v100 row_newbcast:8 row_mask:0xf bank_mask:0xf
	v_fmac_f32_dpp v222, v206, v101 row_newbcast:9 row_mask:0xf bank_mask:0xf
	v_fmac_f32_dpp v223, v206, v102 row_newbcast:10 row_mask:0xf bank_mask:0xf
	v_fmac_f32_dpp v224, v206, v103 row_newbcast:11 row_mask:0xf bank_mask:0xf
	v_fmac_f32_dpp v192, v206, v104 row_newbcast:12 row_mask:0xf bank_mask:0xf
	v_fmac_f32_dpp v222, v206, v105 row_newbcast:13 row_mask:0xf bank_mask:0xf
	v_fmac_f32_dpp v223, v206, v185 row_newbcast:14 row_mask:0xf bank_mask:0xf
	v_fmac_f32_dpp v224, v206, v186 row_newbcast:15 row_mask:0xf bank_mask:0xf
	ds_read_b32 v206, v232 offset:15088
	s_waitcnt lgkmcnt(11)
	v_fmac_f32_dpp v192, v207, v187 row_newbcast:0 row_mask:0xf bank_mask:0xf
	v_fmac_f32_dpp v222, v207, v188 row_newbcast:1 row_mask:0xf bank_mask:0xf
	v_fmac_f32_dpp v223, v207, v189 row_newbcast:2 row_mask:0xf bank_mask:0xf
	v_fmac_f32_dpp v224, v207, v190 row_newbcast:3 row_mask:0xf bank_mask:0xf
	v_add_f32_e32 v192, v192, v222
	v_add_f32_e32 v223, v223, v224
	v_add_f32_e32 v192, v192, v223
	ds_read_b32 v207, v232 offset:15152
	s_waitcnt lgkmcnt(11)
	v_fmac_f32_dpp v193, v208, v18 row_newbcast:0 row_mask:0xf bank_mask:0xf
	v_mul_f32_dpp v225, v208, v19 row_newbcast:1 row_mask:0xf bank_mask:0xf
	v_mul_f32_dpp v228, v208, v20 row_newbcast:2 row_mask:0xf bank_mask:0xf
	v_mul_f32_dpp v229, v208, v21 row_newbcast:3 row_mask:0xf bank_mask:0xf
	v_fmac_f32_dpp v193, v208, v22 row_newbcast:4 row_mask:0xf bank_mask:0xf
	v_fmac_f32_dpp v225, v208, v24 row_newbcast:5 row_mask:0xf bank_mask:0xf
	v_fmac_f32_dpp v228, v208, v25 row_newbcast:6 row_mask:0xf bank_mask:0xf
	v_fmac_f32_dpp v229, v208, v26 row_newbcast:7 row_mask:0xf bank_mask:0xf
	v_fmac_f32_dpp v193, v208, v27 row_newbcast:8 row_mask:0xf bank_mask:0xf
	v_fmac_f32_dpp v225, v208, v28 row_newbcast:9 row_mask:0xf bank_mask:0xf
	v_fmac_f32_dpp v228, v208, v29 row_newbcast:10 row_mask:0xf bank_mask:0xf
	v_fmac_f32_dpp v229, v208, v30 row_newbcast:11 row_mask:0xf bank_mask:0xf
	v_fmac_f32_dpp v193, v208, v31 row_newbcast:12 row_mask:0xf bank_mask:0xf
	v_fmac_f32_dpp v225, v208, v32 row_newbcast:13 row_mask:0xf bank_mask:0xf
	v_fmac_f32_dpp v228, v208, v33 row_newbcast:14 row_mask:0xf bank_mask:0xf
	v_fmac_f32_dpp v229, v208, v34 row_newbcast:15 row_mask:0xf bank_mask:0xf
	ds_read_b32 v208, v232 offset:15232
	s_waitcnt lgkmcnt(11)
	v_fmac_f32_dpp v193, v209, v35 row_newbcast:0 row_mask:0xf bank_mask:0xf
	v_fmac_f32_dpp v225, v209, v36 row_newbcast:1 row_mask:0xf bank_mask:0xf
	v_fmac_f32_dpp v228, v209, v37 row_newbcast:2 row_mask:0xf bank_mask:0xf
	v_fmac_f32_dpp v229, v209, v38 row_newbcast:3 row_mask:0xf bank_mask:0xf
	v_fmac_f32_dpp v193, v209, v39 row_newbcast:4 row_mask:0xf bank_mask:0xf
	v_fmac_f32_dpp v225, v209, v40 row_newbcast:5 row_mask:0xf bank_mask:0xf
	v_fmac_f32_dpp v228, v209, v41 row_newbcast:6 row_mask:0xf bank_mask:0xf
	v_fmac_f32_dpp v229, v209, v42 row_newbcast:7 row_mask:0xf bank_mask:0xf
	v_fmac_f32_dpp v193, v209, v43 row_newbcast:8 row_mask:0xf bank_mask:0xf
	v_fmac_f32_dpp v225, v209, v44 row_newbcast:9 row_mask:0xf bank_mask:0xf
	v_fmac_f32_dpp v228, v209, v45 row_newbcast:10 row_mask:0xf bank_mask:0xf
	v_fmac_f32_dpp v229, v209, v46 row_newbcast:11 row_mask:0xf bank_mask:0xf
	v_fmac_f32_dpp v193, v209, v47 row_newbcast:12 row_mask:0xf bank_mask:0xf
	v_fmac_f32_dpp v225, v209, v48 row_newbcast:13 row_mask:0xf bank_mask:0xf
	v_fmac_f32_dpp v228, v209, v49 row_newbcast:14 row_mask:0xf bank_mask:0xf
	v_fmac_f32_dpp v229, v209, v91 row_newbcast:15 row_mask:0xf bank_mask:0xf
	ds_read_b32 v209, v232 offset:15296
	s_waitcnt lgkmcnt(11)
	v_fmac_f32_dpp v193, v210, v92 row_newbcast:0 row_mask:0xf bank_mask:0xf
	v_fmac_f32_dpp v225, v210, v93 row_newbcast:1 row_mask:0xf bank_mask:0xf
	v_fmac_f32_dpp v228, v210, v94 row_newbcast:2 row_mask:0xf bank_mask:0xf
	v_fmac_f32_dpp v229, v210, v95 row_newbcast:3 row_mask:0xf bank_mask:0xf
	v_fmac_f32_dpp v193, v210, v96 row_newbcast:4 row_mask:0xf bank_mask:0xf
	v_fmac_f32_dpp v225, v210, v97 row_newbcast:5 row_mask:0xf bank_mask:0xf
	v_fmac_f32_dpp v228, v210, v98 row_newbcast:6 row_mask:0xf bank_mask:0xf
	v_fmac_f32_dpp v229, v210, v99 row_newbcast:7 row_mask:0xf bank_mask:0xf
	v_fmac_f32_dpp v193, v210, v100 row_newbcast:8 row_mask:0xf bank_mask:0xf
	v_fmac_f32_dpp v225, v210, v101 row_newbcast:9 row_mask:0xf bank_mask:0xf
	v_fmac_f32_dpp v228, v210, v102 row_newbcast:10 row_mask:0xf bank_mask:0xf
	v_fmac_f32_dpp v229, v210, v103 row_newbcast:11 row_mask:0xf bank_mask:0xf
	v_fmac_f32_dpp v193, v210, v104 row_newbcast:12 row_mask:0xf bank_mask:0xf
	v_fmac_f32_dpp v225, v210, v105 row_newbcast:13 row_mask:0xf bank_mask:0xf
	v_fmac_f32_dpp v228, v210, v185 row_newbcast:14 row_mask:0xf bank_mask:0xf
	v_fmac_f32_dpp v229, v210, v186 row_newbcast:15 row_mask:0xf bank_mask:0xf
	ds_read_b32 v210, v232 offset:15360
	s_waitcnt lgkmcnt(11)
	v_fmac_f32_dpp v193, v211, v187 row_newbcast:0 row_mask:0xf bank_mask:0xf
	v_fmac_f32_dpp v225, v211, v188 row_newbcast:1 row_mask:0xf bank_mask:0xf
	v_fmac_f32_dpp v228, v211, v189 row_newbcast:2 row_mask:0xf bank_mask:0xf
	v_fmac_f32_dpp v229, v211, v190 row_newbcast:3 row_mask:0xf bank_mask:0xf
	v_fmac_f32_dpp v193, v211, v192 row_newbcast:4 row_mask:0xf bank_mask:0xf
	v_add_f32_e32 v193, v193, v225
	v_add_f32_e32 v228, v228, v229
	v_add_f32_e32 v193, v193, v228
	ds_read_b32 v211, v232 offset:15424
	s_waitcnt lgkmcnt(11)
	v_fmac_f32_dpp v194, v212, v18 row_newbcast:0 row_mask:0xf bank_mask:0xf
	v_mul_f32_dpp v222, v212, v19 row_newbcast:1 row_mask:0xf bank_mask:0xf
	v_mul_f32_dpp v223, v212, v20 row_newbcast:2 row_mask:0xf bank_mask:0xf
	v_mul_f32_dpp v224, v212, v21 row_newbcast:3 row_mask:0xf bank_mask:0xf
	v_fmac_f32_dpp v194, v212, v22 row_newbcast:4 row_mask:0xf bank_mask:0xf
	v_fmac_f32_dpp v222, v212, v24 row_newbcast:5 row_mask:0xf bank_mask:0xf
	v_fmac_f32_dpp v223, v212, v25 row_newbcast:6 row_mask:0xf bank_mask:0xf
	v_fmac_f32_dpp v224, v212, v26 row_newbcast:7 row_mask:0xf bank_mask:0xf
	v_fmac_f32_dpp v194, v212, v27 row_newbcast:8 row_mask:0xf bank_mask:0xf
	v_fmac_f32_dpp v222, v212, v28 row_newbcast:9 row_mask:0xf bank_mask:0xf
	v_fmac_f32_dpp v223, v212, v29 row_newbcast:10 row_mask:0xf bank_mask:0xf
	v_fmac_f32_dpp v224, v212, v30 row_newbcast:11 row_mask:0xf bank_mask:0xf
	v_fmac_f32_dpp v194, v212, v31 row_newbcast:12 row_mask:0xf bank_mask:0xf
	v_fmac_f32_dpp v222, v212, v32 row_newbcast:13 row_mask:0xf bank_mask:0xf
	v_fmac_f32_dpp v223, v212, v33 row_newbcast:14 row_mask:0xf bank_mask:0xf
	v_fmac_f32_dpp v224, v212, v34 row_newbcast:15 row_mask:0xf bank_mask:0xf
	ds_read_b32 v212, v232 offset:15504
	s_waitcnt lgkmcnt(11)
	v_fmac_f32_dpp v194, v213, v35 row_newbcast:0 row_mask:0xf bank_mask:0xf
	v_fmac_f32_dpp v222, v213, v36 row_newbcast:1 row_mask:0xf bank_mask:0xf
	v_fmac_f32_dpp v223, v213, v37 row_newbcast:2 row_mask:0xf bank_mask:0xf
	v_fmac_f32_dpp v224, v213, v38 row_newbcast:3 row_mask:0xf bank_mask:0xf
	v_fmac_f32_dpp v194, v213, v39 row_newbcast:4 row_mask:0xf bank_mask:0xf
	v_fmac_f32_dpp v222, v213, v40 row_newbcast:5 row_mask:0xf bank_mask:0xf
	v_fmac_f32_dpp v223, v213, v41 row_newbcast:6 row_mask:0xf bank_mask:0xf
	v_fmac_f32_dpp v224, v213, v42 row_newbcast:7 row_mask:0xf bank_mask:0xf
	v_fmac_f32_dpp v194, v213, v43 row_newbcast:8 row_mask:0xf bank_mask:0xf
	v_fmac_f32_dpp v222, v213, v44 row_newbcast:9 row_mask:0xf bank_mask:0xf
	v_fmac_f32_dpp v223, v213, v45 row_newbcast:10 row_mask:0xf bank_mask:0xf
	v_fmac_f32_dpp v224, v213, v46 row_newbcast:11 row_mask:0xf bank_mask:0xf
	v_fmac_f32_dpp v194, v213, v47 row_newbcast:12 row_mask:0xf bank_mask:0xf
	v_fmac_f32_dpp v222, v213, v48 row_newbcast:13 row_mask:0xf bank_mask:0xf
	v_fmac_f32_dpp v223, v213, v49 row_newbcast:14 row_mask:0xf bank_mask:0xf
	v_fmac_f32_dpp v224, v213, v91 row_newbcast:15 row_mask:0xf bank_mask:0xf
	ds_read_b32 v213, v232 offset:15568
	s_waitcnt lgkmcnt(11)
	v_fmac_f32_dpp v194, v214, v92 row_newbcast:0 row_mask:0xf bank_mask:0xf
	v_fmac_f32_dpp v222, v214, v93 row_newbcast:1 row_mask:0xf bank_mask:0xf
	v_fmac_f32_dpp v223, v214, v94 row_newbcast:2 row_mask:0xf bank_mask:0xf
	v_fmac_f32_dpp v224, v214, v95 row_newbcast:3 row_mask:0xf bank_mask:0xf
	v_fmac_f32_dpp v194, v214, v96 row_newbcast:4 row_mask:0xf bank_mask:0xf
	v_fmac_f32_dpp v222, v214, v97 row_newbcast:5 row_mask:0xf bank_mask:0xf
	v_fmac_f32_dpp v223, v214, v98 row_newbcast:6 row_mask:0xf bank_mask:0xf
	v_fmac_f32_dpp v224, v214, v99 row_newbcast:7 row_mask:0xf bank_mask:0xf
	v_fmac_f32_dpp v194, v214, v100 row_newbcast:8 row_mask:0xf bank_mask:0xf
	v_fmac_f32_dpp v222, v214, v101 row_newbcast:9 row_mask:0xf bank_mask:0xf
	v_fmac_f32_dpp v223, v214, v102 row_newbcast:10 row_mask:0xf bank_mask:0xf
	v_fmac_f32_dpp v224, v214, v103 row_newbcast:11 row_mask:0xf bank_mask:0xf
	v_fmac_f32_dpp v194, v214, v104 row_newbcast:12 row_mask:0xf bank_mask:0xf
	v_fmac_f32_dpp v222, v214, v105 row_newbcast:13 row_mask:0xf bank_mask:0xf
	v_fmac_f32_dpp v223, v214, v185 row_newbcast:14 row_mask:0xf bank_mask:0xf
	v_fmac_f32_dpp v224, v214, v186 row_newbcast:15 row_mask:0xf bank_mask:0xf
	ds_read_b32 v214, v232 offset:15632
	s_waitcnt lgkmcnt(11)
	v_fmac_f32_dpp v194, v215, v187 row_newbcast:0 row_mask:0xf bank_mask:0xf
	v_fmac_f32_dpp v222, v215, v188 row_newbcast:1 row_mask:0xf bank_mask:0xf
	v_fmac_f32_dpp v223, v215, v189 row_newbcast:2 row_mask:0xf bank_mask:0xf
	v_fmac_f32_dpp v224, v215, v190 row_newbcast:3 row_mask:0xf bank_mask:0xf
	v_fmac_f32_dpp v194, v215, v192 row_newbcast:4 row_mask:0xf bank_mask:0xf
	v_fmac_f32_dpp v222, v215, v193 row_newbcast:5 row_mask:0xf bank_mask:0xf
	v_add_f32_e32 v194, v194, v222
	v_add_f32_e32 v223, v223, v224
	v_add_f32_e32 v194, v194, v223
	ds_read_b32 v215, v232 offset:15696
	s_waitcnt lgkmcnt(11)
	v_fmac_f32_dpp v195, v204, v18 row_newbcast:0 row_mask:0xf bank_mask:0xf
	v_mul_f32_dpp v225, v204, v19 row_newbcast:1 row_mask:0xf bank_mask:0xf
	v_mul_f32_dpp v228, v204, v20 row_newbcast:2 row_mask:0xf bank_mask:0xf
	v_mul_f32_dpp v229, v204, v21 row_newbcast:3 row_mask:0xf bank_mask:0xf
	v_fmac_f32_dpp v195, v204, v22 row_newbcast:4 row_mask:0xf bank_mask:0xf
	v_fmac_f32_dpp v225, v204, v24 row_newbcast:5 row_mask:0xf bank_mask:0xf
	v_fmac_f32_dpp v228, v204, v25 row_newbcast:6 row_mask:0xf bank_mask:0xf
	v_fmac_f32_dpp v229, v204, v26 row_newbcast:7 row_mask:0xf bank_mask:0xf
	v_fmac_f32_dpp v195, v204, v27 row_newbcast:8 row_mask:0xf bank_mask:0xf
	v_fmac_f32_dpp v225, v204, v28 row_newbcast:9 row_mask:0xf bank_mask:0xf
	v_fmac_f32_dpp v228, v204, v29 row_newbcast:10 row_mask:0xf bank_mask:0xf
	v_fmac_f32_dpp v229, v204, v30 row_newbcast:11 row_mask:0xf bank_mask:0xf
	v_fmac_f32_dpp v195, v204, v31 row_newbcast:12 row_mask:0xf bank_mask:0xf
	v_fmac_f32_dpp v225, v204, v32 row_newbcast:13 row_mask:0xf bank_mask:0xf
	v_fmac_f32_dpp v228, v204, v33 row_newbcast:14 row_mask:0xf bank_mask:0xf
	v_fmac_f32_dpp v229, v204, v34 row_newbcast:15 row_mask:0xf bank_mask:0xf
	ds_read_b32 v204, v232 offset:15776
	s_waitcnt lgkmcnt(11)
	v_fmac_f32_dpp v195, v205, v35 row_newbcast:0 row_mask:0xf bank_mask:0xf
	v_fmac_f32_dpp v225, v205, v36 row_newbcast:1 row_mask:0xf bank_mask:0xf
	v_fmac_f32_dpp v228, v205, v37 row_newbcast:2 row_mask:0xf bank_mask:0xf
	v_fmac_f32_dpp v229, v205, v38 row_newbcast:3 row_mask:0xf bank_mask:0xf
	v_fmac_f32_dpp v195, v205, v39 row_newbcast:4 row_mask:0xf bank_mask:0xf
	v_fmac_f32_dpp v225, v205, v40 row_newbcast:5 row_mask:0xf bank_mask:0xf
	v_fmac_f32_dpp v228, v205, v41 row_newbcast:6 row_mask:0xf bank_mask:0xf
	v_fmac_f32_dpp v229, v205, v42 row_newbcast:7 row_mask:0xf bank_mask:0xf
	v_fmac_f32_dpp v195, v205, v43 row_newbcast:8 row_mask:0xf bank_mask:0xf
	v_fmac_f32_dpp v225, v205, v44 row_newbcast:9 row_mask:0xf bank_mask:0xf
	v_fmac_f32_dpp v228, v205, v45 row_newbcast:10 row_mask:0xf bank_mask:0xf
	v_fmac_f32_dpp v229, v205, v46 row_newbcast:11 row_mask:0xf bank_mask:0xf
	v_fmac_f32_dpp v195, v205, v47 row_newbcast:12 row_mask:0xf bank_mask:0xf
	v_fmac_f32_dpp v225, v205, v48 row_newbcast:13 row_mask:0xf bank_mask:0xf
	v_fmac_f32_dpp v228, v205, v49 row_newbcast:14 row_mask:0xf bank_mask:0xf
	v_fmac_f32_dpp v229, v205, v91 row_newbcast:15 row_mask:0xf bank_mask:0xf
	ds_read_b32 v205, v232 offset:15840
	s_waitcnt lgkmcnt(11)
	v_fmac_f32_dpp v195, v206, v92 row_newbcast:0 row_mask:0xf bank_mask:0xf
	v_fmac_f32_dpp v225, v206, v93 row_newbcast:1 row_mask:0xf bank_mask:0xf
	v_fmac_f32_dpp v228, v206, v94 row_newbcast:2 row_mask:0xf bank_mask:0xf
	v_fmac_f32_dpp v229, v206, v95 row_newbcast:3 row_mask:0xf bank_mask:0xf
	v_fmac_f32_dpp v195, v206, v96 row_newbcast:4 row_mask:0xf bank_mask:0xf
	v_fmac_f32_dpp v225, v206, v97 row_newbcast:5 row_mask:0xf bank_mask:0xf
	v_fmac_f32_dpp v228, v206, v98 row_newbcast:6 row_mask:0xf bank_mask:0xf
	v_fmac_f32_dpp v229, v206, v99 row_newbcast:7 row_mask:0xf bank_mask:0xf
	v_fmac_f32_dpp v195, v206, v100 row_newbcast:8 row_mask:0xf bank_mask:0xf
	v_fmac_f32_dpp v225, v206, v101 row_newbcast:9 row_mask:0xf bank_mask:0xf
	v_fmac_f32_dpp v228, v206, v102 row_newbcast:10 row_mask:0xf bank_mask:0xf
	v_fmac_f32_dpp v229, v206, v103 row_newbcast:11 row_mask:0xf bank_mask:0xf
	v_fmac_f32_dpp v195, v206, v104 row_newbcast:12 row_mask:0xf bank_mask:0xf
	v_fmac_f32_dpp v225, v206, v105 row_newbcast:13 row_mask:0xf bank_mask:0xf
	v_fmac_f32_dpp v228, v206, v185 row_newbcast:14 row_mask:0xf bank_mask:0xf
	v_fmac_f32_dpp v229, v206, v186 row_newbcast:15 row_mask:0xf bank_mask:0xf
	ds_read_b32 v206, v232 offset:15904
	s_waitcnt lgkmcnt(11)
	v_fmac_f32_dpp v195, v207, v187 row_newbcast:0 row_mask:0xf bank_mask:0xf
	v_fmac_f32_dpp v225, v207, v188 row_newbcast:1 row_mask:0xf bank_mask:0xf
	v_fmac_f32_dpp v228, v207, v189 row_newbcast:2 row_mask:0xf bank_mask:0xf
	v_fmac_f32_dpp v229, v207, v190 row_newbcast:3 row_mask:0xf bank_mask:0xf
	v_fmac_f32_dpp v195, v207, v192 row_newbcast:4 row_mask:0xf bank_mask:0xf
	v_fmac_f32_dpp v225, v207, v193 row_newbcast:5 row_mask:0xf bank_mask:0xf
	v_fmac_f32_dpp v228, v207, v194 row_newbcast:6 row_mask:0xf bank_mask:0xf
	v_add_f32_e32 v195, v195, v225
	v_add_f32_e32 v228, v228, v229
	v_add_f32_e32 v195, v195, v228
	ds_read_b32 v207, v232 offset:15968
	s_waitcnt lgkmcnt(11)
	v_fmac_f32_dpp v196, v208, v18 row_newbcast:0 row_mask:0xf bank_mask:0xf
	v_mul_f32_dpp v222, v208, v19 row_newbcast:1 row_mask:0xf bank_mask:0xf
	v_mul_f32_dpp v223, v208, v20 row_newbcast:2 row_mask:0xf bank_mask:0xf
	v_mul_f32_dpp v224, v208, v21 row_newbcast:3 row_mask:0xf bank_mask:0xf
	v_fmac_f32_dpp v196, v208, v22 row_newbcast:4 row_mask:0xf bank_mask:0xf
	v_fmac_f32_dpp v222, v208, v24 row_newbcast:5 row_mask:0xf bank_mask:0xf
	v_fmac_f32_dpp v223, v208, v25 row_newbcast:6 row_mask:0xf bank_mask:0xf
	v_fmac_f32_dpp v224, v208, v26 row_newbcast:7 row_mask:0xf bank_mask:0xf
	v_fmac_f32_dpp v196, v208, v27 row_newbcast:8 row_mask:0xf bank_mask:0xf
	v_fmac_f32_dpp v222, v208, v28 row_newbcast:9 row_mask:0xf bank_mask:0xf
	v_fmac_f32_dpp v223, v208, v29 row_newbcast:10 row_mask:0xf bank_mask:0xf
	v_fmac_f32_dpp v224, v208, v30 row_newbcast:11 row_mask:0xf bank_mask:0xf
	v_fmac_f32_dpp v196, v208, v31 row_newbcast:12 row_mask:0xf bank_mask:0xf
	v_fmac_f32_dpp v222, v208, v32 row_newbcast:13 row_mask:0xf bank_mask:0xf
	v_fmac_f32_dpp v223, v208, v33 row_newbcast:14 row_mask:0xf bank_mask:0xf
	v_fmac_f32_dpp v224, v208, v34 row_newbcast:15 row_mask:0xf bank_mask:0xf
	ds_read_b32 v208, v232 offset:16048
	s_waitcnt lgkmcnt(11)
	v_fmac_f32_dpp v196, v209, v35 row_newbcast:0 row_mask:0xf bank_mask:0xf
	v_fmac_f32_dpp v222, v209, v36 row_newbcast:1 row_mask:0xf bank_mask:0xf
	v_fmac_f32_dpp v223, v209, v37 row_newbcast:2 row_mask:0xf bank_mask:0xf
	v_fmac_f32_dpp v224, v209, v38 row_newbcast:3 row_mask:0xf bank_mask:0xf
	v_fmac_f32_dpp v196, v209, v39 row_newbcast:4 row_mask:0xf bank_mask:0xf
	v_fmac_f32_dpp v222, v209, v40 row_newbcast:5 row_mask:0xf bank_mask:0xf
	v_fmac_f32_dpp v223, v209, v41 row_newbcast:6 row_mask:0xf bank_mask:0xf
	v_fmac_f32_dpp v224, v209, v42 row_newbcast:7 row_mask:0xf bank_mask:0xf
	v_fmac_f32_dpp v196, v209, v43 row_newbcast:8 row_mask:0xf bank_mask:0xf
	v_fmac_f32_dpp v222, v209, v44 row_newbcast:9 row_mask:0xf bank_mask:0xf
	v_fmac_f32_dpp v223, v209, v45 row_newbcast:10 row_mask:0xf bank_mask:0xf
	v_fmac_f32_dpp v224, v209, v46 row_newbcast:11 row_mask:0xf bank_mask:0xf
	v_fmac_f32_dpp v196, v209, v47 row_newbcast:12 row_mask:0xf bank_mask:0xf
	v_fmac_f32_dpp v222, v209, v48 row_newbcast:13 row_mask:0xf bank_mask:0xf
	v_fmac_f32_dpp v223, v209, v49 row_newbcast:14 row_mask:0xf bank_mask:0xf
	v_fmac_f32_dpp v224, v209, v91 row_newbcast:15 row_mask:0xf bank_mask:0xf
	ds_read_b32 v209, v232 offset:16112
	s_waitcnt lgkmcnt(11)
	v_fmac_f32_dpp v196, v210, v92 row_newbcast:0 row_mask:0xf bank_mask:0xf
	v_fmac_f32_dpp v222, v210, v93 row_newbcast:1 row_mask:0xf bank_mask:0xf
	v_fmac_f32_dpp v223, v210, v94 row_newbcast:2 row_mask:0xf bank_mask:0xf
	v_fmac_f32_dpp v224, v210, v95 row_newbcast:3 row_mask:0xf bank_mask:0xf
	v_fmac_f32_dpp v196, v210, v96 row_newbcast:4 row_mask:0xf bank_mask:0xf
	v_fmac_f32_dpp v222, v210, v97 row_newbcast:5 row_mask:0xf bank_mask:0xf
	v_fmac_f32_dpp v223, v210, v98 row_newbcast:6 row_mask:0xf bank_mask:0xf
	v_fmac_f32_dpp v224, v210, v99 row_newbcast:7 row_mask:0xf bank_mask:0xf
	v_fmac_f32_dpp v196, v210, v100 row_newbcast:8 row_mask:0xf bank_mask:0xf
	v_fmac_f32_dpp v222, v210, v101 row_newbcast:9 row_mask:0xf bank_mask:0xf
	v_fmac_f32_dpp v223, v210, v102 row_newbcast:10 row_mask:0xf bank_mask:0xf
	v_fmac_f32_dpp v224, v210, v103 row_newbcast:11 row_mask:0xf bank_mask:0xf
	v_fmac_f32_dpp v196, v210, v104 row_newbcast:12 row_mask:0xf bank_mask:0xf
	v_fmac_f32_dpp v222, v210, v105 row_newbcast:13 row_mask:0xf bank_mask:0xf
	v_fmac_f32_dpp v223, v210, v185 row_newbcast:14 row_mask:0xf bank_mask:0xf
	v_fmac_f32_dpp v224, v210, v186 row_newbcast:15 row_mask:0xf bank_mask:0xf
	ds_read_b32 v210, v232 offset:16176
	s_waitcnt lgkmcnt(11)
	v_fmac_f32_dpp v196, v211, v187 row_newbcast:0 row_mask:0xf bank_mask:0xf
	v_fmac_f32_dpp v222, v211, v188 row_newbcast:1 row_mask:0xf bank_mask:0xf
	v_fmac_f32_dpp v223, v211, v189 row_newbcast:2 row_mask:0xf bank_mask:0xf
	v_fmac_f32_dpp v224, v211, v190 row_newbcast:3 row_mask:0xf bank_mask:0xf
	v_fmac_f32_dpp v196, v211, v192 row_newbcast:4 row_mask:0xf bank_mask:0xf
	v_fmac_f32_dpp v222, v211, v193 row_newbcast:5 row_mask:0xf bank_mask:0xf
	v_fmac_f32_dpp v223, v211, v194 row_newbcast:6 row_mask:0xf bank_mask:0xf
	v_fmac_f32_dpp v224, v211, v195 row_newbcast:7 row_mask:0xf bank_mask:0xf
	v_add_f32_e32 v196, v196, v222
	v_add_f32_e32 v223, v223, v224
	v_add_f32_e32 v196, v196, v223
	ds_read_b32 v211, v232 offset:16240
	s_waitcnt lgkmcnt(11)
	v_fmac_f32_dpp v197, v212, v18 row_newbcast:0 row_mask:0xf bank_mask:0xf
	v_mul_f32_dpp v225, v212, v19 row_newbcast:1 row_mask:0xf bank_mask:0xf
	v_mul_f32_dpp v228, v212, v20 row_newbcast:2 row_mask:0xf bank_mask:0xf
	v_mul_f32_dpp v229, v212, v21 row_newbcast:3 row_mask:0xf bank_mask:0xf
	v_fmac_f32_dpp v197, v212, v22 row_newbcast:4 row_mask:0xf bank_mask:0xf
	v_fmac_f32_dpp v225, v212, v24 row_newbcast:5 row_mask:0xf bank_mask:0xf
	v_fmac_f32_dpp v228, v212, v25 row_newbcast:6 row_mask:0xf bank_mask:0xf
	v_fmac_f32_dpp v229, v212, v26 row_newbcast:7 row_mask:0xf bank_mask:0xf
	v_fmac_f32_dpp v197, v212, v27 row_newbcast:8 row_mask:0xf bank_mask:0xf
	v_fmac_f32_dpp v225, v212, v28 row_newbcast:9 row_mask:0xf bank_mask:0xf
	v_fmac_f32_dpp v228, v212, v29 row_newbcast:10 row_mask:0xf bank_mask:0xf
	v_fmac_f32_dpp v229, v212, v30 row_newbcast:11 row_mask:0xf bank_mask:0xf
	v_fmac_f32_dpp v197, v212, v31 row_newbcast:12 row_mask:0xf bank_mask:0xf
	v_fmac_f32_dpp v225, v212, v32 row_newbcast:13 row_mask:0xf bank_mask:0xf
	v_fmac_f32_dpp v228, v212, v33 row_newbcast:14 row_mask:0xf bank_mask:0xf
	v_fmac_f32_dpp v229, v212, v34 row_newbcast:15 row_mask:0xf bank_mask:0xf
	ds_read_b32 v212, v232 offset:16320
	s_waitcnt lgkmcnt(11)
	v_fmac_f32_dpp v197, v213, v35 row_newbcast:0 row_mask:0xf bank_mask:0xf
	v_fmac_f32_dpp v225, v213, v36 row_newbcast:1 row_mask:0xf bank_mask:0xf
	v_fmac_f32_dpp v228, v213, v37 row_newbcast:2 row_mask:0xf bank_mask:0xf
	v_fmac_f32_dpp v229, v213, v38 row_newbcast:3 row_mask:0xf bank_mask:0xf
	v_fmac_f32_dpp v197, v213, v39 row_newbcast:4 row_mask:0xf bank_mask:0xf
	v_fmac_f32_dpp v225, v213, v40 row_newbcast:5 row_mask:0xf bank_mask:0xf
	v_fmac_f32_dpp v228, v213, v41 row_newbcast:6 row_mask:0xf bank_mask:0xf
	v_fmac_f32_dpp v229, v213, v42 row_newbcast:7 row_mask:0xf bank_mask:0xf
	v_fmac_f32_dpp v197, v213, v43 row_newbcast:8 row_mask:0xf bank_mask:0xf
	v_fmac_f32_dpp v225, v213, v44 row_newbcast:9 row_mask:0xf bank_mask:0xf
	v_fmac_f32_dpp v228, v213, v45 row_newbcast:10 row_mask:0xf bank_mask:0xf
	v_fmac_f32_dpp v229, v213, v46 row_newbcast:11 row_mask:0xf bank_mask:0xf
	v_fmac_f32_dpp v197, v213, v47 row_newbcast:12 row_mask:0xf bank_mask:0xf
	v_fmac_f32_dpp v225, v213, v48 row_newbcast:13 row_mask:0xf bank_mask:0xf
	v_fmac_f32_dpp v228, v213, v49 row_newbcast:14 row_mask:0xf bank_mask:0xf
	v_fmac_f32_dpp v229, v213, v91 row_newbcast:15 row_mask:0xf bank_mask:0xf
	ds_read_b32 v213, v232 offset:16384
	s_waitcnt lgkmcnt(11)
	v_fmac_f32_dpp v197, v214, v92 row_newbcast:0 row_mask:0xf bank_mask:0xf
	v_fmac_f32_dpp v225, v214, v93 row_newbcast:1 row_mask:0xf bank_mask:0xf
	v_fmac_f32_dpp v228, v214, v94 row_newbcast:2 row_mask:0xf bank_mask:0xf
	v_fmac_f32_dpp v229, v214, v95 row_newbcast:3 row_mask:0xf bank_mask:0xf
	v_fmac_f32_dpp v197, v214, v96 row_newbcast:4 row_mask:0xf bank_mask:0xf
	v_fmac_f32_dpp v225, v214, v97 row_newbcast:5 row_mask:0xf bank_mask:0xf
	v_fmac_f32_dpp v228, v214, v98 row_newbcast:6 row_mask:0xf bank_mask:0xf
	v_fmac_f32_dpp v229, v214, v99 row_newbcast:7 row_mask:0xf bank_mask:0xf
	v_fmac_f32_dpp v197, v214, v100 row_newbcast:8 row_mask:0xf bank_mask:0xf
	v_fmac_f32_dpp v225, v214, v101 row_newbcast:9 row_mask:0xf bank_mask:0xf
	v_fmac_f32_dpp v228, v214, v102 row_newbcast:10 row_mask:0xf bank_mask:0xf
	v_fmac_f32_dpp v229, v214, v103 row_newbcast:11 row_mask:0xf bank_mask:0xf
	v_fmac_f32_dpp v197, v214, v104 row_newbcast:12 row_mask:0xf bank_mask:0xf
	v_fmac_f32_dpp v225, v214, v105 row_newbcast:13 row_mask:0xf bank_mask:0xf
	v_fmac_f32_dpp v228, v214, v185 row_newbcast:14 row_mask:0xf bank_mask:0xf
	v_fmac_f32_dpp v229, v214, v186 row_newbcast:15 row_mask:0xf bank_mask:0xf
	ds_read_b32 v214, v232 offset:16448
	s_waitcnt lgkmcnt(11)
	v_fmac_f32_dpp v197, v215, v187 row_newbcast:0 row_mask:0xf bank_mask:0xf
	v_fmac_f32_dpp v225, v215, v188 row_newbcast:1 row_mask:0xf bank_mask:0xf
	v_fmac_f32_dpp v228, v215, v189 row_newbcast:2 row_mask:0xf bank_mask:0xf
	v_fmac_f32_dpp v229, v215, v190 row_newbcast:3 row_mask:0xf bank_mask:0xf
	v_fmac_f32_dpp v197, v215, v192 row_newbcast:4 row_mask:0xf bank_mask:0xf
	v_fmac_f32_dpp v225, v215, v193 row_newbcast:5 row_mask:0xf bank_mask:0xf
	v_fmac_f32_dpp v228, v215, v194 row_newbcast:6 row_mask:0xf bank_mask:0xf
	v_fmac_f32_dpp v229, v215, v195 row_newbcast:7 row_mask:0xf bank_mask:0xf
	v_fmac_f32_dpp v197, v215, v196 row_newbcast:8 row_mask:0xf bank_mask:0xf
	v_add_f32_e32 v197, v197, v225
	v_add_f32_e32 v228, v228, v229
	v_add_f32_e32 v197, v197, v228
	ds_read_b32 v215, v232 offset:16512
	s_waitcnt lgkmcnt(11)
	v_fmac_f32_dpp v198, v204, v18 row_newbcast:0 row_mask:0xf bank_mask:0xf
	v_mul_f32_dpp v222, v204, v19 row_newbcast:1 row_mask:0xf bank_mask:0xf
	v_mul_f32_dpp v223, v204, v20 row_newbcast:2 row_mask:0xf bank_mask:0xf
	v_mul_f32_dpp v224, v204, v21 row_newbcast:3 row_mask:0xf bank_mask:0xf
	v_fmac_f32_dpp v198, v204, v22 row_newbcast:4 row_mask:0xf bank_mask:0xf
	v_fmac_f32_dpp v222, v204, v24 row_newbcast:5 row_mask:0xf bank_mask:0xf
	v_fmac_f32_dpp v223, v204, v25 row_newbcast:6 row_mask:0xf bank_mask:0xf
	v_fmac_f32_dpp v224, v204, v26 row_newbcast:7 row_mask:0xf bank_mask:0xf
	v_fmac_f32_dpp v198, v204, v27 row_newbcast:8 row_mask:0xf bank_mask:0xf
	v_fmac_f32_dpp v222, v204, v28 row_newbcast:9 row_mask:0xf bank_mask:0xf
	v_fmac_f32_dpp v223, v204, v29 row_newbcast:10 row_mask:0xf bank_mask:0xf
	v_fmac_f32_dpp v224, v204, v30 row_newbcast:11 row_mask:0xf bank_mask:0xf
	v_fmac_f32_dpp v198, v204, v31 row_newbcast:12 row_mask:0xf bank_mask:0xf
	v_fmac_f32_dpp v222, v204, v32 row_newbcast:13 row_mask:0xf bank_mask:0xf
	v_fmac_f32_dpp v223, v204, v33 row_newbcast:14 row_mask:0xf bank_mask:0xf
	v_fmac_f32_dpp v224, v204, v34 row_newbcast:15 row_mask:0xf bank_mask:0xf
	ds_read_b32 v204, v232 offset:16592
	s_waitcnt lgkmcnt(11)
	v_fmac_f32_dpp v198, v205, v35 row_newbcast:0 row_mask:0xf bank_mask:0xf
	v_fmac_f32_dpp v222, v205, v36 row_newbcast:1 row_mask:0xf bank_mask:0xf
	v_fmac_f32_dpp v223, v205, v37 row_newbcast:2 row_mask:0xf bank_mask:0xf
	v_fmac_f32_dpp v224, v205, v38 row_newbcast:3 row_mask:0xf bank_mask:0xf
	v_fmac_f32_dpp v198, v205, v39 row_newbcast:4 row_mask:0xf bank_mask:0xf
	v_fmac_f32_dpp v222, v205, v40 row_newbcast:5 row_mask:0xf bank_mask:0xf
	v_fmac_f32_dpp v223, v205, v41 row_newbcast:6 row_mask:0xf bank_mask:0xf
	v_fmac_f32_dpp v224, v205, v42 row_newbcast:7 row_mask:0xf bank_mask:0xf
	v_fmac_f32_dpp v198, v205, v43 row_newbcast:8 row_mask:0xf bank_mask:0xf
	v_fmac_f32_dpp v222, v205, v44 row_newbcast:9 row_mask:0xf bank_mask:0xf
	v_fmac_f32_dpp v223, v205, v45 row_newbcast:10 row_mask:0xf bank_mask:0xf
	v_fmac_f32_dpp v224, v205, v46 row_newbcast:11 row_mask:0xf bank_mask:0xf
	v_fmac_f32_dpp v198, v205, v47 row_newbcast:12 row_mask:0xf bank_mask:0xf
	v_fmac_f32_dpp v222, v205, v48 row_newbcast:13 row_mask:0xf bank_mask:0xf
	v_fmac_f32_dpp v223, v205, v49 row_newbcast:14 row_mask:0xf bank_mask:0xf
	v_fmac_f32_dpp v224, v205, v91 row_newbcast:15 row_mask:0xf bank_mask:0xf
	ds_read_b32 v205, v232 offset:16656
	s_waitcnt lgkmcnt(11)
	v_fmac_f32_dpp v198, v206, v92 row_newbcast:0 row_mask:0xf bank_mask:0xf
	v_fmac_f32_dpp v222, v206, v93 row_newbcast:1 row_mask:0xf bank_mask:0xf
	v_fmac_f32_dpp v223, v206, v94 row_newbcast:2 row_mask:0xf bank_mask:0xf
	v_fmac_f32_dpp v224, v206, v95 row_newbcast:3 row_mask:0xf bank_mask:0xf
	v_fmac_f32_dpp v198, v206, v96 row_newbcast:4 row_mask:0xf bank_mask:0xf
	v_fmac_f32_dpp v222, v206, v97 row_newbcast:5 row_mask:0xf bank_mask:0xf
	v_fmac_f32_dpp v223, v206, v98 row_newbcast:6 row_mask:0xf bank_mask:0xf
	v_fmac_f32_dpp v224, v206, v99 row_newbcast:7 row_mask:0xf bank_mask:0xf
	v_fmac_f32_dpp v198, v206, v100 row_newbcast:8 row_mask:0xf bank_mask:0xf
	v_fmac_f32_dpp v222, v206, v101 row_newbcast:9 row_mask:0xf bank_mask:0xf
	v_fmac_f32_dpp v223, v206, v102 row_newbcast:10 row_mask:0xf bank_mask:0xf
	v_fmac_f32_dpp v224, v206, v103 row_newbcast:11 row_mask:0xf bank_mask:0xf
	v_fmac_f32_dpp v198, v206, v104 row_newbcast:12 row_mask:0xf bank_mask:0xf
	v_fmac_f32_dpp v222, v206, v105 row_newbcast:13 row_mask:0xf bank_mask:0xf
	v_fmac_f32_dpp v223, v206, v185 row_newbcast:14 row_mask:0xf bank_mask:0xf
	v_fmac_f32_dpp v224, v206, v186 row_newbcast:15 row_mask:0xf bank_mask:0xf
	ds_read_b32 v206, v232 offset:16720
	s_waitcnt lgkmcnt(11)
	v_fmac_f32_dpp v198, v207, v187 row_newbcast:0 row_mask:0xf bank_mask:0xf
	v_fmac_f32_dpp v222, v207, v188 row_newbcast:1 row_mask:0xf bank_mask:0xf
	v_fmac_f32_dpp v223, v207, v189 row_newbcast:2 row_mask:0xf bank_mask:0xf
	v_fmac_f32_dpp v224, v207, v190 row_newbcast:3 row_mask:0xf bank_mask:0xf
	v_fmac_f32_dpp v198, v207, v192 row_newbcast:4 row_mask:0xf bank_mask:0xf
	v_fmac_f32_dpp v222, v207, v193 row_newbcast:5 row_mask:0xf bank_mask:0xf
	v_fmac_f32_dpp v223, v207, v194 row_newbcast:6 row_mask:0xf bank_mask:0xf
	v_fmac_f32_dpp v224, v207, v195 row_newbcast:7 row_mask:0xf bank_mask:0xf
	v_fmac_f32_dpp v198, v207, v196 row_newbcast:8 row_mask:0xf bank_mask:0xf
	v_fmac_f32_dpp v222, v207, v197 row_newbcast:9 row_mask:0xf bank_mask:0xf
	v_add_f32_e32 v198, v198, v222
	v_add_f32_e32 v223, v223, v224
	v_add_f32_e32 v198, v198, v223
	ds_read_b32 v207, v232 offset:16784
	s_waitcnt lgkmcnt(11)
	v_fmac_f32_dpp v199, v208, v18 row_newbcast:0 row_mask:0xf bank_mask:0xf
	v_mul_f32_dpp v225, v208, v19 row_newbcast:1 row_mask:0xf bank_mask:0xf
	v_mul_f32_dpp v228, v208, v20 row_newbcast:2 row_mask:0xf bank_mask:0xf
	v_mul_f32_dpp v229, v208, v21 row_newbcast:3 row_mask:0xf bank_mask:0xf
	v_fmac_f32_dpp v199, v208, v22 row_newbcast:4 row_mask:0xf bank_mask:0xf
	v_fmac_f32_dpp v225, v208, v24 row_newbcast:5 row_mask:0xf bank_mask:0xf
	v_fmac_f32_dpp v228, v208, v25 row_newbcast:6 row_mask:0xf bank_mask:0xf
	v_fmac_f32_dpp v229, v208, v26 row_newbcast:7 row_mask:0xf bank_mask:0xf
	v_fmac_f32_dpp v199, v208, v27 row_newbcast:8 row_mask:0xf bank_mask:0xf
	v_fmac_f32_dpp v225, v208, v28 row_newbcast:9 row_mask:0xf bank_mask:0xf
	v_fmac_f32_dpp v228, v208, v29 row_newbcast:10 row_mask:0xf bank_mask:0xf
	v_fmac_f32_dpp v229, v208, v30 row_newbcast:11 row_mask:0xf bank_mask:0xf
	v_fmac_f32_dpp v199, v208, v31 row_newbcast:12 row_mask:0xf bank_mask:0xf
	v_fmac_f32_dpp v225, v208, v32 row_newbcast:13 row_mask:0xf bank_mask:0xf
	v_fmac_f32_dpp v228, v208, v33 row_newbcast:14 row_mask:0xf bank_mask:0xf
	v_fmac_f32_dpp v229, v208, v34 row_newbcast:15 row_mask:0xf bank_mask:0xf
	ds_read_b32 v208, v232 offset:16864
	s_waitcnt lgkmcnt(11)
	v_fmac_f32_dpp v199, v209, v35 row_newbcast:0 row_mask:0xf bank_mask:0xf
	v_fmac_f32_dpp v225, v209, v36 row_newbcast:1 row_mask:0xf bank_mask:0xf
	v_fmac_f32_dpp v228, v209, v37 row_newbcast:2 row_mask:0xf bank_mask:0xf
	v_fmac_f32_dpp v229, v209, v38 row_newbcast:3 row_mask:0xf bank_mask:0xf
	v_fmac_f32_dpp v199, v209, v39 row_newbcast:4 row_mask:0xf bank_mask:0xf
	v_fmac_f32_dpp v225, v209, v40 row_newbcast:5 row_mask:0xf bank_mask:0xf
	v_fmac_f32_dpp v228, v209, v41 row_newbcast:6 row_mask:0xf bank_mask:0xf
	v_fmac_f32_dpp v229, v209, v42 row_newbcast:7 row_mask:0xf bank_mask:0xf
	v_fmac_f32_dpp v199, v209, v43 row_newbcast:8 row_mask:0xf bank_mask:0xf
	v_fmac_f32_dpp v225, v209, v44 row_newbcast:9 row_mask:0xf bank_mask:0xf
	v_fmac_f32_dpp v228, v209, v45 row_newbcast:10 row_mask:0xf bank_mask:0xf
	v_fmac_f32_dpp v229, v209, v46 row_newbcast:11 row_mask:0xf bank_mask:0xf
	v_fmac_f32_dpp v199, v209, v47 row_newbcast:12 row_mask:0xf bank_mask:0xf
	v_fmac_f32_dpp v225, v209, v48 row_newbcast:13 row_mask:0xf bank_mask:0xf
	v_fmac_f32_dpp v228, v209, v49 row_newbcast:14 row_mask:0xf bank_mask:0xf
	v_fmac_f32_dpp v229, v209, v91 row_newbcast:15 row_mask:0xf bank_mask:0xf
	ds_read_b32 v209, v232 offset:16928
	s_waitcnt lgkmcnt(11)
	v_fmac_f32_dpp v199, v210, v92 row_newbcast:0 row_mask:0xf bank_mask:0xf
	v_fmac_f32_dpp v225, v210, v93 row_newbcast:1 row_mask:0xf bank_mask:0xf
	v_fmac_f32_dpp v228, v210, v94 row_newbcast:2 row_mask:0xf bank_mask:0xf
	v_fmac_f32_dpp v229, v210, v95 row_newbcast:3 row_mask:0xf bank_mask:0xf
	v_fmac_f32_dpp v199, v210, v96 row_newbcast:4 row_mask:0xf bank_mask:0xf
	v_fmac_f32_dpp v225, v210, v97 row_newbcast:5 row_mask:0xf bank_mask:0xf
	v_fmac_f32_dpp v228, v210, v98 row_newbcast:6 row_mask:0xf bank_mask:0xf
	v_fmac_f32_dpp v229, v210, v99 row_newbcast:7 row_mask:0xf bank_mask:0xf
	v_fmac_f32_dpp v199, v210, v100 row_newbcast:8 row_mask:0xf bank_mask:0xf
	v_fmac_f32_dpp v225, v210, v101 row_newbcast:9 row_mask:0xf bank_mask:0xf
	v_fmac_f32_dpp v228, v210, v102 row_newbcast:10 row_mask:0xf bank_mask:0xf
	v_fmac_f32_dpp v229, v210, v103 row_newbcast:11 row_mask:0xf bank_mask:0xf
	v_fmac_f32_dpp v199, v210, v104 row_newbcast:12 row_mask:0xf bank_mask:0xf
	v_fmac_f32_dpp v225, v210, v105 row_newbcast:13 row_mask:0xf bank_mask:0xf
	v_fmac_f32_dpp v228, v210, v185 row_newbcast:14 row_mask:0xf bank_mask:0xf
	v_fmac_f32_dpp v229, v210, v186 row_newbcast:15 row_mask:0xf bank_mask:0xf
	ds_read_b32 v210, v232 offset:16992
	s_waitcnt lgkmcnt(11)
	v_fmac_f32_dpp v199, v211, v187 row_newbcast:0 row_mask:0xf bank_mask:0xf
	v_fmac_f32_dpp v225, v211, v188 row_newbcast:1 row_mask:0xf bank_mask:0xf
	v_fmac_f32_dpp v228, v211, v189 row_newbcast:2 row_mask:0xf bank_mask:0xf
	v_fmac_f32_dpp v229, v211, v190 row_newbcast:3 row_mask:0xf bank_mask:0xf
	v_fmac_f32_dpp v199, v211, v192 row_newbcast:4 row_mask:0xf bank_mask:0xf
	v_fmac_f32_dpp v225, v211, v193 row_newbcast:5 row_mask:0xf bank_mask:0xf
	v_fmac_f32_dpp v228, v211, v194 row_newbcast:6 row_mask:0xf bank_mask:0xf
	v_fmac_f32_dpp v229, v211, v195 row_newbcast:7 row_mask:0xf bank_mask:0xf
	v_fmac_f32_dpp v199, v211, v196 row_newbcast:8 row_mask:0xf bank_mask:0xf
	v_fmac_f32_dpp v225, v211, v197 row_newbcast:9 row_mask:0xf bank_mask:0xf
	v_fmac_f32_dpp v228, v211, v198 row_newbcast:10 row_mask:0xf bank_mask:0xf
	v_add_f32_e32 v199, v199, v225
	v_add_f32_e32 v228, v228, v229
	v_add_f32_e32 v199, v199, v228
	ds_read_b32 v211, v232 offset:17056
	s_waitcnt lgkmcnt(11)
	v_fmac_f32_dpp v200, v212, v18 row_newbcast:0 row_mask:0xf bank_mask:0xf
	v_mul_f32_dpp v222, v212, v19 row_newbcast:1 row_mask:0xf bank_mask:0xf
	v_mul_f32_dpp v223, v212, v20 row_newbcast:2 row_mask:0xf bank_mask:0xf
	v_mul_f32_dpp v224, v212, v21 row_newbcast:3 row_mask:0xf bank_mask:0xf
	v_fmac_f32_dpp v200, v212, v22 row_newbcast:4 row_mask:0xf bank_mask:0xf
	v_fmac_f32_dpp v222, v212, v24 row_newbcast:5 row_mask:0xf bank_mask:0xf
	v_fmac_f32_dpp v223, v212, v25 row_newbcast:6 row_mask:0xf bank_mask:0xf
	v_fmac_f32_dpp v224, v212, v26 row_newbcast:7 row_mask:0xf bank_mask:0xf
	v_fmac_f32_dpp v200, v212, v27 row_newbcast:8 row_mask:0xf bank_mask:0xf
	v_fmac_f32_dpp v222, v212, v28 row_newbcast:9 row_mask:0xf bank_mask:0xf
	v_fmac_f32_dpp v223, v212, v29 row_newbcast:10 row_mask:0xf bank_mask:0xf
	v_fmac_f32_dpp v224, v212, v30 row_newbcast:11 row_mask:0xf bank_mask:0xf
	v_fmac_f32_dpp v200, v212, v31 row_newbcast:12 row_mask:0xf bank_mask:0xf
	v_fmac_f32_dpp v222, v212, v32 row_newbcast:13 row_mask:0xf bank_mask:0xf
	v_fmac_f32_dpp v223, v212, v33 row_newbcast:14 row_mask:0xf bank_mask:0xf
	v_fmac_f32_dpp v224, v212, v34 row_newbcast:15 row_mask:0xf bank_mask:0xf
	ds_read_b32 v212, v232 offset:17136
	s_waitcnt lgkmcnt(11)
	v_fmac_f32_dpp v200, v213, v35 row_newbcast:0 row_mask:0xf bank_mask:0xf
	v_fmac_f32_dpp v222, v213, v36 row_newbcast:1 row_mask:0xf bank_mask:0xf
	v_fmac_f32_dpp v223, v213, v37 row_newbcast:2 row_mask:0xf bank_mask:0xf
	v_fmac_f32_dpp v224, v213, v38 row_newbcast:3 row_mask:0xf bank_mask:0xf
	v_fmac_f32_dpp v200, v213, v39 row_newbcast:4 row_mask:0xf bank_mask:0xf
	v_fmac_f32_dpp v222, v213, v40 row_newbcast:5 row_mask:0xf bank_mask:0xf
	v_fmac_f32_dpp v223, v213, v41 row_newbcast:6 row_mask:0xf bank_mask:0xf
	v_fmac_f32_dpp v224, v213, v42 row_newbcast:7 row_mask:0xf bank_mask:0xf
	v_fmac_f32_dpp v200, v213, v43 row_newbcast:8 row_mask:0xf bank_mask:0xf
	v_fmac_f32_dpp v222, v213, v44 row_newbcast:9 row_mask:0xf bank_mask:0xf
	v_fmac_f32_dpp v223, v213, v45 row_newbcast:10 row_mask:0xf bank_mask:0xf
	v_fmac_f32_dpp v224, v213, v46 row_newbcast:11 row_mask:0xf bank_mask:0xf
	v_fmac_f32_dpp v200, v213, v47 row_newbcast:12 row_mask:0xf bank_mask:0xf
	v_fmac_f32_dpp v222, v213, v48 row_newbcast:13 row_mask:0xf bank_mask:0xf
	v_fmac_f32_dpp v223, v213, v49 row_newbcast:14 row_mask:0xf bank_mask:0xf
	v_fmac_f32_dpp v224, v213, v91 row_newbcast:15 row_mask:0xf bank_mask:0xf
	ds_read_b32 v213, v232 offset:17200
	s_waitcnt lgkmcnt(11)
	v_fmac_f32_dpp v200, v214, v92 row_newbcast:0 row_mask:0xf bank_mask:0xf
	v_fmac_f32_dpp v222, v214, v93 row_newbcast:1 row_mask:0xf bank_mask:0xf
	v_fmac_f32_dpp v223, v214, v94 row_newbcast:2 row_mask:0xf bank_mask:0xf
	v_fmac_f32_dpp v224, v214, v95 row_newbcast:3 row_mask:0xf bank_mask:0xf
	v_fmac_f32_dpp v200, v214, v96 row_newbcast:4 row_mask:0xf bank_mask:0xf
	v_fmac_f32_dpp v222, v214, v97 row_newbcast:5 row_mask:0xf bank_mask:0xf
	v_fmac_f32_dpp v223, v214, v98 row_newbcast:6 row_mask:0xf bank_mask:0xf
	v_fmac_f32_dpp v224, v214, v99 row_newbcast:7 row_mask:0xf bank_mask:0xf
	v_fmac_f32_dpp v200, v214, v100 row_newbcast:8 row_mask:0xf bank_mask:0xf
	v_fmac_f32_dpp v222, v214, v101 row_newbcast:9 row_mask:0xf bank_mask:0xf
	v_fmac_f32_dpp v223, v214, v102 row_newbcast:10 row_mask:0xf bank_mask:0xf
	v_fmac_f32_dpp v224, v214, v103 row_newbcast:11 row_mask:0xf bank_mask:0xf
	v_fmac_f32_dpp v200, v214, v104 row_newbcast:12 row_mask:0xf bank_mask:0xf
	v_fmac_f32_dpp v222, v214, v105 row_newbcast:13 row_mask:0xf bank_mask:0xf
	v_fmac_f32_dpp v223, v214, v185 row_newbcast:14 row_mask:0xf bank_mask:0xf
	v_fmac_f32_dpp v224, v214, v186 row_newbcast:15 row_mask:0xf bank_mask:0xf
	ds_read_b32 v214, v232 offset:17264
	s_waitcnt lgkmcnt(11)
	v_fmac_f32_dpp v200, v215, v187 row_newbcast:0 row_mask:0xf bank_mask:0xf
	v_fmac_f32_dpp v222, v215, v188 row_newbcast:1 row_mask:0xf bank_mask:0xf
	v_fmac_f32_dpp v223, v215, v189 row_newbcast:2 row_mask:0xf bank_mask:0xf
	v_fmac_f32_dpp v224, v215, v190 row_newbcast:3 row_mask:0xf bank_mask:0xf
	v_fmac_f32_dpp v200, v215, v192 row_newbcast:4 row_mask:0xf bank_mask:0xf
	v_fmac_f32_dpp v222, v215, v193 row_newbcast:5 row_mask:0xf bank_mask:0xf
	v_fmac_f32_dpp v223, v215, v194 row_newbcast:6 row_mask:0xf bank_mask:0xf
	v_fmac_f32_dpp v224, v215, v195 row_newbcast:7 row_mask:0xf bank_mask:0xf
	v_fmac_f32_dpp v200, v215, v196 row_newbcast:8 row_mask:0xf bank_mask:0xf
	v_fmac_f32_dpp v222, v215, v197 row_newbcast:9 row_mask:0xf bank_mask:0xf
	v_fmac_f32_dpp v223, v215, v198 row_newbcast:10 row_mask:0xf bank_mask:0xf
	v_fmac_f32_dpp v224, v215, v199 row_newbcast:11 row_mask:0xf bank_mask:0xf
	v_add_f32_e32 v200, v200, v222
	v_add_f32_e32 v223, v223, v224
	v_add_f32_e32 v200, v200, v223
	ds_read_b32 v215, v232 offset:17328
	s_waitcnt lgkmcnt(11)
	v_fmac_f32_dpp v201, v204, v18 row_newbcast:0 row_mask:0xf bank_mask:0xf
	v_mul_f32_dpp v225, v204, v19 row_newbcast:1 row_mask:0xf bank_mask:0xf
	v_mul_f32_dpp v228, v204, v20 row_newbcast:2 row_mask:0xf bank_mask:0xf
	v_mul_f32_dpp v229, v204, v21 row_newbcast:3 row_mask:0xf bank_mask:0xf
	v_fmac_f32_dpp v201, v204, v22 row_newbcast:4 row_mask:0xf bank_mask:0xf
	v_fmac_f32_dpp v225, v204, v24 row_newbcast:5 row_mask:0xf bank_mask:0xf
	v_fmac_f32_dpp v228, v204, v25 row_newbcast:6 row_mask:0xf bank_mask:0xf
	v_fmac_f32_dpp v229, v204, v26 row_newbcast:7 row_mask:0xf bank_mask:0xf
	v_fmac_f32_dpp v201, v204, v27 row_newbcast:8 row_mask:0xf bank_mask:0xf
	v_fmac_f32_dpp v225, v204, v28 row_newbcast:9 row_mask:0xf bank_mask:0xf
	v_fmac_f32_dpp v228, v204, v29 row_newbcast:10 row_mask:0xf bank_mask:0xf
	v_fmac_f32_dpp v229, v204, v30 row_newbcast:11 row_mask:0xf bank_mask:0xf
	v_fmac_f32_dpp v201, v204, v31 row_newbcast:12 row_mask:0xf bank_mask:0xf
	v_fmac_f32_dpp v225, v204, v32 row_newbcast:13 row_mask:0xf bank_mask:0xf
	v_fmac_f32_dpp v228, v204, v33 row_newbcast:14 row_mask:0xf bank_mask:0xf
	v_fmac_f32_dpp v229, v204, v34 row_newbcast:15 row_mask:0xf bank_mask:0xf
	s_waitcnt lgkmcnt(10)
	v_fmac_f32_dpp v201, v205, v35 row_newbcast:0 row_mask:0xf bank_mask:0xf
	v_fmac_f32_dpp v225, v205, v36 row_newbcast:1 row_mask:0xf bank_mask:0xf
	v_fmac_f32_dpp v228, v205, v37 row_newbcast:2 row_mask:0xf bank_mask:0xf
	v_fmac_f32_dpp v229, v205, v38 row_newbcast:3 row_mask:0xf bank_mask:0xf
	v_fmac_f32_dpp v201, v205, v39 row_newbcast:4 row_mask:0xf bank_mask:0xf
	v_fmac_f32_dpp v225, v205, v40 row_newbcast:5 row_mask:0xf bank_mask:0xf
	v_fmac_f32_dpp v228, v205, v41 row_newbcast:6 row_mask:0xf bank_mask:0xf
	v_fmac_f32_dpp v229, v205, v42 row_newbcast:7 row_mask:0xf bank_mask:0xf
	v_fmac_f32_dpp v201, v205, v43 row_newbcast:8 row_mask:0xf bank_mask:0xf
	v_fmac_f32_dpp v225, v205, v44 row_newbcast:9 row_mask:0xf bank_mask:0xf
	v_fmac_f32_dpp v228, v205, v45 row_newbcast:10 row_mask:0xf bank_mask:0xf
	v_fmac_f32_dpp v229, v205, v46 row_newbcast:11 row_mask:0xf bank_mask:0xf
	v_fmac_f32_dpp v201, v205, v47 row_newbcast:12 row_mask:0xf bank_mask:0xf
	v_fmac_f32_dpp v225, v205, v48 row_newbcast:13 row_mask:0xf bank_mask:0xf
	v_fmac_f32_dpp v228, v205, v49 row_newbcast:14 row_mask:0xf bank_mask:0xf
	v_fmac_f32_dpp v229, v205, v91 row_newbcast:15 row_mask:0xf bank_mask:0xf
	s_waitcnt lgkmcnt(9)
	v_fmac_f32_dpp v201, v206, v92 row_newbcast:0 row_mask:0xf bank_mask:0xf
	v_fmac_f32_dpp v225, v206, v93 row_newbcast:1 row_mask:0xf bank_mask:0xf
	v_fmac_f32_dpp v228, v206, v94 row_newbcast:2 row_mask:0xf bank_mask:0xf
	v_fmac_f32_dpp v229, v206, v95 row_newbcast:3 row_mask:0xf bank_mask:0xf
	v_fmac_f32_dpp v201, v206, v96 row_newbcast:4 row_mask:0xf bank_mask:0xf
	v_fmac_f32_dpp v225, v206, v97 row_newbcast:5 row_mask:0xf bank_mask:0xf
	v_fmac_f32_dpp v228, v206, v98 row_newbcast:6 row_mask:0xf bank_mask:0xf
	v_fmac_f32_dpp v229, v206, v99 row_newbcast:7 row_mask:0xf bank_mask:0xf
	v_fmac_f32_dpp v201, v206, v100 row_newbcast:8 row_mask:0xf bank_mask:0xf
	v_fmac_f32_dpp v225, v206, v101 row_newbcast:9 row_mask:0xf bank_mask:0xf
	v_fmac_f32_dpp v228, v206, v102 row_newbcast:10 row_mask:0xf bank_mask:0xf
	v_fmac_f32_dpp v229, v206, v103 row_newbcast:11 row_mask:0xf bank_mask:0xf
	v_fmac_f32_dpp v201, v206, v104 row_newbcast:12 row_mask:0xf bank_mask:0xf
	v_fmac_f32_dpp v225, v206, v105 row_newbcast:13 row_mask:0xf bank_mask:0xf
	v_fmac_f32_dpp v228, v206, v185 row_newbcast:14 row_mask:0xf bank_mask:0xf
	v_fmac_f32_dpp v229, v206, v186 row_newbcast:15 row_mask:0xf bank_mask:0xf
	s_waitcnt lgkmcnt(8)
	v_fmac_f32_dpp v201, v207, v187 row_newbcast:0 row_mask:0xf bank_mask:0xf
	v_fmac_f32_dpp v225, v207, v188 row_newbcast:1 row_mask:0xf bank_mask:0xf
	v_fmac_f32_dpp v228, v207, v189 row_newbcast:2 row_mask:0xf bank_mask:0xf
	v_fmac_f32_dpp v229, v207, v190 row_newbcast:3 row_mask:0xf bank_mask:0xf
	v_fmac_f32_dpp v201, v207, v192 row_newbcast:4 row_mask:0xf bank_mask:0xf
	v_fmac_f32_dpp v225, v207, v193 row_newbcast:5 row_mask:0xf bank_mask:0xf
	v_fmac_f32_dpp v228, v207, v194 row_newbcast:6 row_mask:0xf bank_mask:0xf
	v_fmac_f32_dpp v229, v207, v195 row_newbcast:7 row_mask:0xf bank_mask:0xf
	v_fmac_f32_dpp v201, v207, v196 row_newbcast:8 row_mask:0xf bank_mask:0xf
	v_fmac_f32_dpp v225, v207, v197 row_newbcast:9 row_mask:0xf bank_mask:0xf
	v_fmac_f32_dpp v228, v207, v198 row_newbcast:10 row_mask:0xf bank_mask:0xf
	v_fmac_f32_dpp v229, v207, v199 row_newbcast:11 row_mask:0xf bank_mask:0xf
	v_fmac_f32_dpp v201, v207, v200 row_newbcast:12 row_mask:0xf bank_mask:0xf
	v_add_f32_e32 v201, v201, v225
	v_add_f32_e32 v228, v228, v229
	v_add_f32_e32 v201, v201, v228
	s_waitcnt lgkmcnt(7)
	v_fmac_f32_dpp v202, v208, v18 row_newbcast:0 row_mask:0xf bank_mask:0xf
	v_mul_f32_dpp v222, v208, v19 row_newbcast:1 row_mask:0xf bank_mask:0xf
	v_mul_f32_dpp v223, v208, v20 row_newbcast:2 row_mask:0xf bank_mask:0xf
	v_mul_f32_dpp v224, v208, v21 row_newbcast:3 row_mask:0xf bank_mask:0xf
	v_fmac_f32_dpp v202, v208, v22 row_newbcast:4 row_mask:0xf bank_mask:0xf
	v_fmac_f32_dpp v222, v208, v24 row_newbcast:5 row_mask:0xf bank_mask:0xf
	v_fmac_f32_dpp v223, v208, v25 row_newbcast:6 row_mask:0xf bank_mask:0xf
	v_fmac_f32_dpp v224, v208, v26 row_newbcast:7 row_mask:0xf bank_mask:0xf
	v_fmac_f32_dpp v202, v208, v27 row_newbcast:8 row_mask:0xf bank_mask:0xf
	v_fmac_f32_dpp v222, v208, v28 row_newbcast:9 row_mask:0xf bank_mask:0xf
	v_fmac_f32_dpp v223, v208, v29 row_newbcast:10 row_mask:0xf bank_mask:0xf
	v_fmac_f32_dpp v224, v208, v30 row_newbcast:11 row_mask:0xf bank_mask:0xf
	v_fmac_f32_dpp v202, v208, v31 row_newbcast:12 row_mask:0xf bank_mask:0xf
	v_fmac_f32_dpp v222, v208, v32 row_newbcast:13 row_mask:0xf bank_mask:0xf
	v_fmac_f32_dpp v223, v208, v33 row_newbcast:14 row_mask:0xf bank_mask:0xf
	v_fmac_f32_dpp v224, v208, v34 row_newbcast:15 row_mask:0xf bank_mask:0xf
	s_waitcnt lgkmcnt(6)
	v_fmac_f32_dpp v202, v209, v35 row_newbcast:0 row_mask:0xf bank_mask:0xf
	v_fmac_f32_dpp v222, v209, v36 row_newbcast:1 row_mask:0xf bank_mask:0xf
	v_fmac_f32_dpp v223, v209, v37 row_newbcast:2 row_mask:0xf bank_mask:0xf
	v_fmac_f32_dpp v224, v209, v38 row_newbcast:3 row_mask:0xf bank_mask:0xf
	v_fmac_f32_dpp v202, v209, v39 row_newbcast:4 row_mask:0xf bank_mask:0xf
	v_fmac_f32_dpp v222, v209, v40 row_newbcast:5 row_mask:0xf bank_mask:0xf
	v_fmac_f32_dpp v223, v209, v41 row_newbcast:6 row_mask:0xf bank_mask:0xf
	v_fmac_f32_dpp v224, v209, v42 row_newbcast:7 row_mask:0xf bank_mask:0xf
	v_fmac_f32_dpp v202, v209, v43 row_newbcast:8 row_mask:0xf bank_mask:0xf
	v_fmac_f32_dpp v222, v209, v44 row_newbcast:9 row_mask:0xf bank_mask:0xf
	v_fmac_f32_dpp v223, v209, v45 row_newbcast:10 row_mask:0xf bank_mask:0xf
	v_fmac_f32_dpp v224, v209, v46 row_newbcast:11 row_mask:0xf bank_mask:0xf
	v_fmac_f32_dpp v202, v209, v47 row_newbcast:12 row_mask:0xf bank_mask:0xf
	v_fmac_f32_dpp v222, v209, v48 row_newbcast:13 row_mask:0xf bank_mask:0xf
	v_fmac_f32_dpp v223, v209, v49 row_newbcast:14 row_mask:0xf bank_mask:0xf
	v_fmac_f32_dpp v224, v209, v91 row_newbcast:15 row_mask:0xf bank_mask:0xf
	s_waitcnt lgkmcnt(5)
	v_fmac_f32_dpp v202, v210, v92 row_newbcast:0 row_mask:0xf bank_mask:0xf
	v_fmac_f32_dpp v222, v210, v93 row_newbcast:1 row_mask:0xf bank_mask:0xf
	v_fmac_f32_dpp v223, v210, v94 row_newbcast:2 row_mask:0xf bank_mask:0xf
	v_fmac_f32_dpp v224, v210, v95 row_newbcast:3 row_mask:0xf bank_mask:0xf
	v_fmac_f32_dpp v202, v210, v96 row_newbcast:4 row_mask:0xf bank_mask:0xf
	v_fmac_f32_dpp v222, v210, v97 row_newbcast:5 row_mask:0xf bank_mask:0xf
	v_fmac_f32_dpp v223, v210, v98 row_newbcast:6 row_mask:0xf bank_mask:0xf
	v_fmac_f32_dpp v224, v210, v99 row_newbcast:7 row_mask:0xf bank_mask:0xf
	v_fmac_f32_dpp v202, v210, v100 row_newbcast:8 row_mask:0xf bank_mask:0xf
	v_fmac_f32_dpp v222, v210, v101 row_newbcast:9 row_mask:0xf bank_mask:0xf
	v_fmac_f32_dpp v223, v210, v102 row_newbcast:10 row_mask:0xf bank_mask:0xf
	v_fmac_f32_dpp v224, v210, v103 row_newbcast:11 row_mask:0xf bank_mask:0xf
	v_fmac_f32_dpp v202, v210, v104 row_newbcast:12 row_mask:0xf bank_mask:0xf
	v_fmac_f32_dpp v222, v210, v105 row_newbcast:13 row_mask:0xf bank_mask:0xf
	v_fmac_f32_dpp v223, v210, v185 row_newbcast:14 row_mask:0xf bank_mask:0xf
	v_fmac_f32_dpp v224, v210, v186 row_newbcast:15 row_mask:0xf bank_mask:0xf
	s_waitcnt lgkmcnt(4)
	v_fmac_f32_dpp v202, v211, v187 row_newbcast:0 row_mask:0xf bank_mask:0xf
	v_fmac_f32_dpp v222, v211, v188 row_newbcast:1 row_mask:0xf bank_mask:0xf
	v_fmac_f32_dpp v223, v211, v189 row_newbcast:2 row_mask:0xf bank_mask:0xf
	v_fmac_f32_dpp v224, v211, v190 row_newbcast:3 row_mask:0xf bank_mask:0xf
	v_fmac_f32_dpp v202, v211, v192 row_newbcast:4 row_mask:0xf bank_mask:0xf
	v_fmac_f32_dpp v222, v211, v193 row_newbcast:5 row_mask:0xf bank_mask:0xf
	v_fmac_f32_dpp v223, v211, v194 row_newbcast:6 row_mask:0xf bank_mask:0xf
	v_fmac_f32_dpp v224, v211, v195 row_newbcast:7 row_mask:0xf bank_mask:0xf
	v_fmac_f32_dpp v202, v211, v196 row_newbcast:8 row_mask:0xf bank_mask:0xf
	v_fmac_f32_dpp v222, v211, v197 row_newbcast:9 row_mask:0xf bank_mask:0xf
	v_fmac_f32_dpp v223, v211, v198 row_newbcast:10 row_mask:0xf bank_mask:0xf
	v_fmac_f32_dpp v224, v211, v199 row_newbcast:11 row_mask:0xf bank_mask:0xf
	v_fmac_f32_dpp v202, v211, v200 row_newbcast:12 row_mask:0xf bank_mask:0xf
	v_fmac_f32_dpp v222, v211, v201 row_newbcast:13 row_mask:0xf bank_mask:0xf
	v_add_f32_e32 v202, v202, v222
	v_add_f32_e32 v223, v223, v224
	v_add_f32_e32 v202, v202, v223
	s_waitcnt lgkmcnt(3)
	v_fmac_f32_dpp v203, v212, v18 row_newbcast:0 row_mask:0xf bank_mask:0xf
	v_mul_f32_dpp v225, v212, v19 row_newbcast:1 row_mask:0xf bank_mask:0xf
	v_mul_f32_dpp v228, v212, v20 row_newbcast:2 row_mask:0xf bank_mask:0xf
	v_mul_f32_dpp v229, v212, v21 row_newbcast:3 row_mask:0xf bank_mask:0xf
	v_fmac_f32_dpp v203, v212, v22 row_newbcast:4 row_mask:0xf bank_mask:0xf
	v_fmac_f32_dpp v225, v212, v24 row_newbcast:5 row_mask:0xf bank_mask:0xf
	v_fmac_f32_dpp v228, v212, v25 row_newbcast:6 row_mask:0xf bank_mask:0xf
	v_fmac_f32_dpp v229, v212, v26 row_newbcast:7 row_mask:0xf bank_mask:0xf
	v_fmac_f32_dpp v203, v212, v27 row_newbcast:8 row_mask:0xf bank_mask:0xf
	v_fmac_f32_dpp v225, v212, v28 row_newbcast:9 row_mask:0xf bank_mask:0xf
	v_fmac_f32_dpp v228, v212, v29 row_newbcast:10 row_mask:0xf bank_mask:0xf
	v_fmac_f32_dpp v229, v212, v30 row_newbcast:11 row_mask:0xf bank_mask:0xf
	v_fmac_f32_dpp v203, v212, v31 row_newbcast:12 row_mask:0xf bank_mask:0xf
	v_fmac_f32_dpp v225, v212, v32 row_newbcast:13 row_mask:0xf bank_mask:0xf
	v_fmac_f32_dpp v228, v212, v33 row_newbcast:14 row_mask:0xf bank_mask:0xf
	v_fmac_f32_dpp v229, v212, v34 row_newbcast:15 row_mask:0xf bank_mask:0xf
	s_waitcnt lgkmcnt(2)
	v_fmac_f32_dpp v203, v213, v35 row_newbcast:0 row_mask:0xf bank_mask:0xf
	v_fmac_f32_dpp v225, v213, v36 row_newbcast:1 row_mask:0xf bank_mask:0xf
	v_fmac_f32_dpp v228, v213, v37 row_newbcast:2 row_mask:0xf bank_mask:0xf
	v_fmac_f32_dpp v229, v213, v38 row_newbcast:3 row_mask:0xf bank_mask:0xf
	v_fmac_f32_dpp v203, v213, v39 row_newbcast:4 row_mask:0xf bank_mask:0xf
	v_fmac_f32_dpp v225, v213, v40 row_newbcast:5 row_mask:0xf bank_mask:0xf
	v_fmac_f32_dpp v228, v213, v41 row_newbcast:6 row_mask:0xf bank_mask:0xf
	v_fmac_f32_dpp v229, v213, v42 row_newbcast:7 row_mask:0xf bank_mask:0xf
	v_fmac_f32_dpp v203, v213, v43 row_newbcast:8 row_mask:0xf bank_mask:0xf
	v_fmac_f32_dpp v225, v213, v44 row_newbcast:9 row_mask:0xf bank_mask:0xf
	v_fmac_f32_dpp v228, v213, v45 row_newbcast:10 row_mask:0xf bank_mask:0xf
	v_fmac_f32_dpp v229, v213, v46 row_newbcast:11 row_mask:0xf bank_mask:0xf
	v_fmac_f32_dpp v203, v213, v47 row_newbcast:12 row_mask:0xf bank_mask:0xf
	v_fmac_f32_dpp v225, v213, v48 row_newbcast:13 row_mask:0xf bank_mask:0xf
	v_fmac_f32_dpp v228, v213, v49 row_newbcast:14 row_mask:0xf bank_mask:0xf
	v_fmac_f32_dpp v229, v213, v91 row_newbcast:15 row_mask:0xf bank_mask:0xf
	s_waitcnt lgkmcnt(1)
	v_fmac_f32_dpp v203, v214, v92 row_newbcast:0 row_mask:0xf bank_mask:0xf
	v_fmac_f32_dpp v225, v214, v93 row_newbcast:1 row_mask:0xf bank_mask:0xf
	v_fmac_f32_dpp v228, v214, v94 row_newbcast:2 row_mask:0xf bank_mask:0xf
	v_fmac_f32_dpp v229, v214, v95 row_newbcast:3 row_mask:0xf bank_mask:0xf
	v_fmac_f32_dpp v203, v214, v96 row_newbcast:4 row_mask:0xf bank_mask:0xf
	v_fmac_f32_dpp v225, v214, v97 row_newbcast:5 row_mask:0xf bank_mask:0xf
	v_fmac_f32_dpp v228, v214, v98 row_newbcast:6 row_mask:0xf bank_mask:0xf
	v_fmac_f32_dpp v229, v214, v99 row_newbcast:7 row_mask:0xf bank_mask:0xf
	v_fmac_f32_dpp v203, v214, v100 row_newbcast:8 row_mask:0xf bank_mask:0xf
	v_fmac_f32_dpp v225, v214, v101 row_newbcast:9 row_mask:0xf bank_mask:0xf
	v_fmac_f32_dpp v228, v214, v102 row_newbcast:10 row_mask:0xf bank_mask:0xf
	v_fmac_f32_dpp v229, v214, v103 row_newbcast:11 row_mask:0xf bank_mask:0xf
	v_fmac_f32_dpp v203, v214, v104 row_newbcast:12 row_mask:0xf bank_mask:0xf
	v_fmac_f32_dpp v225, v214, v105 row_newbcast:13 row_mask:0xf bank_mask:0xf
	v_fmac_f32_dpp v228, v214, v185 row_newbcast:14 row_mask:0xf bank_mask:0xf
	v_fmac_f32_dpp v229, v214, v186 row_newbcast:15 row_mask:0xf bank_mask:0xf
	s_waitcnt lgkmcnt(0)
	v_fmac_f32_dpp v203, v215, v187 row_newbcast:0 row_mask:0xf bank_mask:0xf
	v_fmac_f32_dpp v225, v215, v188 row_newbcast:1 row_mask:0xf bank_mask:0xf
	v_fmac_f32_dpp v228, v215, v189 row_newbcast:2 row_mask:0xf bank_mask:0xf
	v_fmac_f32_dpp v229, v215, v190 row_newbcast:3 row_mask:0xf bank_mask:0xf
	v_fmac_f32_dpp v203, v215, v192 row_newbcast:4 row_mask:0xf bank_mask:0xf
	v_fmac_f32_dpp v225, v215, v193 row_newbcast:5 row_mask:0xf bank_mask:0xf
	v_fmac_f32_dpp v228, v215, v194 row_newbcast:6 row_mask:0xf bank_mask:0xf
	v_fmac_f32_dpp v229, v215, v195 row_newbcast:7 row_mask:0xf bank_mask:0xf
	v_fmac_f32_dpp v203, v215, v196 row_newbcast:8 row_mask:0xf bank_mask:0xf
	v_fmac_f32_dpp v225, v215, v197 row_newbcast:9 row_mask:0xf bank_mask:0xf
	v_fmac_f32_dpp v228, v215, v198 row_newbcast:10 row_mask:0xf bank_mask:0xf
	v_fmac_f32_dpp v229, v215, v199 row_newbcast:11 row_mask:0xf bank_mask:0xf
	v_fmac_f32_dpp v203, v215, v200 row_newbcast:12 row_mask:0xf bank_mask:0xf
	v_fmac_f32_dpp v225, v215, v201 row_newbcast:13 row_mask:0xf bank_mask:0xf
	v_fmac_f32_dpp v228, v215, v202 row_newbcast:14 row_mask:0xf bank_mask:0xf
	v_add_f32_e32 v203, v203, v225
	v_add_f32_e32 v228, v228, v229
	v_add_f32_e32 v203, v203, v228
	s_barrier
	s_mov_b64 s[18:19], exec
	v_cvt_pk_bf16_f32 v242, v18, v19
	v_cvt_pk_bf16_f32 v243, v20, v21
	v_cvt_pk_bf16_f32 v244, v22, v24
	v_cvt_pk_bf16_f32 v245, v25, v26
	ds_write_b128 v235, v[242:245] offset:36864
	v_cvt_pk_bf16_f32 v242, v27, v28
	v_cvt_pk_bf16_f32 v243, v29, v30
	v_cvt_pk_bf16_f32 v244, v31, v32
	v_cvt_pk_bf16_f32 v245, v33, v34
	ds_write_b128 v235, v[242:245] offset:36880
	v_cvt_pk_bf16_f32 v242, v35, v36
	v_cvt_pk_bf16_f32 v243, v37, v38
	v_cvt_pk_bf16_f32 v244, v39, v40
	v_cvt_pk_bf16_f32 v245, v41, v42
	ds_write_b128 v235, v[242:245] offset:36896
	v_cvt_pk_bf16_f32 v242, v43, v44
	v_cvt_pk_bf16_f32 v243, v45, v46
	v_cvt_pk_bf16_f32 v244, v47, v48
	v_cvt_pk_bf16_f32 v245, v49, v91
	ds_write_b128 v235, v[242:245] offset:36912
	v_cvt_pk_bf16_f32 v242, v92, v93
	v_cvt_pk_bf16_f32 v243, v94, v95
	v_cvt_pk_bf16_f32 v244, v96, v97
	v_cvt_pk_bf16_f32 v245, v98, v99
	ds_write_b128 v235, v[242:245] offset:36928
	v_cvt_pk_bf16_f32 v242, v100, v101
	v_cvt_pk_bf16_f32 v243, v102, v103
	v_cvt_pk_bf16_f32 v244, v104, v105
	v_cvt_pk_bf16_f32 v245, v185, v186
	ds_write_b128 v235, v[242:245] offset:36944
	v_cvt_pk_bf16_f32 v242, v187, v188
	v_cvt_pk_bf16_f32 v243, v189, v190
	v_cvt_pk_bf16_f32 v244, v192, v193
	v_cvt_pk_bf16_f32 v245, v194, v195
	ds_write_b128 v235, v[242:245] offset:36960
	v_cvt_pk_bf16_f32 v242, v196, v197
	v_cvt_pk_bf16_f32 v243, v198, v199
	v_cvt_pk_bf16_f32 v244, v200, v201
	v_cvt_pk_bf16_f32 v245, v202, v203
	ds_write_b128 v235, v[242:245] offset:36976
	s_branch .LBB0_2333
.Ls3_idle:
	s_barrier
	s_mov_b64 s[18:19], exec
